# ConvGelu epilogue: 16-lane up-shuffles as DPP row_shr moves instead of ds_bpermute, select waits relaxed to lgkmcnt(2); on v58 + cndmask selects
# speedup vs baseline: 1.0016x; 1.0016x over previous
; __device__ __forceinline__ unsigned cvt_pk_bf16(float lo, float hi) { unsigned r; asm volatile("v_cvt_pk_bf16_f32 %0, %1, %2" : "=v"(r) : "v"(lo), "v"(hi)); return r; }
;     __device__ __forceinline__ void operator()(const f32x4 (&acc)[2][2][4][2], const Unit& u, int wr, int wc, int fr, int fq) const {
;     ...
;             for (int m = 0; m < 4; ++m) {
;                 const int row = u.pm * BM + ai * HALF + wr * 64 + m * 16 + fr;
;                 unsigned pk[4];
;                 pk[0] = cvt_pk_bf16(acc[ai][0][m][0][0], acc[ai][0][m][0][1]); pk[1] = cvt_pk_bf16(acc[ai][0][m][0][2], acc[ai][0][m][0][3]);
;                 pk[2] = cvt_pk_bf16(acc[ai][0][m][1][0], acc[ai][0][m][1][1]); pk[3] = cvt_pk_bf16(acc[ai][0][m][1][2], acc[ai][0][m][1][3]);
;                 float hv[8];
; #pragma unroll
;                 for (int q = 0; q < 4; ++q) {
;                     unsigned g1 = (unsigned)__shfl_up((int)pk[q], 1, 16), g2 = (unsigned)__shfl_up((int)pk[q], 2, 16);
;                     if (fr == 0) { g1 = l15[q]; g2 = l14[q]; } else if (fr == 1) { g2 = l15[q]; }
;                     const unsigned n14 = (unsigned)__shfl((int)pk[q], 14, 16), n15 = (unsigned)__shfl((int)pk[q], 15, 16);
;                     l14[q] = n14; l15[q] = n15;
.LBB0_1195:
	v_add_u32_e32 v182, -1, v199
	v_and_b32_e32 v183, 0x70, v199
	v_cmp_lt_i32_e32 vcc, v182, v183
	v_cvt_pk_bf16_f32 v204, v104, v105
	v_cvt_pk_bf16_f32 v211, v106, v107
	v_cvt_pk_bf16_f32 v208, v100, v101
	v_cvt_pk_bf16_f32 v187, v102, v103
	s_nop 1
	v_cndmask_b32_e32 v182, v182, v199, vcc
	v_lshlrev_b32_e32 v200, 2, v182
	v_add_u32_e32 v182, -2, v199
	v_cmp_lt_i32_e32 vcc, v182, v183
	s_nop 1
	v_cndmask_b32_e32 v182, v182, v199, vcc
	v_lshlrev_b32_e32 v201, 2, v182
	s_nop 1
	v_mov_b32_dpp v182, v204 row_shr:1 row_mask:0xf bank_mask:0xf
	v_mov_b32_dpp v183, v204 row_shr:2 row_mask:0xf bank_mask:0xf
	v_cmp_lt_i32_e32 vcc, 0, v188
	v_cmp_eq_u32_e64 s[98:99], 0, v188
	v_cmp_eq_u32_e64 s[100:101], 1, v188
	s_waitcnt lgkmcnt(2)
	s_nop 1
	v_cndmask_b32_e64 v183, v183, v203, s[100:101]
	v_cndmask_b32_e64 v183, v183, v186, s[98:99]
	v_cndmask_b32_e64 v182, v182, v203, s[98:99]
	v_lshlrev_b32_e32 v186, 2, v199
	v_and_b32_e32 v212, 0x1c0, v186
	v_or_b32_e32 v203, 60, v186
	ds_bpermute_b32 v209, v212, v204 offset:56
	ds_bpermute_b32 v205, v203, v204
	s_nop 1
	v_mov_b32_dpp v186, v211 row_shr:1 row_mask:0xf bank_mask:0xf
	v_mov_b32_dpp v213, v211 row_shr:2 row_mask:0xf bank_mask:0xf
	v_or_b32_e32 v204, 56, v212
	v_cmp_lt_i32_e32 vcc, 0, v188
	v_cmp_eq_u32_e64 s[98:99], 0, v188
	v_cmp_eq_u32_e64 s[100:101], 1, v188
	s_waitcnt lgkmcnt(2)
	s_nop 1
	v_cndmask_b32_e64 v213, v213, v210, s[100:101]
	v_cndmask_b32_e64 v213, v213, v206, s[98:99]
	v_cndmask_b32_e64 v186, v186, v210, s[98:99]
	ds_bpermute_b32 v210, v204, v211
	ds_bpermute_b32 v206, v203, v211
	s_nop 1
	v_mov_b32_dpp v216, v208 row_shr:1 row_mask:0xf bank_mask:0xf
	v_mov_b32_dpp v217, v208 row_shr:2 row_mask:0xf bank_mask:0xf
	v_cmp_lt_i32_e32 vcc, 0, v188
	v_cmp_eq_u32_e64 s[98:99], 0, v188
	v_cmp_eq_u32_e64 s[100:101], 1, v188
	s_waitcnt lgkmcnt(2)
	s_nop 1
	v_cndmask_b32_e64 v217, v217, v207, s[100:101]
	v_cndmask_b32_e64 v217, v217, v202, s[98:99]
	v_cndmask_b32_e64 v216, v216, v207, s[98:99]
	ds_bpermute_b32 v211, v204, v208
	ds_bpermute_b32 v207, v203, v208
	s_nop 1
	v_mov_b32_dpp v214, v187 row_shr:1 row_mask:0xf bank_mask:0xf
	v_mov_b32_dpp v215, v187 row_shr:2 row_mask:0xf bank_mask:0xf
	v_cmp_lt_i32_e32 vcc, 0, v188
	v_cmp_eq_u32_e64 s[98:99], 0, v188
	v_cmp_eq_u32_e64 s[100:101], 1, v188
	s_waitcnt lgkmcnt(2)
	s_nop 1
	v_cndmask_b32_e64 v215, v215, v185, s[100:101]
	v_cndmask_b32_e64 v215, v215, v184, s[98:99]
	v_cndmask_b32_e64 v214, v214, v185, s[98:99]
	ds_bpermute_b32 v212, v204, v187
	ds_bpermute_b32 v208, v203, v187
	s_mul_i32 s57, s62, 0x40800
	s_mul_hi_i32 s55, s62, 0x40800
	s_add_u32 s64, s80, s57
	s_addc_u32 s65, s81, s55
	v_lshl_add_u32 v202, s62, 8, v189
	s_and_saveexec_b64 s[62:63], s[24:25]
	s_xor_b64 s[62:63], exec, s[62:63]
	s_cbranch_execz .LBB0_1221
; __device__ __forceinline__ unsigned cvt_pk_bf16(float lo, float hi) { unsigned r; asm volatile("v_cvt_pk_bf16_f32 %0, %1, %2" : "=v"(r) : "v"(lo), "v"(hi)); return r; }
; __device__ __forceinline__ float gelu_tanh_f(float x) { const float y = -2.3022081983651455f * (x + 0.044715f * x * x * x); return x * __builtin_amdgcn_rcpf(1.f + __builtin_amdgcn_exp2f(y)); }
;     __device__ __forceinline__ void operator()(const f32x4 (&acc)[2][2][4][2], const Unit& u, int wr, int wc, int fr, int fq) const {
;     ...
;                     const int n = q >> 1, j = (q & 1) * 2, e = 2 * q;
;                     const float x0 = bb[e] + w0[e] * __uint_as_float(g2 << 16) + w1[e] * __uint_as_float(g1 << 16) + w2[e] * acc[ai][0][m][n][j];
;                     const float x1 = bb[e + 1] + w0[e + 1] * __uint_as_float(g2 & 0xffff0000u) + w1[e + 1] * __uint_as_float(g1 & 0xffff0000u) + w2[e + 1] * acc[ai][0][m][n][j + 1];
;                     hv[e] = gelu_tanh_f(x0) * acc[ai][1][m][n][j]; hv[e + 1] = gelu_tanh_f(x1) * acc[ai][1][m][n][j + 1];
;                 }
;                 const bool first2 = (slab == 0 && m == 0 && fr < 2);
;                 if (!first2) { u32x4 w; w.x = cvt_pk_bf16(hv[0], hv[1]); w.y = cvt_pk_bf16(hv[2], hv[3]); w.z = cvt_pk_bf16(hv[4], hv[5]); w.w = cvt_pk_bf16(hv[6], hv[7]);
;                     *(u32x4*)(H + (size_t)row * ldh + f0) = w; }
	s_waitcnt lgkmcnt(0)
	v_lshlrev_b32_e32 v184, 16, v217
	s_waitcnt vmcnt(0)
	v_fma_f32 v184, v56, v184, v52
	v_lshlrev_b32_e32 v185, 16, v216
	v_fmac_f32_e32 v184, v48, v185
	v_fmac_f32_e32 v184, v100, v44
	v_mul_f32_e32 v187, 0x3d372713, v184
	v_mul_f32_e32 v187, v184, v187
	v_and_b32_e32 v185, 0xffff0000, v217
	v_fma_f32 v187, v184, v187, v184
	v_fma_f32 v185, v57, v185, v53
	v_mul_f32_e32 v187, 0xc0135761, v187
	v_and_b32_e32 v216, 0xffff0000, v216
	v_exp_f32_e32 v187, v187
	v_fmac_f32_e32 v185, v49, v216
	v_fmac_f32_e32 v185, v101, v45
	v_mul_f32_e32 v216, 0x3d372713, v185
	v_mul_f32_e32 v216, v185, v216
	v_add_f32_e32 v187, 1.0, v187
	v_fma_f32 v216, v185, v216, v185
	v_rcp_f32_e32 v187, v187
	v_mul_f32_e32 v216, 0xc0135761, v216
	v_exp_f32_e32 v216, v216
	v_lshlrev_b32_e32 v217, 16, v186
	v_mul_f32_e32 v184, v184, v187
	v_mul_f32_e32 v187, v88, v184
	v_add_f32_e32 v184, 1.0, v216
	v_lshlrev_b32_e32 v216, 16, v213
	v_fma_f32 v216, v78, v216, v62
	v_and_b32_e32 v213, 0xffff0000, v213
	v_fmac_f32_e32 v216, v70, v217
	v_fma_f32 v213, v79, v213, v63
	v_and_b32_e32 v186, 0xffff0000, v186
	v_fmac_f32_e32 v216, v106, v74
	v_fmac_f32_e32 v213, v71, v186
	v_fmac_f32_e32 v213, v107, v75
	v_mul_f32_e32 v186, 0x3d372713, v216
	v_mul_f32_e32 v186, v216, v186
	v_mul_f32_e32 v217, 0x3d372713, v213
	v_fma_f32 v186, v216, v186, v216
	v_mul_f32_e32 v217, v213, v217
	v_mul_f32_e32 v186, 0xc0135761, v186
	v_fma_f32 v217, v213, v217, v213
	v_rcp_f32_e32 v184, v184
	v_exp_f32_e32 v186, v186
	v_mul_f32_e32 v217, 0xc0135761, v217
	v_exp_f32_e32 v217, v217
	v_mul_f32_e32 v184, v185, v184
	v_add_f32_e32 v185, 1.0, v186
	v_rcp_f32_e32 v185, v185
	v_add_f32_e32 v186, 1.0, v217
	v_rcp_f32_e32 v186, v186
	v_mul_f32_e32 v217, v89, v184
	v_mul_f32_e32 v184, v216, v185
	v_lshlrev_b32_e32 v185, 16, v183
	v_mul_f32_e32 v216, v94, v184
	v_mul_f32_e32 v184, v213, v186
	v_fma_f32 v185, v76, v185, v60
	v_lshlrev_b32_e32 v186, 16, v182
	v_fmac_f32_e32 v185, v68, v186
	v_fmac_f32_e32 v185, v104, v72
	v_and_b32_e32 v183, 0xffff0000, v183
	v_fma_f32 v186, v77, v183, v61
	v_mul_f32_e32 v183, 0x3d372713, v185
	v_mul_f32_e32 v183, v185, v183
	v_fma_f32 v183, v185, v183, v185
	v_mul_f32_e32 v183, 0xc0135761, v183
	v_exp_f32_e32 v183, v183
	v_and_b32_e32 v182, 0xffff0000, v182
	v_fmac_f32_e32 v186, v69, v182
	v_fmac_f32_e32 v186, v105, v73
	v_add_f32_e32 v182, 1.0, v183
	v_mul_f32_e32 v183, 0x3d372713, v186
	v_mul_f32_e32 v183, v186, v183
	v_fma_f32 v183, v186, v183, v186
	v_rcp_f32_e32 v182, v182
	v_mul_f32_e32 v183, 0xc0135761, v183
	v_exp_f32_e32 v183, v183
	v_mul_f32_e32 v213, v95, v184
	v_mul_f32_e32 v182, v185, v182
	v_mul_f32_e32 v218, v92, v182
	v_add_f32_e32 v182, 1.0, v183
	v_rcp_f32_e32 v219, v182
	v_and_b32_e32 v182, 0xffff0000, v215
	v_fma_f32 v220, v59, v182, v55
	v_and_b32_e32 v183, 0xffff0000, v214
	v_mov_b32_e32 v184, v103
	v_mov_b32_e32 v185, v51
	v_mov_b32_e32 v182, v47
	v_pk_mul_f32 v[182:183], v[184:185], v[182:183]
	v_mov_b32_e32 v184, v102
	v_add_f32_e32 v183, v220, v183
	v_add_f32_e32 v220, v182, v183
	v_mul_f32_e32 v182, 0x3d372713, v220
	v_mul_f32_e32 v182, v220, v182
	v_fma_f32 v182, v220, v182, v220
	v_mul_f32_e32 v182, 0xc0135761, v182
	v_exp_f32_e32 v221, v182
	v_lshlrev_b32_e32 v182, 16, v215
	v_fma_f32 v215, v58, v182, v54
	v_lshlrev_b32_e32 v183, 16, v214
	v_mov_b32_e32 v185, v50
	v_mov_b32_e32 v182, v46
	v_pk_mul_f32 v[182:183], v[184:185], v[182:183]
	v_add_f32_e32 v185, 1.0, v221
	v_add_f32_e32 v183, v215, v183
	v_add_f32_e32 v182, v182, v183
	v_mul_f32_e32 v183, 0x3d372713, v182
	v_mul_f32_e32 v183, v182, v183
	v_fma_f32 v183, v182, v183, v182
	v_mul_f32_e32 v183, 0xc0135761, v183
	v_exp_f32_e32 v183, v183
	v_rcp_f32_e32 v185, v185
	v_mul_f32_e32 v184, v186, v219
	v_mul_f32_e32 v184, v93, v184
	v_add_f32_e32 v183, 1.0, v183
	v_rcp_f32_e32 v183, v183
	v_mul_f32_e32 v185, v220, v185
	v_mul_f32_e32 v185, v91, v185
	v_mul_f32_e32 v182, v182, v183
	v_mul_f32_e32 v186, v90, v182
	v_cvt_pk_bf16_f32 v182, v218, v184
	v_cvt_pk_bf16_f32 v183, v216, v213
	v_cvt_pk_bf16_f32 v184, v187, v217
	v_cvt_pk_bf16_f32 v185, v186, v185
	v_mov_b64_e32 v[186:187], s[14:15]
	v_mad_i64_i32 v[186:187], s[66:67], v202, s91, v[186:187]
	v_lshl_add_u64 v[186:187], v[180:181], 1, v[186:187]
	global_store_dwordx4 v[186:187], v[182:185], off

; __device__ __forceinline__ unsigned cvt_pk_bf16(float lo, float hi) { unsigned r; asm volatile("v_cvt_pk_bf16_f32 %0, %1, %2" : "=v"(r) : "v"(lo), "v"(hi)); return r; }
; __device__ __forceinline__ float gelu_tanh_f(float x) { const float y = -2.3022081983651455f * (x + 0.044715f * x * x * x); return x * __builtin_amdgcn_rcpf(1.f + __builtin_amdgcn_exp2f(y)); }
;     __device__ __forceinline__ void operator()(const f32x4 (&acc)[2][2][4][2], const Unit& u, int wr, int wc, int fr, int fq) const {
;     ...
;             for (int m = 0; m < 4; ++m) {
;                 const int row = u.pm * BM + ai * HALF + wr * 64 + m * 16 + fr;
;                 unsigned pk[4];
;                 pk[0] = cvt_pk_bf16(acc[ai][0][m][0][0], acc[ai][0][m][0][1]); pk[1] = cvt_pk_bf16(acc[ai][0][m][0][2], acc[ai][0][m][0][3]);
;                 pk[2] = cvt_pk_bf16(acc[ai][0][m][1][0], acc[ai][0][m][1][1]); pk[3] = cvt_pk_bf16(acc[ai][0][m][1][2], acc[ai][0][m][1][3]);
;                 float hv[8];
; #pragma unroll
;                 for (int q = 0; q < 4; ++q) {
;                     unsigned g1 = (unsigned)__shfl_up((int)pk[q], 1, 16), g2 = (unsigned)__shfl_up((int)pk[q], 2, 16);
;                     if (fr == 0) { g1 = l15[q]; g2 = l14[q]; } else if (fr == 1) { g2 = l15[q]; }
;                     const unsigned n14 = (unsigned)__shfl((int)pk[q], 14, 16), n15 = (unsigned)__shfl((int)pk[q], 15, 16);
;                     l14[q] = n14; l15[q] = n15;
;                     const int n = q >> 1, j = (q & 1) * 2, e = 2 * q;
;                     const float x0 = bb[e] + w0[e] * __uint_as_float(g2 << 16) + w1[e] * __uint_as_float(g1 << 16) + w2[e] * acc[ai][0][m][n][j];
;                     const float x1 = bb[e + 1] + w0[e + 1] * __uint_as_float(g2 & 0xffff0000u) + w1[e + 1] * __uint_as_float(g1 & 0xffff0000u) + w2[e + 1] * acc[ai][0][m][n][j + 1];
;                     hv[e] = gelu_tanh_f(x0) * acc[ai][1][m][n][j]; hv[e + 1] = gelu_tanh_f(x1) * acc[ai][1][m][n][j + 1];
;                 }
;                 const bool first2 = (slab == 0 && m == 0 && fr < 2);
;                 if (!first2) { u32x4 w; w.x = cvt_pk_bf16(hv[0], hv[1]); w.y = cvt_pk_bf16(hv[2], hv[3]); w.z = cvt_pk_bf16(hv[4], hv[5]); w.w = cvt_pk_bf16(hv[6], hv[7]);
;                     *(u32x4*)(H + (size_t)row * ldh + f0) = w; }
.LBB0_1223:
	s_or_b64 exec, exec, s[62:63]
	v_cvt_pk_bf16_f32 v216, v156, v157
	s_nop 1
	v_mov_b32_dpp v214, v216 row_shr:1 row_mask:0xf bank_mask:0xf
	v_mov_b32_dpp v215, v216 row_shr:2 row_mask:0xf bank_mask:0xf
	v_cmp_lt_i32_e32 vcc, 0, v188
	v_cvt_pk_bf16_f32 v219, v158, v159
	v_cvt_pk_bf16_f32 v218, v148, v149
	v_cvt_pk_bf16_f32 v213, v150, v151
	v_cmp_eq_u32_e64 s[98:99], 0, v188
	v_cmp_eq_u32_e64 s[100:101], 1, v188
	s_waitcnt lgkmcnt(2)
	s_nop 1
	v_cndmask_b32_e64 v215, v215, v205, s[100:101]
	v_cndmask_b32_e64 v215, v215, v209, s[98:99]
	v_cndmask_b32_e64 v214, v214, v205, s[98:99]
	ds_bpermute_b32 v209, v204, v216
	ds_bpermute_b32 v205, v203, v216
	s_nop 1
	v_mov_b32_dpp v216, v219 row_shr:1 row_mask:0xf bank_mask:0xf
	v_mov_b32_dpp v217, v219 row_shr:2 row_mask:0xf bank_mask:0xf
	v_cmp_lt_i32_e32 vcc, 0, v188
	v_cmp_eq_u32_e64 s[98:99], 0, v188
	v_cmp_eq_u32_e64 s[100:101], 1, v188
	s_waitcnt lgkmcnt(2)
	s_nop 1
	v_cndmask_b32_e64 v217, v217, v206, s[100:101]
	v_cndmask_b32_e64 v217, v217, v210, s[98:99]
	v_cndmask_b32_e64 v216, v216, v206, s[98:99]
	ds_bpermute_b32 v210, v204, v219
	ds_bpermute_b32 v206, v203, v219
	s_nop 1
	v_mov_b32_dpp v220, v218 row_shr:1 row_mask:0xf bank_mask:0xf
	v_mov_b32_dpp v221, v218 row_shr:2 row_mask:0xf bank_mask:0xf
	v_cmp_lt_i32_e32 vcc, 0, v188
	v_cmp_eq_u32_e64 s[98:99], 0, v188
	v_cmp_eq_u32_e64 s[100:101], 1, v188
	s_waitcnt lgkmcnt(2)
	s_nop 1
	v_cndmask_b32_e64 v221, v221, v207, s[100:101]
	v_cndmask_b32_e64 v221, v221, v211, s[98:99]
	v_cndmask_b32_e64 v220, v220, v207, s[98:99]
	ds_bpermute_b32 v211, v204, v218
	ds_bpermute_b32 v207, v203, v218
	s_nop 1
	v_mov_b32_dpp v218, v213 row_shr:1 row_mask:0xf bank_mask:0xf
	v_mov_b32_dpp v219, v213 row_shr:2 row_mask:0xf bank_mask:0xf
	v_cmp_lt_i32_e32 vcc, 0, v188
	v_cmp_eq_u32_e64 s[98:99], 0, v188
	v_cmp_eq_u32_e64 s[100:101], 1, v188
	s_waitcnt lgkmcnt(2)
	s_nop 1
	v_cndmask_b32_e64 v219, v219, v208, s[100:101]
	v_cndmask_b32_e64 v219, v219, v212, s[98:99]
	v_cndmask_b32_e64 v218, v218, v208, s[98:99]
	s_waitcnt lgkmcnt(0)
	v_lshlrev_b32_e32 v208, 16, v221
	s_waitcnt vmcnt(0)
	v_fma_f32 v208, v56, v208, v52
	v_lshlrev_b32_e32 v212, 16, v220
	v_fmac_f32_e32 v208, v48, v212
	v_fmac_f32_e32 v208, v148, v44
	v_and_b32_e32 v148, 0xffff0000, v221
	v_fma_f32 v148, v57, v148, v53
	v_and_b32_e32 v212, 0xffff0000, v220
	v_fmac_f32_e32 v148, v49, v212
	v_fmac_f32_e32 v148, v149, v45
	v_mul_f32_e32 v149, 0x3d372713, v208
	v_mul_f32_e32 v149, v208, v149
	v_mul_f32_e32 v212, 0x3d372713, v148
	v_fma_f32 v149, v208, v149, v208
	v_mul_f32_e32 v212, v148, v212
	v_mul_f32_e32 v149, 0xc0135761, v149
	v_fma_f32 v212, v148, v212, v148
	v_exp_f32_e32 v149, v149
	v_mul_f32_e32 v212, 0xc0135761, v212
	v_exp_f32_e32 v212, v212
	v_cmp_lt_i32_e32 vcc, 0, v188
	v_add_f32_e32 v149, 1.0, v149
	v_rcp_f32_e32 v149, v149
	v_add_f32_e32 v212, 1.0, v212
	v_rcp_f32_e32 v212, v212
	v_mul_f32_e32 v149, v208, v149
	v_mul_f32_e32 v208, v144, v149
	v_mul_f32_e32 v144, v148, v212
	v_lshlrev_b32_e32 v148, 16, v217
	v_fma_f32 v148, v78, v148, v62
	v_lshlrev_b32_e32 v149, 16, v216
	v_fmac_f32_e32 v148, v70, v149
	v_fmac_f32_e32 v148, v158, v74
	v_mul_f32_e32 v158, 0x3d372713, v148
	v_mul_f32_e32 v158, v148, v158
	v_fma_f32 v158, v148, v158, v148
	v_mul_f32_e32 v158, 0xc0135761, v158
	v_exp_f32_e32 v158, v158
	v_and_b32_e32 v149, 0xffff0000, v217
	v_fma_f32 v149, v79, v149, v63
	v_and_b32_e32 v212, 0xffff0000, v216
	v_add_f32_e32 v158, 1.0, v158
	v_rcp_f32_e32 v158, v158
	v_fmac_f32_e32 v149, v71, v212
	v_fmac_f32_e32 v149, v159, v75
	v_mul_f32_e32 v159, 0x3d372713, v149
	v_mul_f32_e32 v145, v145, v144
	v_mul_f32_e32 v144, v148, v158
	v_lshlrev_b32_e32 v148, 16, v215
	v_mul_f32_e32 v159, v149, v159
	v_mul_f32_e32 v158, v154, v144
	v_fma_f32 v148, v76, v148, v60
	v_lshlrev_b32_e32 v154, 16, v214
	v_fma_f32 v159, v149, v159, v149
	v_fmac_f32_e32 v148, v68, v154
	v_and_b32_e32 v154, 0xffff0000, v215
	v_mul_f32_e32 v159, 0xc0135761, v159
	v_fmac_f32_e32 v148, v156, v72
	v_fma_f32 v154, v77, v154, v61
	v_and_b32_e32 v156, 0xffff0000, v214
	v_exp_f32_e32 v159, v159
	v_fmac_f32_e32 v154, v69, v156
	v_fmac_f32_e32 v154, v157, v73
	v_mul_f32_e32 v156, 0x3d372713, v148
	v_mul_f32_e32 v156, v148, v156
	v_mul_f32_e32 v157, 0x3d372713, v154
	v_fma_f32 v156, v148, v156, v148
	v_mul_f32_e32 v157, v154, v157
	v_add_f32_e32 v144, 1.0, v159
	v_mul_f32_e32 v156, 0xc0135761, v156
	v_fma_f32 v157, v154, v157, v154
	v_rcp_f32_e32 v144, v144
	v_exp_f32_e32 v156, v156
	v_mul_f32_e32 v157, 0xc0135761, v157
	v_exp_f32_e32 v157, v157
	v_mul_f32_e32 v144, v149, v144
	v_add_f32_e32 v149, 1.0, v156
	v_rcp_f32_e32 v149, v149
	v_add_f32_e32 v156, 1.0, v157
	v_rcp_f32_e32 v156, v156
	v_mul_f32_e32 v157, v155, v144
	v_mul_f32_e32 v144, v148, v149
	v_mul_f32_e32 v152, v152, v144
	v_mul_f32_e32 v144, v154, v156
	v_mul_f32_e32 v156, v153, v144
	v_and_b32_e32 v144, 0xffff0000, v219
	v_and_b32_e32 v149, 0xffff0000, v218
	v_mov_b32_e32 v154, v151
	v_mov_b32_e32 v155, v51
	v_mov_b32_e32 v148, v47
	v_fma_f32 v159, v59, v144, v55
	v_pk_mul_f32 v[148:149], v[154:155], v[148:149]
	v_mov_b32_e32 v144, v47
	v_add_f32_e32 v47, v159, v149
	v_add_f32_e32 v155, v148, v47
	v_mul_f32_e32 v47, 0x3d372713, v155
	v_mul_f32_e32 v47, v155, v47
	v_fma_f32 v47, v155, v47, v155
	v_mul_f32_e32 v47, 0xc0135761, v47
	v_exp_f32_e32 v159, v47
	v_lshlrev_b32_e32 v47, 16, v219
	v_fma_f32 v154, v58, v47, v54
	v_lshlrev_b32_e32 v47, 16, v218
	v_mov_b32_e32 v151, v50
	v_pk_mul_f32 v[148:149], v[150:151], v[46:47]
	v_mov_b64_e32 v[150:151], s[14:15]
	v_add_f32_e32 v47, v154, v149
	v_add_f32_e32 v47, v148, v47
	v_mul_f32_e32 v148, 0x3d372713, v47
	v_mul_f32_e32 v148, v47, v148
	v_fma_f32 v148, v47, v148, v47
	v_mul_f32_e32 v148, 0xc0135761, v148
	v_exp_f32_e32 v148, v148
	v_add_f32_e32 v149, 1.0, v159
	v_rcp_f32_e32 v149, v149
	v_or_b32_e32 v159, 16, v202
	v_add_f32_e32 v148, 1.0, v148
	v_rcp_f32_e32 v148, v148
	v_mul_f32_e32 v149, v155, v149
	v_mad_i64_i32 v[150:151], s[62:63], v159, s91, v[150:151]
	v_mul_f32_e32 v47, v47, v148
	v_mul_f32_e32 v149, v147, v149
	v_mul_f32_e32 v47, v146, v47
	v_cvt_pk_bf16_f32 v146, v152, v156
	v_lshl_add_u64 v[150:151], v[180:181], 1, v[150:151]
	ds_bpermute_b32 v153, v204, v213
	ds_bpermute_b32 v154, v203, v213
	v_cvt_pk_bf16_f32 v147, v158, v157
	v_cvt_pk_bf16_f32 v148, v208, v145
	v_cvt_pk_bf16_f32 v149, v47, v149
	global_store_dwordx4 v[150:151], v[146:149], off
	s_nop 1
	v_cvt_pk_bf16_f32 v146, v140, v141
	s_nop 1
	v_mov_b32_dpp v47, v146 row_shr:1 row_mask:0xf bank_mask:0xf
	v_mov_b32_dpp v145, v146 row_shr:2 row_mask:0xf bank_mask:0xf
	v_cvt_pk_bf16_f32 v147, v142, v143
	v_cvt_pk_bf16_f32 v148, v132, v133
	v_cvt_pk_bf16_f32 v152, v134, v135
	v_cmp_eq_u32_e64 s[98:99], 0, v188
	v_cmp_eq_u32_e64 s[100:101], 1, v188
	s_waitcnt lgkmcnt(2)
; __device__ __forceinline__ unsigned cvt_pk_bf16(float lo, float hi) { unsigned r; asm volatile("v_cvt_pk_bf16_f32 %0, %1, %2" : "=v"(r) : "v"(lo), "v"(hi)); return r; }
; __device__ __forceinline__ float gelu_tanh_f(float x) { const float y = -2.3022081983651455f * (x + 0.044715f * x * x * x); return x * __builtin_amdgcn_rcpf(1.f + __builtin_amdgcn_exp2f(y)); }
;     __device__ __forceinline__ void operator()(const f32x4 (&acc)[2][2][4][2], const Unit& u, int wr, int wc, int fr, int fq) const {
;     ...
;             for (int m = 0; m < 4; ++m) {
;                 const int row = u.pm * BM + ai * HALF + wr * 64 + m * 16 + fr;
;                 unsigned pk[4];
;                 pk[0] = cvt_pk_bf16(acc[ai][0][m][0][0], acc[ai][0][m][0][1]); pk[1] = cvt_pk_bf16(acc[ai][0][m][0][2], acc[ai][0][m][0][3]);
;                 pk[2] = cvt_pk_bf16(acc[ai][0][m][1][0], acc[ai][0][m][1][1]); pk[3] = cvt_pk_bf16(acc[ai][0][m][1][2], acc[ai][0][m][1][3]);
;                 float hv[8];
; #pragma unroll
;                 for (int q = 0; q < 4; ++q) {
;                     unsigned g1 = (unsigned)__shfl_up((int)pk[q], 1, 16), g2 = (unsigned)__shfl_up((int)pk[q], 2, 16);
;                     if (fr == 0) { g1 = l15[q]; g2 = l14[q]; } else if (fr == 1) { g2 = l15[q]; }
;                     const unsigned n14 = (unsigned)__shfl((int)pk[q], 14, 16), n15 = (unsigned)__shfl((int)pk[q], 15, 16);
;                     l14[q] = n14; l15[q] = n15;
;                     const int n = q >> 1, j = (q & 1) * 2, e = 2 * q;
;                     const float x0 = bb[e] + w0[e] * __uint_as_float(g2 << 16) + w1[e] * __uint_as_float(g1 << 16) + w2[e] * acc[ai][0][m][n][j];
;                     const float x1 = bb[e + 1] + w0[e + 1] * __uint_as_float(g2 & 0xffff0000u) + w1[e + 1] * __uint_as_float(g1 & 0xffff0000u) + w2[e + 1] * acc[ai][0][m][n][j + 1];
;                     hv[e] = gelu_tanh_f(x0) * acc[ai][1][m][n][j]; hv[e + 1] = gelu_tanh_f(x1) * acc[ai][1][m][n][j + 1];
;                 }
;                 const bool first2 = (slab == 0 && m == 0 && fr < 2);
;                 if (!first2) { u32x4 w; w.x = cvt_pk_bf16(hv[0], hv[1]); w.y = cvt_pk_bf16(hv[2], hv[3]); w.z = cvt_pk_bf16(hv[4], hv[5]); w.w = cvt_pk_bf16(hv[6], hv[7]);
;                     *(u32x4*)(H + (size_t)row * ldh + f0) = w; }
	s_nop 1
	v_cndmask_b32_e64 v145, v145, v205, s[100:101]
	v_cndmask_b32_e64 v145, v145, v209, s[98:99]
	v_cndmask_b32_e64 v47, v47, v205, s[98:99]
	ds_bpermute_b32 v149, v204, v146
	ds_bpermute_b32 v146, v203, v146
	s_nop 1
	v_mov_b32_dpp v155, v147 row_shr:1 row_mask:0xf bank_mask:0xf
	v_mov_b32_dpp v156, v147 row_shr:2 row_mask:0xf bank_mask:0xf
	v_cmp_lt_i32_e32 vcc, 0, v188
	v_cmp_eq_u32_e64 s[98:99], 0, v188
	v_cmp_eq_u32_e64 s[100:101], 1, v188
	s_waitcnt lgkmcnt(2)
	s_nop 1
	v_cndmask_b32_e64 v156, v156, v206, s[100:101]
	v_cndmask_b32_e64 v156, v156, v210, s[98:99]
	v_cndmask_b32_e64 v155, v155, v206, s[98:99]
	ds_bpermute_b32 v150, v204, v147
	ds_bpermute_b32 v147, v203, v147
	s_nop 1
	v_mov_b32_dpp v159, v148 row_shr:1 row_mask:0xf bank_mask:0xf
	v_mov_b32_dpp v205, v148 row_shr:2 row_mask:0xf bank_mask:0xf
	v_cmp_lt_i32_e32 vcc, 0, v188
	v_cmp_eq_u32_e64 s[98:99], 0, v188
	v_cmp_eq_u32_e64 s[100:101], 1, v188
	s_waitcnt lgkmcnt(2)
	s_nop 1
	v_cndmask_b32_e64 v205, v205, v207, s[100:101]
	v_cndmask_b32_e64 v205, v205, v211, s[98:99]
	v_cndmask_b32_e64 v159, v159, v207, s[98:99]
	ds_bpermute_b32 v151, v204, v148
	ds_bpermute_b32 v148, v203, v148
	s_nop 1
	v_mov_b32_dpp v157, v152 row_shr:1 row_mask:0xf bank_mask:0xf
	v_mov_b32_dpp v158, v152 row_shr:2 row_mask:0xf bank_mask:0xf
	v_cmp_lt_i32_e32 vcc, 0, v188
	v_cmp_eq_u32_e64 s[98:99], 0, v188
	v_cmp_eq_u32_e64 s[100:101], 1, v188
	s_waitcnt lgkmcnt(2)
	s_nop 1
	v_cndmask_b32_e64 v158, v158, v154, s[100:101]
	v_cndmask_b32_e64 v158, v158, v153, s[98:99]
	v_cndmask_b32_e64 v157, v157, v154, s[98:99]
	s_waitcnt lgkmcnt(4)
	v_lshlrev_b32_e32 v153, 16, v205
	v_fma_f32 v153, v56, v153, v52
	v_lshlrev_b32_e32 v154, 16, v159
	v_fmac_f32_e32 v153, v48, v154
	v_fmac_f32_e32 v153, v132, v44
	v_and_b32_e32 v132, 0xffff0000, v205
	v_fma_f32 v132, v57, v132, v53
	v_and_b32_e32 v154, 0xffff0000, v159
	v_fmac_f32_e32 v132, v49, v154
	v_fmac_f32_e32 v132, v133, v45
	v_mul_f32_e32 v133, 0x3d372713, v153
	v_mul_f32_e32 v133, v153, v133
	v_fma_f32 v133, v153, v133, v153
	v_mul_f32_e32 v133, 0xc0135761, v133
	v_exp_f32_e32 v133, v133
	v_mul_f32_e32 v154, 0x3d372713, v132
	v_mul_f32_e32 v154, v132, v154
	v_fma_f32 v154, v132, v154, v132
	v_add_f32_e32 v133, 1.0, v133
	v_rcp_f32_e32 v133, v133
	v_mul_f32_e32 v154, 0xc0135761, v154
	v_exp_f32_e32 v154, v154
	v_cmp_lt_i32_e32 vcc, 0, v188
	v_mul_f32_e32 v133, v153, v133
	v_mul_f32_e32 v128, v128, v133
	v_lshlrev_b32_e32 v133, 16, v156
	v_fma_f32 v133, v78, v133, v62
	v_lshlrev_b32_e32 v153, 16, v155
	v_fmac_f32_e32 v133, v70, v153
	v_fmac_f32_e32 v133, v142, v74
	v_mul_f32_e32 v153, 0x3d372713, v133
	v_add_f32_e32 v154, 1.0, v154
	v_mul_f32_e32 v153, v133, v153
	v_rcp_f32_e32 v154, v154
	v_fma_f32 v153, v133, v153, v133
	v_mul_f32_e32 v153, 0xc0135761, v153
	v_exp_f32_e32 v153, v153
	v_and_b32_e32 v142, 0xffff0000, v156
	v_mul_f32_e32 v132, v132, v154
	v_fma_f32 v142, v79, v142, v63
	v_and_b32_e32 v154, 0xffff0000, v155
	v_fmac_f32_e32 v142, v71, v154
	v_fmac_f32_e32 v142, v143, v75
	v_add_f32_e32 v143, 1.0, v153
	v_rcp_f32_e32 v143, v143
	v_mul_f32_e32 v154, v129, v132
	v_lshlrev_b32_e32 v132, 16, v145
	v_fma_f32 v132, v76, v132, v60
	v_mul_f32_e32 v129, v133, v143
	v_lshlrev_b32_e32 v133, 16, v47
	v_fmac_f32_e32 v132, v68, v133
	v_and_b32_e32 v133, 0xffff0000, v145
	v_fma_f32 v133, v77, v133, v61
	v_and_b32_e32 v47, 0xffff0000, v47
	v_fmac_f32_e32 v132, v140, v72
	v_fmac_f32_e32 v133, v69, v47
	v_fmac_f32_e32 v133, v141, v73
	v_mul_f32_e32 v47, 0x3d372713, v132
	v_mul_f32_e32 v47, v132, v47
	v_mul_f32_e32 v140, 0x3d372713, v133
	v_fma_f32 v47, v132, v47, v132
	v_mul_f32_e32 v140, v133, v140
	v_mul_f32_e32 v47, 0xc0135761, v47
	v_fma_f32 v140, v133, v140, v133
	v_exp_f32_e32 v47, v47
	v_mul_f32_e32 v140, 0xc0135761, v140
	v_exp_f32_e32 v140, v140
	v_mul_f32_e32 v153, 0x3d372713, v142
	v_add_f32_e32 v47, 1.0, v47
	v_rcp_f32_e32 v47, v47
	v_add_f32_e32 v140, 1.0, v140
	v_rcp_f32_e32 v140, v140
	v_mul_f32_e32 v153, v142, v153
	v_fma_f32 v153, v142, v153, v142
	v_mul_f32_e32 v47, v132, v47
	v_mul_f32_e32 v153, 0xc0135761, v153
	v_mul_f32_e32 v136, v136, v47
	v_mul_f32_e32 v47, v133, v140
	v_exp_f32_e32 v153, v153
	v_mul_f32_e32 v137, v137, v47
	s_waitcnt lgkmcnt(0)
	v_and_b32_e32 v47, 0xffff0000, v158
	v_and_b32_e32 v145, 0xffff0000, v157
	v_mov_b32_e32 v132, v135
	v_mov_b32_e32 v133, v51
	v_fma_f32 v47, v59, v47, v55
	v_pk_mul_f32 v[132:133], v[132:133], v[144:145]
	v_mul_f32_e32 v138, v138, v129
	v_add_f32_e32 v47, v47, v133
	v_add_f32_e32 v140, v132, v47
	v_add_f32_e32 v129, 1.0, v153
	v_mul_f32_e32 v47, 0x3d372713, v140
	v_rcp_f32_e32 v129, v129
	v_mul_f32_e32 v47, v140, v47
	v_fma_f32 v47, v140, v47, v140
	v_mul_f32_e32 v47, 0xc0135761, v47
	v_exp_f32_e32 v141, v47
	v_lshlrev_b32_e32 v47, 16, v158
	v_mul_f32_e32 v129, v142, v129
	v_fma_f32 v142, v58, v47, v54
	v_lshlrev_b32_e32 v47, 16, v157
	v_mov_b32_e32 v135, v50
	v_pk_mul_f32 v[132:133], v[134:135], v[46:47]
	v_add_f32_e32 v134, 1.0, v141
	v_add_f32_e32 v47, v142, v133
	v_add_f32_e32 v47, v132, v47
	v_mul_f32_e32 v132, 0x3d372713, v47
	v_mul_f32_e32 v132, v47, v132
	v_fma_f32 v132, v47, v132, v47
	v_mul_f32_e32 v132, 0xc0135761, v132
	v_exp_f32_e32 v133, v132
	v_rcp_f32_e32 v134, v134
	v_mul_f32_e32 v139, v139, v129
	v_or_b32_e32 v141, 32, v202
	v_add_f32_e32 v133, 1.0, v133
	v_rcp_f32_e32 v133, v133
	v_mul_f32_e32 v134, v140, v134
	v_mul_f32_e32 v131, v131, v134
	v_cvt_pk_bf16_f32 v134, v136, v137
	v_mul_f32_e32 v47, v47, v133
	v_mul_f32_e32 v47, v130, v47
	v_cvt_pk_bf16_f32 v135, v138, v139
	v_cvt_pk_bf16_f32 v136, v128, v154
	v_cvt_pk_bf16_f32 v137, v47, v131
	v_mov_b64_e32 v[130:131], s[14:15]
	v_mad_i64_i32 v[130:131], s[62:63], v141, s91, v[130:131]
	v_lshl_add_u64 v[130:131], v[180:181], 1, v[130:131]
	global_store_dwordx4 v[130:131], v[134:137], off
	v_cvt_pk_bf16_f32 v128, v124, v125
	ds_bpermute_b32 v129, v204, v152
	ds_bpermute_b32 v132, v203, v152
	s_nop 1
	v_mov_b32_dpp v47, v128 row_shr:1 row_mask:0xf bank_mask:0xf
	v_mov_b32_dpp v128, v128 row_shr:2 row_mask:0xf bank_mask:0xf
	v_cvt_pk_bf16_f32 v131, v126, v127
	v_cvt_pk_bf16_f32 v133, v120, v121
	v_cvt_pk_bf16_f32 v134, v122, v123
	v_cmp_eq_u32_e64 s[98:99], 0, v188
	v_cmp_eq_u32_e64 s[100:101], 1, v188
	s_waitcnt lgkmcnt(2)
;     __device__ __forceinline__ void operator()(const f32x4 (&acc)[2][2][4][2], const Unit& u, int wr, int wc, int fr, int fq) const {
;     ...
;             for (int m = 0; m < 4; ++m) {
;                 const int row = u.pm * BM + ai * HALF + wr * 64 + m * 16 + fr;
;                 unsigned pk[4];
;                 pk[0] = cvt_pk_bf16(acc[ai][0][m][0][0], acc[ai][0][m][0][1]); pk[1] = cvt_pk_bf16(acc[ai][0][m][0][2], acc[ai][0][m][0][3]);
;                 pk[2] = cvt_pk_bf16(acc[ai][0][m][1][0], acc[ai][0][m][1][1]); pk[3] = cvt_pk_bf16(acc[ai][0][m][1][2], acc[ai][0][m][1][3]);
;                 float hv[8];
; #pragma unroll
;                 for (int q = 0; q < 4; ++q) {
;                     unsigned g1 = (unsigned)__shfl_up((int)pk[q], 1, 16), g2 = (unsigned)__shfl_up((int)pk[q], 2, 16);
;                     if (fr == 0) { g1 = l15[q]; g2 = l14[q]; } else if (fr == 1) { g2 = l15[q]; }
;                     const unsigned n14 = (unsigned)__shfl((int)pk[q], 14, 16), n15 = (unsigned)__shfl((int)pk[q], 15, 16);
;                     l14[q] = n14; l15[q] = n15;
;                     const int n = q >> 1, j = (q & 1) * 2, e = 2 * q;
;                     const float x0 = bb[e] + w0[e] * __uint_as_float(g2 << 16) + w1[e] * __uint_as_float(g1 << 16) + w2[e] * acc[ai][0][m][n][j];
;                     const float x1 = bb[e + 1] + w0[e + 1] * __uint_as_float(g2 & 0xffff0000u) + w1[e + 1] * __uint_as_float(g1 & 0xffff0000u) + w2[e + 1] * acc[ai][0][m][n][j + 1];
;                     hv[e] = gelu_tanh_f(x0) * acc[ai][1][m][n][j]; hv[e + 1] = gelu_tanh_f(x1) * acc[ai][1][m][n][j + 1];
;                 }
;                 const bool first2 = (slab == 0 && m == 0 && fr < 2);
;                 if (!first2) { u32x4 w; w.x = cvt_pk_bf16(hv[0], hv[1]); w.y = cvt_pk_bf16(hv[2], hv[3]); w.z = cvt_pk_bf16(hv[4], hv[5]); w.w = cvt_pk_bf16(hv[6], hv[7]);
;                     *(u32x4*)(H + (size_t)row * ldh + f0) = w; }
;                 else { float* p = hp + (size_t)fr * ff; *(f32x4*)p = acc[0][0][0][0]; *(f32x4*)(p + 4) = acc[0][0][0][1];
;                     float* pu = hp + (size_t)(4 + fr) * ff; *(f32x4*)pu = acc[0][1][0][0]; *(f32x4*)(pu + 4) = acc[0][1][0][1]; }
;                 if (slab == 3 && m == 3 && fr >= 14) { float* p = hp + (size_t)(2 + fr - 14) * ff; *(f32x4*)p = acc[1][0][3][0]; *(f32x4*)(p + 4) = acc[1][0][3][1]; }
	s_nop 1
	v_cndmask_b32_e64 v128, v128, v146, s[100:101]
	v_cndmask_b32_e64 v128, v128, v149, s[98:99]
	v_cndmask_b32_e64 v47, v47, v146, s[98:99]
	s_nop 1
	v_mov_b32_dpp v130, v131 row_shr:1 row_mask:0xf bank_mask:0xf
	v_mov_b32_dpp v131, v131 row_shr:2 row_mask:0xf bank_mask:0xf
	v_cmp_lt_i32_e32 vcc, 0, v188
	v_cmp_eq_u32_e64 s[98:99], 0, v188
	v_cmp_eq_u32_e64 s[100:101], 1, v188
	s_waitcnt lgkmcnt(2)
	s_nop 1
	v_cndmask_b32_e64 v131, v131, v147, s[100:101]
	v_cndmask_b32_e64 v131, v131, v150, s[98:99]
	v_cndmask_b32_e64 v130, v130, v147, s[98:99]
	s_nop 1
	v_mov_b32_dpp v135, v133 row_shr:1 row_mask:0xf bank_mask:0xf
	v_mov_b32_dpp v136, v133 row_shr:2 row_mask:0xf bank_mask:0xf
	v_cmp_lt_i32_e32 vcc, 0, v188
	v_cmp_eq_u32_e64 s[98:99], 0, v188
	v_cmp_eq_u32_e64 s[100:101], 1, v188
	s_waitcnt lgkmcnt(2)
	s_nop 1
	v_cndmask_b32_e64 v136, v136, v148, s[100:101]
	v_cndmask_b32_e64 v136, v136, v151, s[98:99]
	v_cndmask_b32_e64 v135, v135, v148, s[98:99]
	s_nop 1
	v_mov_b32_dpp v133, v134 row_shr:1 row_mask:0xf bank_mask:0xf
	v_mov_b32_dpp v134, v134 row_shr:2 row_mask:0xf bank_mask:0xf
	v_cmp_lt_i32_e32 vcc, 0, v188
	v_cmp_eq_u32_e64 s[98:99], 0, v188
	v_cmp_eq_u32_e64 s[100:101], 1, v188
	s_waitcnt lgkmcnt(2)
	s_nop 1
	v_cndmask_b32_e64 v134, v134, v132, s[100:101]
	v_cndmask_b32_e64 v134, v134, v129, s[98:99]
	v_cndmask_b32_e64 v133, v133, v132, s[98:99]
	s_waitcnt lgkmcnt(2)
	v_lshlrev_b32_e32 v129, 16, v136
	v_fma_f32 v129, v56, v129, v52
	v_lshlrev_b32_e32 v132, 16, v135
	v_fmac_f32_e32 v129, v48, v132
	v_fmac_f32_e32 v129, v120, v44
	v_and_b32_e32 v120, 0xffff0000, v136
	v_fma_f32 v120, v57, v120, v53
	v_and_b32_e32 v132, 0xffff0000, v135
	v_fmac_f32_e32 v120, v49, v132
	v_fmac_f32_e32 v120, v121, v45
	v_mul_f32_e32 v121, 0x3d372713, v129
	v_mul_f32_e32 v121, v129, v121
	v_mul_f32_e32 v132, 0x3d372713, v120
	v_fma_f32 v121, v129, v121, v129
	v_mul_f32_e32 v132, v120, v132
	v_mul_f32_e32 v121, 0xc0135761, v121
	v_fma_f32 v132, v120, v132, v120
	v_exp_f32_e32 v121, v121
	v_mul_f32_e32 v132, 0xc0135761, v132
	v_exp_f32_e32 v132, v132
	s_waitcnt lgkmcnt(1)
	v_and_b32_e32 v145, 0xffff0000, v133
	v_add_f32_e32 v121, 1.0, v121
	v_rcp_f32_e32 v121, v121
	v_add_f32_e32 v132, 1.0, v132
	v_rcp_f32_e32 v132, v132
	v_mul_f32_e32 v121, v129, v121
	v_mul_f32_e32 v121, v112, v121
	v_mul_f32_e32 v112, v120, v132
	v_lshlrev_b32_e32 v120, 16, v131
	v_fma_f32 v120, v78, v120, v62
	v_lshlrev_b32_e32 v129, 16, v130
	v_fmac_f32_e32 v120, v70, v129
	v_fmac_f32_e32 v120, v126, v74
	v_mul_f32_e32 v129, 0x3d372713, v120
	v_mul_f32_e32 v129, v120, v129
	v_fma_f32 v129, v120, v129, v120
	v_mul_f32_e32 v129, 0xc0135761, v129
	v_exp_f32_e32 v129, v129
	v_and_b32_e32 v126, 0xffff0000, v131
	v_fma_f32 v126, v79, v126, v63
	v_and_b32_e32 v130, 0xffff0000, v130
	v_fmac_f32_e32 v126, v71, v130
	v_fmac_f32_e32 v126, v127, v75
	v_add_f32_e32 v127, 1.0, v129
	v_rcp_f32_e32 v127, v127
	v_mul_f32_e32 v130, v113, v112
	v_lshlrev_b32_e32 v113, 16, v128
	v_fma_f32 v113, v76, v113, v60
	v_mul_f32_e32 v112, v120, v127
	v_lshlrev_b32_e32 v120, 16, v47
	v_fmac_f32_e32 v113, v68, v120
	v_and_b32_e32 v120, 0xffff0000, v128
	v_fmac_f32_e32 v113, v124, v72
	v_fma_f32 v120, v77, v120, v61
	v_and_b32_e32 v47, 0xffff0000, v47
	v_mul_f32_e32 v129, 0x3d372713, v126
	v_fmac_f32_e32 v120, v69, v47
	v_mul_f32_e32 v47, 0x3d372713, v113
	v_mul_f32_e32 v129, v126, v129
	v_mul_f32_e32 v47, v113, v47
	v_fma_f32 v129, v126, v129, v126
	v_fma_f32 v47, v113, v47, v113
	v_mul_f32_e32 v129, 0xc0135761, v129
	v_fmac_f32_e32 v120, v125, v73
	v_mul_f32_e32 v47, 0xc0135761, v47
	v_exp_f32_e32 v129, v129
	v_exp_f32_e32 v47, v47
	v_mul_f32_e32 v124, 0x3d372713, v120
	v_mul_f32_e32 v124, v120, v124
	v_fma_f32 v124, v120, v124, v120
	v_mul_f32_e32 v124, 0xc0135761, v124
	v_mul_f32_e32 v118, v118, v112
	v_add_f32_e32 v112, 1.0, v129
	v_exp_f32_e32 v124, v124
	v_add_f32_e32 v47, 1.0, v47
	v_rcp_f32_e32 v112, v112
	v_rcp_f32_e32 v47, v47
	v_add_f32_e32 v124, 1.0, v124
	v_rcp_f32_e32 v124, v124
	v_mul_f32_e32 v112, v126, v112
	v_mul_f32_e32 v47, v113, v47
	v_mul_f32_e32 v119, v119, v112
	v_mul_f32_e32 v116, v116, v47
	s_waitcnt lgkmcnt(0)
	v_and_b32_e32 v47, 0xffff0000, v134
	v_mov_b32_e32 v112, v123
	v_mov_b32_e32 v113, v51
	v_fma_f32 v47, v59, v47, v55
	v_pk_mul_f32 v[112:113], v[112:113], v[144:145]
	v_mul_f32_e32 v120, v120, v124
	v_add_f32_e32 v47, v47, v113
	v_add_f32_e32 v124, v112, v47
	v_mul_f32_e32 v47, 0x3d372713, v124
	v_mul_f32_e32 v47, v124, v47
	v_fma_f32 v47, v124, v47, v124
	v_mul_f32_e32 v47, 0xc0135761, v47
	v_exp_f32_e32 v125, v47
	v_lshlrev_b32_e32 v47, 16, v134
	v_fma_f32 v126, v58, v47, v54
	v_lshlrev_b32_e32 v47, 16, v133
	v_mov_b32_e32 v123, v50
	v_pk_mul_f32 v[112:113], v[122:123], v[46:47]
	s_nop 0
	v_add_f32_e32 v47, v126, v113
	v_add_f32_e32 v47, v112, v47
	v_mul_f32_e32 v112, 0x3d372713, v47
	v_mul_f32_e32 v112, v47, v112
	v_fma_f32 v112, v47, v112, v47
	v_mul_f32_e32 v112, 0xc0135761, v112
	v_exp_f32_e32 v112, v112
	v_mul_f32_e32 v113, v117, v120
	v_add_f32_e32 v117, 1.0, v125
	v_rcp_f32_e32 v117, v117
	v_add_f32_e32 v112, 1.0, v112
	v_rcp_f32_e32 v112, v112
	v_or_b32_e32 v120, 48, v202
	v_mul_f32_e32 v117, v124, v117
	v_mul_f32_e32 v115, v115, v117
	v_mul_f32_e32 v47, v47, v112
	v_cvt_pk_bf16_f32 v112, v116, v113
	v_mov_b64_e32 v[116:117], s[14:15]
	v_mad_i64_i32 v[116:117], s[62:63], v120, s91, v[116:117]
	v_cvt_pk_bf16_f32 v113, v118, v119
	v_lshl_add_u64 v[116:117], v[180:181], 1, v[116:117]
	v_mul_f32_e32 v47, v114, v47
	v_cvt_pk_bf16_f32 v114, v121, v130
	v_cvt_pk_bf16_f32 v115, v47, v115
	global_store_dwordx4 v[116:117], v[112:115], off
	s_nop 1
	v_lshl_add_u64 v[112:113], v[186:187], 0, v[170:171]
	s_and_saveexec_b64 s[62:63], s[26:27]
	s_cbranch_execz .LBB0_1297
	global_store_dwordx4 v[112:113], v[12:15], off
	global_store_dwordx4 v[112:113], v[4:7], off offset:16

; __device__ __forceinline__ unsigned cvt_pk_bf16(float lo, float hi) { unsigned r; asm volatile("v_cvt_pk_bf16_f32 %0, %1, %2" : "=v"(r) : "v"(lo), "v"(hi)); return r; }
; __device__ __forceinline__ float gelu_tanh_f(float x) { const float y = -2.3022081983651455f * (x + 0.044715f * x * x * x); return x * __builtin_amdgcn_rcpf(1.f + __builtin_amdgcn_exp2f(y)); }
;     __device__ __forceinline__ void operator()(const f32x4 (&acc)[2][2][4][2], const Unit& u, int wr, int wc, int fr, int fq) const {
;     ...
;             for (int m = 0; m < 4; ++m) {
;                 const int row = u.pm * BM + ai * HALF + wr * 64 + m * 16 + fr;
;                 unsigned pk[4];
;                 pk[0] = cvt_pk_bf16(acc[ai][0][m][0][0], acc[ai][0][m][0][1]); pk[1] = cvt_pk_bf16(acc[ai][0][m][0][2], acc[ai][0][m][0][3]);
;                 pk[2] = cvt_pk_bf16(acc[ai][0][m][1][0], acc[ai][0][m][1][1]); pk[3] = cvt_pk_bf16(acc[ai][0][m][1][2], acc[ai][0][m][1][3]);
;                 float hv[8];
; #pragma unroll
;                 for (int q = 0; q < 4; ++q) {
;                     unsigned g1 = (unsigned)__shfl_up((int)pk[q], 1, 16), g2 = (unsigned)__shfl_up((int)pk[q], 2, 16);
;                     if (fr == 0) { g1 = l15[q]; g2 = l14[q]; } else if (fr == 1) { g2 = l15[q]; }
;                     const unsigned n14 = (unsigned)__shfl((int)pk[q], 14, 16), n15 = (unsigned)__shfl((int)pk[q], 15, 16);
;                     l14[q] = n14; l15[q] = n15;
;                     const int n = q >> 1, j = (q & 1) * 2, e = 2 * q;
;                     const float x0 = bb[e] + w0[e] * __uint_as_float(g2 << 16) + w1[e] * __uint_as_float(g1 << 16) + w2[e] * acc[ai][0][m][n][j];
;                     const float x1 = bb[e + 1] + w0[e + 1] * __uint_as_float(g2 & 0xffff0000u) + w1[e + 1] * __uint_as_float(g1 & 0xffff0000u) + w2[e + 1] * acc[ai][0][m][n][j + 1];
;                     hv[e] = gelu_tanh_f(x0) * acc[ai][1][m][n][j]; hv[e + 1] = gelu_tanh_f(x1) * acc[ai][1][m][n][j + 1];
;                 }
;                 const bool first2 = (slab == 0 && m == 0 && fr < 2);
;                 if (!first2) { u32x4 w; w.x = cvt_pk_bf16(hv[0], hv[1]); w.y = cvt_pk_bf16(hv[2], hv[3]); w.z = cvt_pk_bf16(hv[4], hv[5]); w.w = cvt_pk_bf16(hv[6], hv[7]);
;                     *(u32x4*)(H + (size_t)row * ldh + f0) = w; }
.LBB0_1299:
	v_cvt_pk_bf16_f32 v123, v108, v109
	s_nop 1
	v_mov_b32_dpp v47, v123 row_shr:1 row_mask:0xf bank_mask:0xf
	v_mov_b32_dpp v122, v123 row_shr:2 row_mask:0xf bank_mask:0xf
	v_cmp_lt_i32_e32 vcc, 0, v188
	v_cvt_pk_bf16_f32 v127, v110, v111
	v_cvt_pk_bf16_f32 v126, v96, v97
	v_cvt_pk_bf16_f32 v124, v98, v99
	v_cmp_eq_u32_e64 s[98:99], 0, v188
	v_cmp_eq_u32_e64 s[100:101], 1, v188
	s_waitcnt lgkmcnt(2)
	s_nop 1
	v_cndmask_b32_e64 v122, v122, v118, s[100:101]
	v_cndmask_b32_e64 v122, v122, v114, s[98:99]
	v_cndmask_b32_e64 v47, v47, v118, s[98:99]
	ds_bpermute_b32 v118, v204, v123
	ds_bpermute_b32 v114, v203, v123
	s_nop 1
	v_mov_b32_dpp v123, v127 row_shr:1 row_mask:0xf bank_mask:0xf
	v_mov_b32_dpp v125, v127 row_shr:2 row_mask:0xf bank_mask:0xf
	v_cmp_lt_i32_e32 vcc, 0, v188
	v_cmp_eq_u32_e64 s[98:99], 0, v188
	v_cmp_eq_u32_e64 s[100:101], 1, v188
	s_waitcnt lgkmcnt(2)
	s_nop 1
	v_cndmask_b32_e64 v125, v125, v119, s[100:101]
	v_cndmask_b32_e64 v125, v125, v115, s[98:99]
	v_cndmask_b32_e64 v123, v123, v119, s[98:99]
	ds_bpermute_b32 v119, v204, v127
	ds_bpermute_b32 v115, v203, v127
	s_nop 1
	v_mov_b32_dpp v128, v126 row_shr:1 row_mask:0xf bank_mask:0xf
	v_mov_b32_dpp v129, v126 row_shr:2 row_mask:0xf bank_mask:0xf
	v_cmp_lt_i32_e32 vcc, 0, v188
	v_cmp_eq_u32_e64 s[98:99], 0, v188
	v_cmp_eq_u32_e64 s[100:101], 1, v188
	s_waitcnt lgkmcnt(2)
	s_nop 1
	v_cndmask_b32_e64 v129, v129, v120, s[100:101]
	v_cndmask_b32_e64 v129, v129, v116, s[98:99]
	v_cndmask_b32_e64 v128, v128, v120, s[98:99]
	ds_bpermute_b32 v120, v204, v126
	ds_bpermute_b32 v116, v203, v126
	s_nop 1
	v_mov_b32_dpp v126, v124 row_shr:1 row_mask:0xf bank_mask:0xf
	v_mov_b32_dpp v127, v124 row_shr:2 row_mask:0xf bank_mask:0xf
	v_cmp_lt_i32_e32 vcc, 0, v188
	v_cmp_eq_u32_e64 s[98:99], 0, v188
	v_cmp_eq_u32_e64 s[100:101], 1, v188
	s_waitcnt lgkmcnt(2)
	s_nop 1
	v_cndmask_b32_e64 v127, v127, v121, s[100:101]
	v_cndmask_b32_e64 v127, v127, v117, s[98:99]
	v_cndmask_b32_e64 v126, v126, v121, s[98:99]
	ds_bpermute_b32 v121, v204, v124
	ds_bpermute_b32 v117, v203, v124
	s_and_saveexec_b64 s[62:63], s[44:45]
	s_xor_b64 s[62:63], exec, s[62:63]
	s_cbranch_execz .LBB0_1325
	s_waitcnt lgkmcnt(6)
	v_lshlrev_b32_e32 v124, 16, v129
	v_fma_f32 v124, v56, v124, v52
	v_lshlrev_b32_e32 v130, 16, v128
	v_fmac_f32_e32 v124, v48, v130
	v_fmac_f32_e32 v124, v96, v44
	v_and_b32_e32 v96, 0xffff0000, v129
	v_fma_f32 v96, v57, v96, v53
	v_and_b32_e32 v128, 0xffff0000, v128
	v_fmac_f32_e32 v96, v49, v128
	v_fmac_f32_e32 v96, v97, v45
	v_mul_f32_e32 v97, 0x3d372713, v124
	v_mul_f32_e32 v97, v124, v97
	v_mul_f32_e32 v128, 0x3d372713, v96
	v_fma_f32 v97, v124, v97, v124
	v_mul_f32_e32 v128, v96, v128
	v_mul_f32_e32 v97, 0xc0135761, v97
	v_fma_f32 v128, v96, v128, v96
	v_exp_f32_e32 v97, v97
	v_mul_f32_e32 v128, 0xc0135761, v128
	v_exp_f32_e32 v128, v128
	s_waitcnt lgkmcnt(3)
	v_and_b32_e32 v145, 0xffff0000, v126
	v_add_f32_e32 v97, 1.0, v97
	v_rcp_f32_e32 v97, v97
	v_add_f32_e32 v128, 1.0, v128
	v_rcp_f32_e32 v128, v128
	v_mul_f32_e32 v97, v124, v97
	v_mul_f32_e32 v97, v80, v97
	v_mul_f32_e32 v80, v96, v128
	v_lshlrev_b32_e32 v96, 16, v125
	v_fma_f32 v96, v78, v96, v62
	v_lshlrev_b32_e32 v124, 16, v123
	v_fmac_f32_e32 v96, v70, v124
	v_fmac_f32_e32 v96, v110, v74
	v_mul_f32_e32 v124, 0x3d372713, v96
	v_mul_f32_e32 v124, v96, v124
	v_fma_f32 v124, v96, v124, v96
	v_mul_f32_e32 v124, 0xc0135761, v124
	v_exp_f32_e32 v124, v124
	v_and_b32_e32 v110, 0xffff0000, v125
	v_fma_f32 v110, v79, v110, v63
	v_and_b32_e32 v123, 0xffff0000, v123
	v_fmac_f32_e32 v110, v71, v123
	v_fmac_f32_e32 v110, v111, v75
	v_add_f32_e32 v111, 1.0, v124
	v_rcp_f32_e32 v111, v111
	v_mul_f32_e32 v124, v81, v80
	v_lshlrev_b32_e32 v81, 16, v122
	v_fma_f32 v81, v76, v81, v60
	v_mul_f32_e32 v80, v96, v111
	v_lshlrev_b32_e32 v96, 16, v47
	v_fmac_f32_e32 v81, v68, v96
	v_and_b32_e32 v96, 0xffff0000, v122
	v_fmac_f32_e32 v81, v108, v72
	v_fma_f32 v96, v77, v96, v61
	v_and_b32_e32 v47, 0xffff0000, v47
	v_mul_f32_e32 v123, 0x3d372713, v110
	v_fmac_f32_e32 v96, v69, v47
	v_mul_f32_e32 v47, 0x3d372713, v81
	v_mul_f32_e32 v123, v110, v123
	v_mul_f32_e32 v47, v81, v47
	v_fma_f32 v123, v110, v123, v110
	v_fma_f32 v47, v81, v47, v81
	v_mul_f32_e32 v123, 0xc0135761, v123
	v_fmac_f32_e32 v96, v109, v73
	v_mul_f32_e32 v47, 0xc0135761, v47
	v_exp_f32_e32 v123, v123
	v_exp_f32_e32 v47, v47
	v_mul_f32_e32 v108, 0x3d372713, v96
	v_mul_f32_e32 v108, v96, v108
	v_fma_f32 v108, v96, v108, v96
	v_mul_f32_e32 v108, 0xc0135761, v108
	v_mul_f32_e32 v86, v86, v80
	v_add_f32_e32 v80, 1.0, v123
	v_exp_f32_e32 v108, v108
	v_add_f32_e32 v47, 1.0, v47
	v_rcp_f32_e32 v80, v80
	v_rcp_f32_e32 v47, v47
	v_add_f32_e32 v108, 1.0, v108
	v_rcp_f32_e32 v108, v108
	v_mul_f32_e32 v80, v110, v80
	v_mul_f32_e32 v47, v81, v47
	v_mul_f32_e32 v87, v87, v80
	v_mul_f32_e32 v84, v84, v47
	s_waitcnt lgkmcnt(2)
	v_and_b32_e32 v47, 0xffff0000, v127
	v_mov_b32_e32 v80, v99
	v_mov_b32_e32 v81, v51
	v_fma_f32 v47, v59, v47, v55
	v_pk_mul_f32 v[80:81], v[80:81], v[144:145]
	v_mul_f32_e32 v96, v96, v108
	v_add_f32_e32 v47, v47, v81
	v_add_f32_e32 v108, v80, v47
	v_mul_f32_e32 v47, 0x3d372713, v108
	v_mul_f32_e32 v47, v108, v47
	v_fma_f32 v47, v108, v47, v108
	v_mul_f32_e32 v47, 0xc0135761, v47
	v_exp_f32_e32 v109, v47
	v_lshlrev_b32_e32 v47, 16, v127
	v_fma_f32 v110, v58, v47, v54
	v_lshlrev_b32_e32 v47, 16, v126
	v_mov_b32_e32 v99, v50
	v_pk_mul_f32 v[80:81], v[98:99], v[46:47]
	s_nop 0
	v_add_f32_e32 v47, v110, v81
	v_add_f32_e32 v47, v80, v47
	v_mul_f32_e32 v80, 0x3d372713, v47
	v_mul_f32_e32 v80, v47, v80
	v_fma_f32 v80, v47, v80, v47
	v_mul_f32_e32 v80, 0xc0135761, v80
	v_exp_f32_e32 v80, v80
	v_mul_f32_e32 v81, v85, v96
	v_add_f32_e32 v85, 1.0, v109
	v_rcp_f32_e32 v85, v85
	v_add_f32_e32 v80, 1.0, v80
	v_rcp_f32_e32 v80, v80
	v_add_u32_e32 v96, 0x80, v202
	v_mul_f32_e32 v85, v108, v85
	v_mul_f32_e32 v83, v83, v85
	v_mul_f32_e32 v47, v47, v80
	v_cvt_pk_bf16_f32 v80, v84, v81
	v_mov_b64_e32 v[84:85], s[14:15]
	v_mad_i64_i32 v[84:85], s[64:65], v96, s91, v[84:85]
	v_lshl_add_u64 v[84:85], v[180:181], 1, v[84:85]
	v_mul_f32_e32 v47, v82, v47
	v_cvt_pk_bf16_f32 v81, v86, v87
	v_cvt_pk_bf16_f32 v82, v97, v124
	v_cvt_pk_bf16_f32 v83, v47, v83
	global_store_dwordx4 v[84:85], v[80:83], off

; __device__ __forceinline__ unsigned cvt_pk_bf16(float lo, float hi) { unsigned r; asm volatile("v_cvt_pk_bf16_f32 %0, %1, %2" : "=v"(r) : "v"(lo), "v"(hi)); return r; }
; __device__ __forceinline__ float gelu_tanh_f(float x) { const float y = -2.3022081983651455f * (x + 0.044715f * x * x * x); return x * __builtin_amdgcn_rcpf(1.f + __builtin_amdgcn_exp2f(y)); }
;     __device__ __forceinline__ void operator()(const f32x4 (&acc)[2][2][4][2], const Unit& u, int wr, int wc, int fr, int fq) const {
;     ...
;             for (int m = 0; m < 4; ++m) {
;                 const int row = u.pm * BM + ai * HALF + wr * 64 + m * 16 + fr;
;                 unsigned pk[4];
;                 pk[0] = cvt_pk_bf16(acc[ai][0][m][0][0], acc[ai][0][m][0][1]); pk[1] = cvt_pk_bf16(acc[ai][0][m][0][2], acc[ai][0][m][0][3]);
;                 pk[2] = cvt_pk_bf16(acc[ai][0][m][1][0], acc[ai][0][m][1][1]); pk[3] = cvt_pk_bf16(acc[ai][0][m][1][2], acc[ai][0][m][1][3]);
;                 float hv[8];
; #pragma unroll
;                 for (int q = 0; q < 4; ++q) {
;                     unsigned g1 = (unsigned)__shfl_up((int)pk[q], 1, 16), g2 = (unsigned)__shfl_up((int)pk[q], 2, 16);
;                     if (fr == 0) { g1 = l15[q]; g2 = l14[q]; } else if (fr == 1) { g2 = l15[q]; }
;                     const unsigned n14 = (unsigned)__shfl((int)pk[q], 14, 16), n15 = (unsigned)__shfl((int)pk[q], 15, 16);
;                     l14[q] = n14; l15[q] = n15;
;                     const int n = q >> 1, j = (q & 1) * 2, e = 2 * q;
;                     const float x0 = bb[e] + w0[e] * __uint_as_float(g2 << 16) + w1[e] * __uint_as_float(g1 << 16) + w2[e] * acc[ai][0][m][n][j];
;                     const float x1 = bb[e + 1] + w0[e + 1] * __uint_as_float(g2 & 0xffff0000u) + w1[e + 1] * __uint_as_float(g1 & 0xffff0000u) + w2[e + 1] * acc[ai][0][m][n][j + 1];
;                     hv[e] = gelu_tanh_f(x0) * acc[ai][1][m][n][j]; hv[e + 1] = gelu_tanh_f(x1) * acc[ai][1][m][n][j + 1];
;                 }
;                 const bool first2 = (slab == 0 && m == 0 && fr < 2);
;                 if (!first2) { u32x4 w; w.x = cvt_pk_bf16(hv[0], hv[1]); w.y = cvt_pk_bf16(hv[2], hv[3]); w.z = cvt_pk_bf16(hv[4], hv[5]); w.w = cvt_pk_bf16(hv[6], hv[7]);
;                     *(u32x4*)(H + (size_t)row * ldh + f0) = w; }
.LBB0_1327:
	s_or_b64 exec, exec, s[62:63]
	v_cvt_pk_bf16_f32 v80, v64, v65
	s_waitcnt lgkmcnt(14)
	s_nop 1
	v_mov_b32_dpp v47, v80 row_shr:1 row_mask:0xf bank_mask:0xf
	v_mov_b32_dpp v87, v80 row_shr:2 row_mask:0xf bank_mask:0xf
	v_cmp_lt_i32_e32 vcc, 0, v188
	v_cvt_pk_bf16_f32 v81, v66, v67
	v_cvt_pk_bf16_f32 v82, v36, v37
	v_cvt_pk_bf16_f32 v86, v38, v39
	v_cmp_eq_u32_e64 s[98:99], 0, v188
	v_cmp_eq_u32_e64 s[100:101], 1, v188
	s_waitcnt lgkmcnt(2)
	s_nop 1
	v_cndmask_b32_e64 v87, v87, v114, s[100:101]
	v_cndmask_b32_e64 v87, v87, v118, s[98:99]
	v_cndmask_b32_e64 v47, v47, v114, s[98:99]
	ds_bpermute_b32 v83, v204, v80
	ds_bpermute_b32 v80, v203, v80
	s_nop 1
	v_mov_b32_dpp v88, v81 row_shr:1 row_mask:0xf bank_mask:0xf
	v_mov_b32_dpp v89, v81 row_shr:2 row_mask:0xf bank_mask:0xf
	v_cmp_lt_i32_e32 vcc, 0, v188
	v_cmp_eq_u32_e64 s[98:99], 0, v188
	v_cmp_eq_u32_e64 s[100:101], 1, v188
	s_waitcnt lgkmcnt(2)
	s_nop 1
	v_cndmask_b32_e64 v89, v89, v115, s[100:101]
	v_cndmask_b32_e64 v89, v89, v119, s[98:99]
	v_cndmask_b32_e64 v88, v88, v115, s[98:99]
	ds_bpermute_b32 v84, v204, v81
	ds_bpermute_b32 v81, v203, v81
	s_nop 1
	v_mov_b32_dpp v92, v82 row_shr:1 row_mask:0xf bank_mask:0xf
	v_mov_b32_dpp v93, v82 row_shr:2 row_mask:0xf bank_mask:0xf
	v_cmp_lt_i32_e32 vcc, 0, v188
	v_cmp_eq_u32_e64 s[98:99], 0, v188
	v_cmp_eq_u32_e64 s[100:101], 1, v188
	s_waitcnt lgkmcnt(2)
	s_nop 1
	v_cndmask_b32_e64 v93, v93, v116, s[100:101]
	v_cndmask_b32_e64 v93, v93, v120, s[98:99]
	v_cndmask_b32_e64 v92, v92, v116, s[98:99]
	ds_bpermute_b32 v85, v204, v82
	ds_bpermute_b32 v82, v203, v82
	s_nop 1
	v_mov_b32_dpp v90, v86 row_shr:1 row_mask:0xf bank_mask:0xf
	v_mov_b32_dpp v91, v86 row_shr:2 row_mask:0xf bank_mask:0xf
	v_cmp_lt_i32_e32 vcc, 0, v188
	v_cmp_eq_u32_e64 s[98:99], 0, v188
	v_cmp_eq_u32_e64 s[100:101], 1, v188
	s_waitcnt lgkmcnt(2)
	s_nop 1
	v_cndmask_b32_e64 v91, v91, v117, s[100:101]
	v_cndmask_b32_e64 v91, v91, v121, s[98:99]
	v_cndmask_b32_e64 v90, v90, v117, s[98:99]
	s_waitcnt lgkmcnt(4)
	v_lshlrev_b32_e32 v94, 16, v93
	v_fma_f32 v94, v56, v94, v52
	v_lshlrev_b32_e32 v95, 16, v92
	v_fmac_f32_e32 v94, v48, v95
	v_fmac_f32_e32 v94, v36, v44
	v_and_b32_e32 v36, 0xffff0000, v93
	v_fma_f32 v36, v57, v36, v53
	v_and_b32_e32 v92, 0xffff0000, v92
	v_fmac_f32_e32 v36, v49, v92
	v_fmac_f32_e32 v36, v37, v45
	v_mul_f32_e32 v37, 0x3d372713, v94
	v_mul_f32_e32 v37, v94, v37
	v_mul_f32_e32 v92, 0x3d372713, v36
	v_fma_f32 v37, v94, v37, v94
	v_mul_f32_e32 v92, v36, v92
	v_mul_f32_e32 v37, 0xc0135761, v37
	v_fma_f32 v92, v36, v92, v36
	v_exp_f32_e32 v37, v37
	v_mul_f32_e32 v92, 0xc0135761, v92
	v_exp_f32_e32 v92, v92
	s_waitcnt lgkmcnt(1)
	v_and_b32_e32 v145, 0xffff0000, v90
	v_add_f32_e32 v37, 1.0, v37
	v_rcp_f32_e32 v37, v37
	v_add_f32_e32 v92, 1.0, v92
	v_rcp_f32_e32 v92, v92
	v_cmp_lt_i32_e32 vcc, 0, v188
	v_mul_f32_e32 v37, v94, v37
	v_mul_f32_e32 v37, v32, v37
	v_mul_f32_e32 v32, v36, v92
	v_lshlrev_b32_e32 v36, 16, v89
	v_fma_f32 v36, v78, v36, v62
	v_lshlrev_b32_e32 v92, 16, v88
	v_fmac_f32_e32 v36, v70, v92
	v_fmac_f32_e32 v36, v66, v74
	v_and_b32_e32 v66, 0xffff0000, v89
	v_mul_f32_e32 v89, 0x3d372713, v36
	v_mul_f32_e32 v89, v36, v89
	v_fma_f32 v89, v36, v89, v36
	v_mul_f32_e32 v89, 0xc0135761, v89
	v_exp_f32_e32 v89, v89
	v_fma_f32 v66, v79, v66, v63
	v_and_b32_e32 v88, 0xffff0000, v88
	v_fmac_f32_e32 v66, v71, v88
	v_fmac_f32_e32 v66, v67, v75
	v_add_f32_e32 v67, 1.0, v89
	v_rcp_f32_e32 v67, v67
	v_mul_f32_e32 v89, v33, v32
	v_lshlrev_b32_e32 v33, 16, v87
	v_fma_f32 v33, v76, v33, v60
	v_mul_f32_e32 v32, v36, v67
	v_mul_f32_e32 v36, v42, v32
	v_lshlrev_b32_e32 v42, 16, v47
	v_fmac_f32_e32 v33, v68, v42
	v_and_b32_e32 v42, 0xffff0000, v87
	v_fma_f32 v42, v77, v42, v61
	v_and_b32_e32 v47, 0xffff0000, v47
	v_mul_f32_e32 v88, 0x3d372713, v66
	v_fmac_f32_e32 v33, v64, v72
	v_fmac_f32_e32 v42, v69, v47
	v_mul_f32_e32 v88, v66, v88
	v_fmac_f32_e32 v42, v65, v73
	v_mul_f32_e32 v47, 0x3d372713, v33
	v_fma_f32 v88, v66, v88, v66
	v_mul_f32_e32 v47, v33, v47
	v_mul_f32_e32 v64, 0x3d372713, v42
	v_mul_f32_e32 v88, 0xc0135761, v88
	v_fma_f32 v47, v33, v47, v33
	v_mul_f32_e32 v64, v42, v64
	v_exp_f32_e32 v88, v88
	v_mul_f32_e32 v47, 0xc0135761, v47
	v_fma_f32 v64, v42, v64, v42
	v_exp_f32_e32 v47, v47
	v_mul_f32_e32 v64, 0xc0135761, v64
	v_exp_f32_e32 v64, v64
	v_add_f32_e32 v32, 1.0, v88
	v_rcp_f32_e32 v32, v32
	v_add_f32_e32 v47, 1.0, v47
	v_rcp_f32_e32 v47, v47
	v_add_f32_e32 v64, 1.0, v64
	v_rcp_f32_e32 v64, v64
	v_mul_f32_e32 v32, v66, v32
	v_mul_f32_e32 v43, v43, v32
	v_mul_f32_e32 v32, v33, v47
	v_mul_f32_e32 v40, v40, v32
	v_mul_f32_e32 v32, v42, v64
	v_mul_f32_e32 v64, v41, v32
	s_waitcnt lgkmcnt(0)
	v_and_b32_e32 v32, 0xffff0000, v91
	v_fma_f32 v42, v59, v32, v55
	v_mov_b32_e32 v32, v39
	v_mov_b32_e32 v33, v51
	v_pk_mul_f32 v[32:33], v[32:33], v[144:145]
	v_lshlrev_b32_e32 v47, 16, v90
	v_add_f32_e32 v33, v42, v33
	v_add_f32_e32 v65, v32, v33
	v_mul_f32_e32 v32, 0x3d372713, v65
	v_mul_f32_e32 v32, v65, v32
	v_fma_f32 v32, v65, v32, v65
	v_mul_f32_e32 v32, 0xc0135761, v32
	v_exp_f32_e32 v66, v32
	v_lshlrev_b32_e32 v32, 16, v91
	v_mov_b32_e32 v39, v50
	v_fma_f32 v42, v58, v32, v54
	v_pk_mul_f32 v[32:33], v[38:39], v[46:47]
	v_add_f32_e32 v38, 1.0, v66
	v_add_f32_e32 v33, v42, v33
	v_add_f32_e32 v32, v32, v33
	v_mul_f32_e32 v33, 0x3d372713, v32
	v_mul_f32_e32 v33, v32, v33
	v_fma_f32 v33, v32, v33, v32
	v_mul_f32_e32 v33, 0xc0135761, v33
	v_exp_f32_e32 v33, v33
	v_rcp_f32_e32 v38, v38
	v_add_u32_e32 v39, 0x90, v202
	ds_bpermute_b32 v41, v204, v86
	v_add_f32_e32 v33, 1.0, v33
	v_rcp_f32_e32 v33, v33
	v_mul_f32_e32 v38, v65, v38
	v_mul_f32_e32 v35, v35, v38
	ds_bpermute_b32 v42, v203, v86
	v_mul_f32_e32 v32, v32, v33
	v_mul_f32_e32 v38, v34, v32
	v_cvt_pk_bf16_f32 v32, v40, v64
	v_cvt_pk_bf16_f32 v33, v36, v43
	v_cvt_pk_bf16_f32 v34, v37, v89
	v_mov_b64_e32 v[36:37], s[14:15]
	v_mad_i64_i32 v[36:37], s[62:63], v39, s91, v[36:37]
	v_lshl_add_u64 v[36:37], v[180:181], 1, v[36:37]
	v_cvt_pk_bf16_f32 v35, v38, v35
	global_store_dwordx4 v[36:37], v[32:35], off
	s_nop 1
	v_cvt_pk_bf16_f32 v32, v28, v29
	s_nop 1
	v_mov_b32_dpp v39, v32 row_shr:1 row_mask:0xf bank_mask:0xf
	v_mov_b32_dpp v40, v32 row_shr:2 row_mask:0xf bank_mask:0xf
	v_cvt_pk_bf16_f32 v33, v30, v31
	v_cvt_pk_bf16_f32 v34, v20, v21
	v_cvt_pk_bf16_f32 v38, v22, v23
	v_cmp_eq_u32_e64 s[98:99], 0, v188
	v_cmp_eq_u32_e64 s[100:101], 1, v188
	s_waitcnt lgkmcnt(2)
; __device__ __forceinline__ unsigned cvt_pk_bf16(float lo, float hi) { unsigned r; asm volatile("v_cvt_pk_bf16_f32 %0, %1, %2" : "=v"(r) : "v"(lo), "v"(hi)); return r; }
; __device__ __forceinline__ float gelu_tanh_f(float x) { const float y = -2.3022081983651455f * (x + 0.044715f * x * x * x); return x * __builtin_amdgcn_rcpf(1.f + __builtin_amdgcn_exp2f(y)); }
;     __device__ __forceinline__ void operator()(const f32x4 (&acc)[2][2][4][2], const Unit& u, int wr, int wc, int fr, int fq) const {
;     ...
;             for (int m = 0; m < 4; ++m) {
;                 const int row = u.pm * BM + ai * HALF + wr * 64 + m * 16 + fr;
;                 unsigned pk[4];
;                 pk[0] = cvt_pk_bf16(acc[ai][0][m][0][0], acc[ai][0][m][0][1]); pk[1] = cvt_pk_bf16(acc[ai][0][m][0][2], acc[ai][0][m][0][3]);
;                 pk[2] = cvt_pk_bf16(acc[ai][0][m][1][0], acc[ai][0][m][1][1]); pk[3] = cvt_pk_bf16(acc[ai][0][m][1][2], acc[ai][0][m][1][3]);
;                 float hv[8];
; #pragma unroll
;                 for (int q = 0; q < 4; ++q) {
;                     unsigned g1 = (unsigned)__shfl_up((int)pk[q], 1, 16), g2 = (unsigned)__shfl_up((int)pk[q], 2, 16);
;                     if (fr == 0) { g1 = l15[q]; g2 = l14[q]; } else if (fr == 1) { g2 = l15[q]; }
;                     const unsigned n14 = (unsigned)__shfl((int)pk[q], 14, 16), n15 = (unsigned)__shfl((int)pk[q], 15, 16);
;                     l14[q] = n14; l15[q] = n15;
;                     const int n = q >> 1, j = (q & 1) * 2, e = 2 * q;
;                     const float x0 = bb[e] + w0[e] * __uint_as_float(g2 << 16) + w1[e] * __uint_as_float(g1 << 16) + w2[e] * acc[ai][0][m][n][j];
;                     const float x1 = bb[e + 1] + w0[e + 1] * __uint_as_float(g2 & 0xffff0000u) + w1[e + 1] * __uint_as_float(g1 & 0xffff0000u) + w2[e + 1] * acc[ai][0][m][n][j + 1];
;                     hv[e] = gelu_tanh_f(x0) * acc[ai][1][m][n][j]; hv[e + 1] = gelu_tanh_f(x1) * acc[ai][1][m][n][j + 1];
;                 }
;                 const bool first2 = (slab == 0 && m == 0 && fr < 2);
;                 if (!first2) { u32x4 w; w.x = cvt_pk_bf16(hv[0], hv[1]); w.y = cvt_pk_bf16(hv[2], hv[3]); w.z = cvt_pk_bf16(hv[4], hv[5]); w.w = cvt_pk_bf16(hv[6], hv[7]);
;                     *(u32x4*)(H + (size_t)row * ldh + f0) = w; }
	s_nop 1
	v_cndmask_b32_e64 v40, v40, v80, s[100:101]
	v_cndmask_b32_e64 v40, v40, v83, s[98:99]
	v_cndmask_b32_e64 v39, v39, v80, s[98:99]
	ds_bpermute_b32 v35, v204, v32
	ds_bpermute_b32 v32, v203, v32
	s_nop 1
	v_mov_b32_dpp v43, v33 row_shr:1 row_mask:0xf bank_mask:0xf
	v_mov_b32_dpp v47, v33 row_shr:2 row_mask:0xf bank_mask:0xf
	v_cmp_lt_i32_e32 vcc, 0, v188
	v_cmp_eq_u32_e64 s[98:99], 0, v188
	v_cmp_eq_u32_e64 s[100:101], 1, v188
	s_waitcnt lgkmcnt(2)
	s_nop 1
	v_cndmask_b32_e64 v47, v47, v81, s[100:101]
	v_cndmask_b32_e64 v47, v47, v84, s[98:99]
	v_cndmask_b32_e64 v43, v43, v81, s[98:99]
	ds_bpermute_b32 v36, v204, v33
	ds_bpermute_b32 v33, v203, v33
	s_nop 1
	v_mov_b32_dpp v66, v34 row_shr:1 row_mask:0xf bank_mask:0xf
	v_mov_b32_dpp v67, v34 row_shr:2 row_mask:0xf bank_mask:0xf
	v_cmp_lt_i32_e32 vcc, 0, v188
	v_cmp_eq_u32_e64 s[98:99], 0, v188
	v_cmp_eq_u32_e64 s[100:101], 1, v188
	s_waitcnt lgkmcnt(2)
	s_nop 1
	v_cndmask_b32_e64 v67, v67, v82, s[100:101]
	v_cndmask_b32_e64 v67, v67, v85, s[98:99]
	v_cndmask_b32_e64 v66, v66, v82, s[98:99]
	ds_bpermute_b32 v37, v204, v34
	ds_bpermute_b32 v34, v203, v34
	s_nop 1
	v_mov_b32_dpp v64, v38 row_shr:1 row_mask:0xf bank_mask:0xf
	v_mov_b32_dpp v65, v38 row_shr:2 row_mask:0xf bank_mask:0xf
	v_cmp_lt_i32_e32 vcc, 0, v188
	v_cmp_eq_u32_e64 s[98:99], 0, v188
	v_cmp_eq_u32_e64 s[100:101], 1, v188
	s_waitcnt lgkmcnt(2)
	s_nop 1
	v_cndmask_b32_e64 v65, v65, v42, s[100:101]
	v_cndmask_b32_e64 v65, v65, v41, s[98:99]
	v_cndmask_b32_e64 v64, v64, v42, s[98:99]
	s_waitcnt lgkmcnt(4)
	v_lshlrev_b32_e32 v41, 16, v67
	v_fma_f32 v41, v56, v41, v52
	v_lshlrev_b32_e32 v42, 16, v66
	v_fmac_f32_e32 v41, v48, v42
	v_fmac_f32_e32 v41, v20, v44
	v_and_b32_e32 v20, 0xffff0000, v67
	v_fma_f32 v20, v57, v20, v53
	v_and_b32_e32 v42, 0xffff0000, v66
	v_fmac_f32_e32 v20, v49, v42
	v_fmac_f32_e32 v20, v21, v45
	v_mul_f32_e32 v21, 0x3d372713, v41
	v_mul_f32_e32 v21, v41, v21
	v_mul_f32_e32 v42, 0x3d372713, v20
	v_fma_f32 v21, v41, v21, v41
	v_mul_f32_e32 v42, v20, v42
	v_mul_f32_e32 v21, 0xc0135761, v21
	v_fma_f32 v42, v20, v42, v20
	v_exp_f32_e32 v21, v21
	v_mul_f32_e32 v42, 0xc0135761, v42
	v_exp_f32_e32 v42, v42
	s_waitcnt lgkmcnt(1)
	v_and_b32_e32 v145, 0xffff0000, v64
	v_add_f32_e32 v21, 1.0, v21
	v_rcp_f32_e32 v21, v21
	v_add_f32_e32 v42, 1.0, v42
	v_rcp_f32_e32 v42, v42
	v_cmp_lt_i32_e32 vcc, 0, v188
	v_mul_f32_e32 v21, v41, v21
	v_mul_f32_e32 v41, v16, v21
	v_mul_f32_e32 v16, v20, v42
	v_lshlrev_b32_e32 v20, 16, v47
	v_fma_f32 v20, v78, v20, v62
	v_lshlrev_b32_e32 v21, 16, v43
	v_fmac_f32_e32 v20, v70, v21
	v_fmac_f32_e32 v20, v30, v74
	v_mul_f32_e32 v30, 0x3d372713, v20
	v_mul_f32_e32 v30, v20, v30
	v_fma_f32 v30, v20, v30, v20
	v_mul_f32_e32 v30, 0xc0135761, v30
	v_exp_f32_e32 v30, v30
	v_and_b32_e32 v21, 0xffff0000, v47
	v_fma_f32 v21, v79, v21, v63
	v_and_b32_e32 v42, 0xffff0000, v43
	v_add_f32_e32 v30, 1.0, v30
	v_rcp_f32_e32 v30, v30
	v_fmac_f32_e32 v21, v71, v42
	v_fmac_f32_e32 v21, v31, v75
	v_mul_f32_e32 v31, 0x3d372713, v21
	v_mul_f32_e32 v42, v17, v16
	v_lshlrev_b32_e32 v17, 16, v40
	v_mul_f32_e32 v31, v21, v31
	v_mul_f32_e32 v16, v20, v30
	v_fma_f32 v17, v76, v17, v60
	v_lshlrev_b32_e32 v20, 16, v39
	v_fma_f32 v31, v21, v31, v21
	v_fmac_f32_e32 v17, v68, v20
	v_and_b32_e32 v20, 0xffff0000, v40
	v_mul_f32_e32 v31, 0xc0135761, v31
	v_fmac_f32_e32 v17, v28, v72
	v_fma_f32 v20, v77, v20, v61
	v_and_b32_e32 v28, 0xffff0000, v39
	v_exp_f32_e32 v31, v31
	v_fmac_f32_e32 v20, v69, v28
	v_fmac_f32_e32 v20, v29, v73
	v_mul_f32_e32 v28, 0x3d372713, v17
	v_mul_f32_e32 v28, v17, v28
	v_mul_f32_e32 v29, 0x3d372713, v20
	v_fma_f32 v28, v17, v28, v17
	v_mul_f32_e32 v29, v20, v29
	v_mul_f32_e32 v26, v26, v16
	v_add_f32_e32 v16, 1.0, v31
	v_mul_f32_e32 v28, 0xc0135761, v28
	v_fma_f32 v29, v20, v29, v20
	v_rcp_f32_e32 v16, v16
	v_exp_f32_e32 v28, v28
	v_mul_f32_e32 v29, 0xc0135761, v29
	v_exp_f32_e32 v29, v29
	v_mul_f32_e32 v16, v21, v16
	v_add_f32_e32 v21, 1.0, v28
	v_rcp_f32_e32 v21, v21
	v_add_f32_e32 v28, 1.0, v29
	v_rcp_f32_e32 v28, v28
	v_mul_f32_e32 v27, v27, v16
	v_mul_f32_e32 v16, v17, v21
	v_mul_f32_e32 v24, v24, v16
	v_mul_f32_e32 v16, v20, v28
	v_mul_f32_e32 v25, v25, v16
	s_waitcnt lgkmcnt(0)
	v_and_b32_e32 v16, 0xffff0000, v65
	v_fma_f32 v21, v59, v16, v55
	v_mov_b32_e32 v16, v23
	v_mov_b32_e32 v17, v51
	v_pk_mul_f32 v[16:17], v[16:17], v[144:145]
	v_lshlrev_b32_e32 v47, 16, v64
	v_add_f32_e32 v17, v21, v17
	v_add_f32_e32 v28, v16, v17
	v_mul_f32_e32 v16, 0x3d372713, v28
	v_mul_f32_e32 v16, v28, v16
	v_fma_f32 v16, v28, v16, v28
	v_mul_f32_e32 v16, 0xc0135761, v16
	v_exp_f32_e32 v29, v16
	v_lshlrev_b32_e32 v16, 16, v65
	v_mov_b32_e32 v23, v50
	v_fma_f32 v21, v58, v16, v54
	v_pk_mul_f32 v[16:17], v[22:23], v[46:47]
	v_add_f32_e32 v22, 1.0, v29
	v_add_f32_e32 v17, v21, v17
	v_add_f32_e32 v16, v16, v17
	v_mul_f32_e32 v17, 0x3d372713, v16
	v_mul_f32_e32 v17, v16, v17
	v_fma_f32 v17, v16, v17, v16
	v_mul_f32_e32 v17, 0xc0135761, v17
	v_exp_f32_e32 v17, v17
	v_rcp_f32_e32 v22, v22
	v_add_u32_e32 v29, 0xa0, v202
	ds_bpermute_b32 v20, v204, v38
	v_add_f32_e32 v17, 1.0, v17
	v_rcp_f32_e32 v17, v17
	v_mul_f32_e32 v22, v28, v22
	v_mul_f32_e32 v19, v19, v22
	ds_bpermute_b32 v21, v203, v38
	v_mul_f32_e32 v16, v16, v17
	v_mul_f32_e32 v22, v18, v16
	v_cvt_pk_bf16_f32 v16, v24, v25
	v_cvt_pk_bf16_f32 v17, v26, v27
	v_cvt_pk_bf16_f32 v18, v41, v42
	v_cvt_pk_bf16_f32 v19, v22, v19
	v_mov_b64_e32 v[22:23], s[14:15]
	v_mad_i64_i32 v[22:23], s[62:63], v29, s91, v[22:23]
	v_lshl_add_u64 v[22:23], v[180:181], 1, v[22:23]
	global_store_dwordx4 v[22:23], v[16:19], off
	s_nop 1
	v_cvt_pk_bf16_f32 v17, v12, v13
	s_nop 1
	v_mov_b32_dpp v16, v17 row_shr:1 row_mask:0xf bank_mask:0xf
	v_mov_b32_dpp v17, v17 row_shr:2 row_mask:0xf bank_mask:0xf
	v_cvt_pk_bf16_f32 v19, v14, v15
	v_cvt_pk_bf16_f32 v22, v4, v5
	v_cvt_pk_bf16_f32 v23, v6, v7
	v_cmp_eq_u32_e64 s[98:99], 0, v188
	v_cmp_eq_u32_e64 s[100:101], 1, v188
	s_waitcnt lgkmcnt(2)
;     __device__ __forceinline__ void operator()(const f32x4 (&acc)[2][2][4][2], const Unit& u, int wr, int wc, int fr, int fq) const {
;     ...
;             for (int m = 0; m < 4; ++m) {
;                 const int row = u.pm * BM + ai * HALF + wr * 64 + m * 16 + fr;
;                 unsigned pk[4];
;                 pk[0] = cvt_pk_bf16(acc[ai][0][m][0][0], acc[ai][0][m][0][1]); pk[1] = cvt_pk_bf16(acc[ai][0][m][0][2], acc[ai][0][m][0][3]);
;                 pk[2] = cvt_pk_bf16(acc[ai][0][m][1][0], acc[ai][0][m][1][1]); pk[3] = cvt_pk_bf16(acc[ai][0][m][1][2], acc[ai][0][m][1][3]);
;                 float hv[8];
; #pragma unroll
;                 for (int q = 0; q < 4; ++q) {
;                     unsigned g1 = (unsigned)__shfl_up((int)pk[q], 1, 16), g2 = (unsigned)__shfl_up((int)pk[q], 2, 16);
;                     if (fr == 0) { g1 = l15[q]; g2 = l14[q]; } else if (fr == 1) { g2 = l15[q]; }
;                     const unsigned n14 = (unsigned)__shfl((int)pk[q], 14, 16), n15 = (unsigned)__shfl((int)pk[q], 15, 16);
;                     l14[q] = n14; l15[q] = n15;
;                     const int n = q >> 1, j = (q & 1) * 2, e = 2 * q;
;                     const float x0 = bb[e] + w0[e] * __uint_as_float(g2 << 16) + w1[e] * __uint_as_float(g1 << 16) + w2[e] * acc[ai][0][m][n][j];
;                     const float x1 = bb[e + 1] + w0[e + 1] * __uint_as_float(g2 & 0xffff0000u) + w1[e + 1] * __uint_as_float(g1 & 0xffff0000u) + w2[e + 1] * acc[ai][0][m][n][j + 1];
;                     hv[e] = gelu_tanh_f(x0) * acc[ai][1][m][n][j]; hv[e + 1] = gelu_tanh_f(x1) * acc[ai][1][m][n][j + 1];
;                 }
;                 const bool first2 = (slab == 0 && m == 0 && fr < 2);
;                 if (!first2) { u32x4 w; w.x = cvt_pk_bf16(hv[0], hv[1]); w.y = cvt_pk_bf16(hv[2], hv[3]); w.z = cvt_pk_bf16(hv[4], hv[5]); w.w = cvt_pk_bf16(hv[6], hv[7]);
;                     *(u32x4*)(H + (size_t)row * ldh + f0) = w; }
;                 else { float* p = hp + (size_t)fr * ff; *(f32x4*)p = acc[0][0][0][0]; *(f32x4*)(p + 4) = acc[0][0][0][1];
;                     float* pu = hp + (size_t)(4 + fr) * ff; *(f32x4*)pu = acc[0][1][0][0]; *(f32x4*)(pu + 4) = acc[0][1][0][1]; }
;                 if (slab == 3 && m == 3 && fr >= 14) { float* p = hp + (size_t)(2 + fr - 14) * ff; *(f32x4*)p = acc[1][0][3][0]; *(f32x4*)(p + 4) = acc[1][0][3][1]; }
	s_nop 1
	v_cndmask_b32_e64 v17, v17, v32, s[100:101]
	v_cndmask_b32_e64 v17, v17, v35, s[98:99]
	v_cndmask_b32_e64 v16, v16, v32, s[98:99]
	s_nop 1
	v_mov_b32_dpp v18, v19 row_shr:1 row_mask:0xf bank_mask:0xf
	v_mov_b32_dpp v19, v19 row_shr:2 row_mask:0xf bank_mask:0xf
	v_cmp_lt_i32_e32 vcc, 0, v188
	v_cmp_eq_u32_e64 s[98:99], 0, v188
	v_cmp_eq_u32_e64 s[100:101], 1, v188
	s_waitcnt lgkmcnt(2)
	s_nop 1
	v_cndmask_b32_e64 v19, v19, v33, s[100:101]
	v_cndmask_b32_e64 v19, v19, v36, s[98:99]
	v_cndmask_b32_e64 v18, v18, v33, s[98:99]
	s_nop 1
	v_mov_b32_dpp v24, v22 row_shr:1 row_mask:0xf bank_mask:0xf
	v_mov_b32_dpp v25, v22 row_shr:2 row_mask:0xf bank_mask:0xf
	v_cmp_lt_i32_e32 vcc, 0, v188
	v_cmp_eq_u32_e64 s[98:99], 0, v188
	v_cmp_eq_u32_e64 s[100:101], 1, v188
	s_waitcnt lgkmcnt(2)
	s_nop 1
	v_cndmask_b32_e64 v25, v25, v34, s[100:101]
	v_cndmask_b32_e64 v25, v25, v37, s[98:99]
	v_cndmask_b32_e64 v24, v24, v34, s[98:99]
	s_nop 1
	v_mov_b32_dpp v22, v23 row_shr:1 row_mask:0xf bank_mask:0xf
	v_mov_b32_dpp v23, v23 row_shr:2 row_mask:0xf bank_mask:0xf
	v_cmp_lt_i32_e32 vcc, 0, v188
	v_cmp_eq_u32_e64 s[98:99], 0, v188
	v_cmp_eq_u32_e64 s[100:101], 1, v188
	s_waitcnt lgkmcnt(2)
	s_nop 1
	v_cndmask_b32_e64 v23, v23, v21, s[100:101]
	v_cndmask_b32_e64 v23, v23, v20, s[98:99]
	v_cndmask_b32_e64 v22, v22, v21, s[98:99]
	s_waitcnt lgkmcnt(2)
	v_lshlrev_b32_e32 v20, 16, v25
	v_fma_f32 v20, v56, v20, v52
	v_lshlrev_b32_e32 v21, 16, v24
	v_fmac_f32_e32 v20, v48, v21
	v_and_b32_e32 v21, 0xffff0000, v25
	v_fma_f32 v21, v57, v21, v53
	v_and_b32_e32 v24, 0xffff0000, v24
	v_fmac_f32_e32 v20, v4, v44
	v_fmac_f32_e32 v21, v49, v24
	v_fmac_f32_e32 v21, v5, v45
	v_mul_f32_e32 v24, 0x3d372713, v20
	v_mul_f32_e32 v24, v20, v24
	v_mul_f32_e32 v25, 0x3d372713, v21
	v_fma_f32 v24, v20, v24, v20
	v_mul_f32_e32 v25, v21, v25
	v_mul_f32_e32 v24, 0xc0135761, v24
	v_fma_f32 v25, v21, v25, v21
	v_exp_f32_e32 v24, v24
	v_mul_f32_e32 v25, 0xc0135761, v25
	v_exp_f32_e32 v25, v25
	s_waitcnt lgkmcnt(1)
	v_and_b32_e32 v145, 0xffff0000, v22
	v_add_f32_e32 v24, 1.0, v24
	v_rcp_f32_e32 v24, v24
	v_add_f32_e32 v25, 1.0, v25
	v_rcp_f32_e32 v25, v25
	v_lshlrev_b32_e32 v47, 16, v22
	v_mul_f32_e32 v20, v20, v24
	v_mul_f32_e32 v20, v0, v20
	v_mul_f32_e32 v0, v21, v25
	v_lshlrev_b32_e32 v21, 16, v19
	v_fma_f32 v21, v78, v21, v62
	v_lshlrev_b32_e32 v24, 16, v18
	v_fmac_f32_e32 v21, v70, v24
	v_fmac_f32_e32 v21, v14, v74
	v_mul_f32_e32 v24, 0x3d372713, v21
	v_mul_f32_e32 v24, v21, v24
	v_fma_f32 v24, v21, v24, v21
	v_mul_f32_e32 v24, 0xc0135761, v24
	v_exp_f32_e32 v24, v24
	v_and_b32_e32 v19, 0xffff0000, v19
	v_fma_f32 v19, v79, v19, v63
	v_and_b32_e32 v18, 0xffff0000, v18
	v_fmac_f32_e32 v19, v71, v18
	v_add_f32_e32 v18, 1.0, v24
	v_rcp_f32_e32 v18, v18
	v_mul_f32_e32 v25, v1, v0
	v_lshlrev_b32_e32 v1, 16, v17
	v_fma_f32 v1, v76, v1, v60
	v_mul_f32_e32 v0, v21, v18
	v_lshlrev_b32_e32 v18, 16, v16
	v_fmac_f32_e32 v19, v15, v75
	v_fmac_f32_e32 v1, v68, v18
	v_and_b32_e32 v17, 0xffff0000, v17
	v_mul_f32_e32 v24, 0x3d372713, v19
	v_fmac_f32_e32 v1, v12, v72
	v_fmac_f32_e32 v61, v77, v17
	v_and_b32_e32 v16, 0xffff0000, v16
	v_mul_f32_e32 v24, v19, v24
	v_fmac_f32_e32 v61, v69, v16
	v_mul_f32_e32 v16, 0x3d372713, v1
	v_fma_f32 v24, v19, v24, v19
	v_fmac_f32_e32 v61, v13, v73
	v_mul_f32_e32 v16, v1, v16
	v_mul_f32_e32 v24, 0xc0135761, v24
	v_fma_f32 v16, v1, v16, v1
	v_mul_f32_e32 v17, 0x3d372713, v61
	v_exp_f32_e32 v24, v24
	v_mul_f32_e32 v16, 0xc0135761, v16
	v_mul_f32_e32 v17, v61, v17
	v_exp_f32_e32 v16, v16
	v_fma_f32 v17, v61, v17, v61
	v_mul_f32_e32 v17, 0xc0135761, v17
	v_exp_f32_e32 v17, v17
	v_mul_f32_e32 v10, v10, v0
	v_add_f32_e32 v0, 1.0, v24
	v_rcp_f32_e32 v0, v0
	v_add_f32_e32 v16, 1.0, v16
	v_rcp_f32_e32 v16, v16
	v_add_f32_e32 v17, 1.0, v17
	v_rcp_f32_e32 v17, v17
	v_mul_f32_e32 v0, v19, v0
	v_mul_f32_e32 v11, v11, v0
	v_mul_f32_e32 v0, v1, v16
	v_mul_f32_e32 v8, v8, v0
	s_waitcnt lgkmcnt(0)
	v_and_b32_e32 v0, 0xffff0000, v23
	v_mul_f32_e32 v16, v61, v17
	v_fma_f32 v17, v59, v0, v55
	v_mov_b32_e32 v0, v7
	v_mov_b32_e32 v1, v51
	v_pk_mul_f32 v[0:1], v[0:1], v[144:145]
	v_mul_f32_e32 v9, v9, v16
	v_add_f32_e32 v1, v17, v1
	v_add_f32_e32 v17, v0, v1
	v_mul_f32_e32 v0, 0x3d372713, v17
	v_mul_f32_e32 v0, v17, v0
	v_fma_f32 v0, v17, v0, v17
	v_mul_f32_e32 v0, 0xc0135761, v0
	v_exp_f32_e32 v18, v0
	v_lshlrev_b32_e32 v0, 16, v23
	v_fmac_f32_e32 v54, v58, v0
	v_mov_b32_e32 v0, v6
	v_mov_b32_e32 v1, v50
	v_pk_mul_f32 v[0:1], v[0:1], v[46:47]
	v_add_f32_e32 v16, 1.0, v18
	v_add_f32_e32 v1, v54, v1
	v_add_f32_e32 v0, v0, v1
	v_mul_f32_e32 v1, 0x3d372713, v0
	v_mul_f32_e32 v1, v0, v1
	v_fma_f32 v1, v0, v1, v0
	v_mul_f32_e32 v1, 0xc0135761, v1
	v_exp_f32_e32 v1, v1
	v_rcp_f32_e32 v16, v16
	v_add_u32_e32 v18, 0xb0, v202
	v_add_f32_e32 v1, 1.0, v1
	v_rcp_f32_e32 v1, v1
	v_mul_f32_e32 v16, v17, v16
	v_mul_f32_e32 v3, v3, v16
	v_mul_f32_e32 v0, v0, v1
	v_mul_f32_e32 v16, v2, v0
	v_cvt_pk_bf16_f32 v0, v8, v9
	v_mov_b64_e32 v[8:9], s[14:15]
	v_mad_i64_i32 v[8:9], s[62:63], v18, s91, v[8:9]
	v_lshl_add_u64 v[8:9], v[180:181], 1, v[8:9]
	v_cvt_pk_bf16_f32 v1, v10, v11
	v_cvt_pk_bf16_f32 v2, v20, v25
	v_cvt_pk_bf16_f32 v3, v16, v3
	global_store_dwordx4 v[8:9], v[0:3], off
	s_and_saveexec_b64 s[62:63], s[46:47]
	s_cbranch_execz .LBB0_1401
	global_store_dwordx4 v[112:113], v[12:15], off
	global_store_dwordx4 v[112:113], v[4:7], off offset:16

; __device__ __forceinline__ unsigned cvt_pk_bf16(float lo, float hi) { unsigned r; asm volatile("v_cvt_pk_bf16_f32 %0, %1, %2" : "=v"(r) : "v"(lo), "v"(hi)); return r; }
;     __device__ __forceinline__ void operator()(const f32x4 (&acc)[2][2][4][2], const Unit& u, int wr, int wc, int fr, int fq) const {
;     ...
;             for (int m = 0; m < 4; ++m) {
;                 const int row = u.pm * BM + ai * HALF + wr * 64 + m * 16 + fr;
;                 unsigned pk[4];
;                 pk[0] = cvt_pk_bf16(acc[ai][0][m][0][0], acc[ai][0][m][0][1]); pk[1] = cvt_pk_bf16(acc[ai][0][m][0][2], acc[ai][0][m][0][3]);
;                 pk[2] = cvt_pk_bf16(acc[ai][0][m][1][0], acc[ai][0][m][1][1]); pk[3] = cvt_pk_bf16(acc[ai][0][m][1][2], acc[ai][0][m][1][3]);
;                 float hv[8];
; #pragma unroll
;                 for (int q = 0; q < 4; ++q) {
;                     unsigned g1 = (unsigned)__shfl_up((int)pk[q], 1, 16), g2 = (unsigned)__shfl_up((int)pk[q], 2, 16);
;                     if (fr == 0) { g1 = l15[q]; g2 = l14[q]; } else if (fr == 1) { g2 = l15[q]; }
;                     const unsigned n14 = (unsigned)__shfl((int)pk[q], 14, 16), n15 = (unsigned)__shfl((int)pk[q], 15, 16);
;                     l14[q] = n14; l15[q] = n15;
;                     const int n = q >> 1, j = (q & 1) * 2, e = 2 * q;
.LBB0_2407:
	v_add_u32_e32 v182, -1, v199
	v_and_b32_e32 v183, 0x70, v199
	v_cmp_lt_i32_e32 vcc, v182, v183
	v_cvt_pk_bf16_f32 v204, v104, v105
	v_cvt_pk_bf16_f32 v211, v106, v107
	v_cvt_pk_bf16_f32 v208, v100, v101
	v_cvt_pk_bf16_f32 v187, v102, v103
	s_nop 1
	v_cndmask_b32_e32 v182, v182, v199, vcc
	v_lshlrev_b32_e32 v200, 2, v182
	v_add_u32_e32 v182, -2, v199
	v_cmp_lt_i32_e32 vcc, v182, v183
	s_nop 1
	v_cndmask_b32_e32 v182, v182, v199, vcc
	v_lshlrev_b32_e32 v201, 2, v182
	s_nop 1
	v_mov_b32_dpp v182, v204 row_shr:1 row_mask:0xf bank_mask:0xf
	v_mov_b32_dpp v183, v204 row_shr:2 row_mask:0xf bank_mask:0xf
	v_cmp_lt_i32_e32 vcc, 0, v188
	v_cmp_eq_u32_e64 s[98:99], 0, v188
	v_cmp_eq_u32_e64 s[100:101], 1, v188
	s_waitcnt lgkmcnt(2)
	s_nop 1
	v_cndmask_b32_e64 v183, v183, v203, s[100:101]
	v_cndmask_b32_e64 v183, v183, v186, s[98:99]
	v_cndmask_b32_e64 v182, v182, v203, s[98:99]
	v_lshlrev_b32_e32 v186, 2, v199
	v_and_b32_e32 v212, 0x1c0, v186
	v_or_b32_e32 v203, 60, v186
	ds_bpermute_b32 v209, v212, v204 offset:56
	ds_bpermute_b32 v205, v203, v204
	s_nop 1
	v_mov_b32_dpp v186, v211 row_shr:1 row_mask:0xf bank_mask:0xf
	v_mov_b32_dpp v213, v211 row_shr:2 row_mask:0xf bank_mask:0xf
	v_or_b32_e32 v204, 56, v212
	v_cmp_lt_i32_e32 vcc, 0, v188
	v_cmp_eq_u32_e64 s[98:99], 0, v188
	v_cmp_eq_u32_e64 s[100:101], 1, v188
	s_waitcnt lgkmcnt(2)
	s_nop 1
	v_cndmask_b32_e64 v213, v213, v210, s[100:101]
	v_cndmask_b32_e64 v213, v213, v206, s[98:99]
	v_cndmask_b32_e64 v186, v186, v210, s[98:99]
	ds_bpermute_b32 v210, v204, v211
	ds_bpermute_b32 v206, v203, v211
	s_nop 1
	v_mov_b32_dpp v216, v208 row_shr:1 row_mask:0xf bank_mask:0xf
	v_mov_b32_dpp v217, v208 row_shr:2 row_mask:0xf bank_mask:0xf
	v_cmp_lt_i32_e32 vcc, 0, v188
	v_cmp_eq_u32_e64 s[98:99], 0, v188
	v_cmp_eq_u32_e64 s[100:101], 1, v188
	s_waitcnt lgkmcnt(2)
	s_nop 1
	v_cndmask_b32_e64 v217, v217, v207, s[100:101]
	v_cndmask_b32_e64 v217, v217, v202, s[98:99]
	v_cndmask_b32_e64 v216, v216, v207, s[98:99]
	ds_bpermute_b32 v211, v204, v208
	ds_bpermute_b32 v207, v203, v208
	s_nop 1
	v_mov_b32_dpp v214, v187 row_shr:1 row_mask:0xf bank_mask:0xf
	v_mov_b32_dpp v215, v187 row_shr:2 row_mask:0xf bank_mask:0xf
	v_cmp_lt_i32_e32 vcc, 0, v188
	v_cmp_eq_u32_e64 s[98:99], 0, v188
	v_cmp_eq_u32_e64 s[100:101], 1, v188
	s_waitcnt lgkmcnt(2)
	s_nop 1
	v_cndmask_b32_e64 v215, v215, v185, s[100:101]
	v_cndmask_b32_e64 v215, v215, v184, s[98:99]
	v_cndmask_b32_e64 v214, v214, v185, s[98:99]
	ds_bpermute_b32 v212, v204, v187
	ds_bpermute_b32 v208, v203, v187
	s_mul_i32 s57, s62, 0x40800
	s_mul_hi_i32 s55, s62, 0x40800
	s_add_u32 s64, s80, s57
	s_addc_u32 s65, s81, s55
	v_lshl_add_u32 v202, s62, 8, v189
	s_and_saveexec_b64 s[62:63], s[26:27]
	s_xor_b64 s[62:63], exec, s[62:63]
	s_cbranch_execz .LBB0_2433
; __device__ __forceinline__ unsigned cvt_pk_bf16(float lo, float hi) { unsigned r; asm volatile("v_cvt_pk_bf16_f32 %0, %1, %2" : "=v"(r) : "v"(lo), "v"(hi)); return r; }
; __device__ __forceinline__ float gelu_tanh_f(float x) { const float y = -2.3022081983651455f * (x + 0.044715f * x * x * x); return x * __builtin_amdgcn_rcpf(1.f + __builtin_amdgcn_exp2f(y)); }
;     __device__ __forceinline__ void operator()(const f32x4 (&acc)[2][2][4][2], const Unit& u, int wr, int wc, int fr, int fq) const {
;     ...
;                     const float x0 = bb[e] + w0[e] * __uint_as_float(g2 << 16) + w1[e] * __uint_as_float(g1 << 16) + w2[e] * acc[ai][0][m][n][j];
;                     const float x1 = bb[e + 1] + w0[e + 1] * __uint_as_float(g2 & 0xffff0000u) + w1[e + 1] * __uint_as_float(g1 & 0xffff0000u) + w2[e + 1] * acc[ai][0][m][n][j + 1];
;                     hv[e] = gelu_tanh_f(x0) * acc[ai][1][m][n][j]; hv[e + 1] = gelu_tanh_f(x1) * acc[ai][1][m][n][j + 1];
;                 }
;                 const bool first2 = (slab == 0 && m == 0 && fr < 2);
;                 if (!first2) { u32x4 w; w.x = cvt_pk_bf16(hv[0], hv[1]); w.y = cvt_pk_bf16(hv[2], hv[3]); w.z = cvt_pk_bf16(hv[4], hv[5]); w.w = cvt_pk_bf16(hv[6], hv[7]);
;                     *(u32x4*)(H + (size_t)row * ldh + f0) = w; }
	s_waitcnt lgkmcnt(0)
	v_lshlrev_b32_e32 v184, 16, v217
	s_waitcnt vmcnt(0)
	v_fma_f32 v184, v56, v184, v52
	v_lshlrev_b32_e32 v185, 16, v216
	v_fmac_f32_e32 v184, v48, v185
	v_fmac_f32_e32 v184, v100, v44
	v_mul_f32_e32 v187, 0x3d372713, v184
	v_mul_f32_e32 v187, v184, v187
	v_and_b32_e32 v185, 0xffff0000, v217
	v_fma_f32 v187, v184, v187, v184
	v_fma_f32 v185, v57, v185, v53
	v_mul_f32_e32 v187, 0xc0135761, v187
	v_and_b32_e32 v216, 0xffff0000, v216
	v_exp_f32_e32 v187, v187
	v_fmac_f32_e32 v185, v49, v216
	v_fmac_f32_e32 v185, v101, v45
	v_mul_f32_e32 v216, 0x3d372713, v185
	v_mul_f32_e32 v216, v185, v216
	v_add_f32_e32 v187, 1.0, v187
	v_fma_f32 v216, v185, v216, v185
	v_rcp_f32_e32 v187, v187
	v_mul_f32_e32 v216, 0xc0135761, v216
	v_exp_f32_e32 v216, v216
	v_lshlrev_b32_e32 v217, 16, v186
	v_mul_f32_e32 v184, v184, v187
	v_mul_f32_e32 v187, v88, v184
	v_add_f32_e32 v184, 1.0, v216
	v_lshlrev_b32_e32 v216, 16, v213
	v_fma_f32 v216, v78, v216, v62
	v_and_b32_e32 v213, 0xffff0000, v213
	v_fmac_f32_e32 v216, v70, v217
	v_fma_f32 v213, v79, v213, v63
	v_and_b32_e32 v186, 0xffff0000, v186
	v_fmac_f32_e32 v216, v106, v74
	v_fmac_f32_e32 v213, v71, v186
	v_fmac_f32_e32 v213, v107, v75
	v_mul_f32_e32 v186, 0x3d372713, v216
	v_mul_f32_e32 v186, v216, v186
	v_mul_f32_e32 v217, 0x3d372713, v213
	v_fma_f32 v186, v216, v186, v216
	v_mul_f32_e32 v217, v213, v217
	v_mul_f32_e32 v186, 0xc0135761, v186
	v_fma_f32 v217, v213, v217, v213
	v_rcp_f32_e32 v184, v184
	v_exp_f32_e32 v186, v186
	v_mul_f32_e32 v217, 0xc0135761, v217
	v_exp_f32_e32 v217, v217
	v_mul_f32_e32 v184, v185, v184
	v_add_f32_e32 v185, 1.0, v186
	v_rcp_f32_e32 v185, v185
	v_add_f32_e32 v186, 1.0, v217
	v_rcp_f32_e32 v186, v186
	v_mul_f32_e32 v217, v89, v184
	v_mul_f32_e32 v184, v216, v185
	v_lshlrev_b32_e32 v185, 16, v183
	v_mul_f32_e32 v216, v94, v184
	v_mul_f32_e32 v184, v213, v186
	v_fma_f32 v185, v76, v185, v60
	v_lshlrev_b32_e32 v186, 16, v182
	v_fmac_f32_e32 v185, v68, v186
	v_fmac_f32_e32 v185, v104, v72
	v_and_b32_e32 v183, 0xffff0000, v183
	v_fma_f32 v186, v77, v183, v61
	v_mul_f32_e32 v183, 0x3d372713, v185
	v_mul_f32_e32 v183, v185, v183
	v_fma_f32 v183, v185, v183, v185
	v_mul_f32_e32 v183, 0xc0135761, v183
	v_exp_f32_e32 v183, v183
	v_and_b32_e32 v182, 0xffff0000, v182
	v_fmac_f32_e32 v186, v69, v182
	v_fmac_f32_e32 v186, v105, v73
	v_add_f32_e32 v182, 1.0, v183
	v_mul_f32_e32 v183, 0x3d372713, v186
	v_mul_f32_e32 v183, v186, v183
	v_fma_f32 v183, v186, v183, v186
	v_rcp_f32_e32 v182, v182
	v_mul_f32_e32 v183, 0xc0135761, v183
	v_exp_f32_e32 v183, v183
	v_mul_f32_e32 v213, v95, v184
	v_mul_f32_e32 v182, v185, v182
	v_mul_f32_e32 v218, v92, v182
	v_add_f32_e32 v182, 1.0, v183
	v_rcp_f32_e32 v219, v182
	v_and_b32_e32 v182, 0xffff0000, v215
	v_fma_f32 v220, v59, v182, v55
	v_and_b32_e32 v183, 0xffff0000, v214
	v_mov_b32_e32 v184, v103
	v_mov_b32_e32 v185, v51
	v_mov_b32_e32 v182, v47
	v_pk_mul_f32 v[182:183], v[184:185], v[182:183]
	v_mov_b32_e32 v184, v102
	v_add_f32_e32 v183, v220, v183
	v_add_f32_e32 v220, v182, v183
	v_mul_f32_e32 v182, 0x3d372713, v220
	v_mul_f32_e32 v182, v220, v182
	v_fma_f32 v182, v220, v182, v220
	v_mul_f32_e32 v182, 0xc0135761, v182
	v_exp_f32_e32 v221, v182
	v_lshlrev_b32_e32 v182, 16, v215
	v_fma_f32 v215, v58, v182, v54
	v_lshlrev_b32_e32 v183, 16, v214
	v_mov_b32_e32 v185, v50
	v_mov_b32_e32 v182, v46
	v_pk_mul_f32 v[182:183], v[184:185], v[182:183]
	v_add_f32_e32 v185, 1.0, v221
	v_add_f32_e32 v183, v215, v183
	v_add_f32_e32 v182, v182, v183
	v_mul_f32_e32 v183, 0x3d372713, v182
	v_mul_f32_e32 v183, v182, v183
	v_fma_f32 v183, v182, v183, v182
	v_mul_f32_e32 v183, 0xc0135761, v183
	v_exp_f32_e32 v183, v183
	v_rcp_f32_e32 v185, v185
	v_mul_f32_e32 v184, v186, v219
	v_mul_f32_e32 v184, v93, v184
	v_add_f32_e32 v183, 1.0, v183
	v_rcp_f32_e32 v183, v183
	v_mul_f32_e32 v185, v220, v185
	v_mul_f32_e32 v185, v91, v185
	v_mul_f32_e32 v182, v182, v183
	v_mul_f32_e32 v186, v90, v182
	v_cvt_pk_bf16_f32 v182, v218, v184
	v_cvt_pk_bf16_f32 v183, v216, v213
	v_cvt_pk_bf16_f32 v184, v187, v217
	v_cvt_pk_bf16_f32 v185, v186, v185
	v_mov_b64_e32 v[186:187], s[14:15]
	v_mad_i64_i32 v[186:187], s[66:67], v202, s91, v[186:187]
	v_lshl_add_u64 v[186:187], v[180:181], 1, v[186:187]
	global_store_dwordx4 v[186:187], v[182:185], off

; __device__ __forceinline__ unsigned cvt_pk_bf16(float lo, float hi) { unsigned r; asm volatile("v_cvt_pk_bf16_f32 %0, %1, %2" : "=v"(r) : "v"(lo), "v"(hi)); return r; }
; __device__ __forceinline__ float gelu_tanh_f(float x) { const float y = -2.3022081983651455f * (x + 0.044715f * x * x * x); return x * __builtin_amdgcn_rcpf(1.f + __builtin_amdgcn_exp2f(y)); }
;     __device__ __forceinline__ void operator()(const f32x4 (&acc)[2][2][4][2], const Unit& u, int wr, int wc, int fr, int fq) const {
;     ...
;                 pk[0] = cvt_pk_bf16(acc[ai][0][m][0][0], acc[ai][0][m][0][1]); pk[1] = cvt_pk_bf16(acc[ai][0][m][0][2], acc[ai][0][m][0][3]);
;                 pk[2] = cvt_pk_bf16(acc[ai][0][m][1][0], acc[ai][0][m][1][1]); pk[3] = cvt_pk_bf16(acc[ai][0][m][1][2], acc[ai][0][m][1][3]);
;                 float hv[8];
; #pragma unroll
;                 for (int q = 0; q < 4; ++q) {
;                     unsigned g1 = (unsigned)__shfl_up((int)pk[q], 1, 16), g2 = (unsigned)__shfl_up((int)pk[q], 2, 16);
;                     if (fr == 0) { g1 = l15[q]; g2 = l14[q]; } else if (fr == 1) { g2 = l15[q]; }
;                     const unsigned n14 = (unsigned)__shfl((int)pk[q], 14, 16), n15 = (unsigned)__shfl((int)pk[q], 15, 16);
;                     l14[q] = n14; l15[q] = n15;
;                     const int n = q >> 1, j = (q & 1) * 2, e = 2 * q;
;                     const float x0 = bb[e] + w0[e] * __uint_as_float(g2 << 16) + w1[e] * __uint_as_float(g1 << 16) + w2[e] * acc[ai][0][m][n][j];
;                     const float x1 = bb[e + 1] + w0[e + 1] * __uint_as_float(g2 & 0xffff0000u) + w1[e + 1] * __uint_as_float(g1 & 0xffff0000u) + w2[e + 1] * acc[ai][0][m][n][j + 1];
;                     hv[e] = gelu_tanh_f(x0) * acc[ai][1][m][n][j]; hv[e + 1] = gelu_tanh_f(x1) * acc[ai][1][m][n][j + 1];
;                 }
;                 const bool first2 = (slab == 0 && m == 0 && fr < 2);
;                 if (!first2) { u32x4 w; w.x = cvt_pk_bf16(hv[0], hv[1]); w.y = cvt_pk_bf16(hv[2], hv[3]); w.z = cvt_pk_bf16(hv[4], hv[5]); w.w = cvt_pk_bf16(hv[6], hv[7]);
;                     *(u32x4*)(H + (size_t)row * ldh + f0) = w; }
.LBB0_2435:
	s_or_b64 exec, exec, s[62:63]
	v_cvt_pk_bf16_f32 v216, v156, v157
	s_nop 1
	v_mov_b32_dpp v214, v216 row_shr:1 row_mask:0xf bank_mask:0xf
	v_mov_b32_dpp v215, v216 row_shr:2 row_mask:0xf bank_mask:0xf
	v_cmp_lt_i32_e32 vcc, 0, v188
	v_cvt_pk_bf16_f32 v219, v158, v159
	v_cvt_pk_bf16_f32 v218, v148, v149
	v_cvt_pk_bf16_f32 v213, v150, v151
	v_cmp_eq_u32_e64 s[98:99], 0, v188
	v_cmp_eq_u32_e64 s[100:101], 1, v188
	s_waitcnt lgkmcnt(2)
	s_nop 1
	v_cndmask_b32_e64 v215, v215, v205, s[100:101]
	v_cndmask_b32_e64 v215, v215, v209, s[98:99]
	v_cndmask_b32_e64 v214, v214, v205, s[98:99]
	ds_bpermute_b32 v209, v204, v216
	ds_bpermute_b32 v205, v203, v216
	s_nop 1
	v_mov_b32_dpp v216, v219 row_shr:1 row_mask:0xf bank_mask:0xf
	v_mov_b32_dpp v217, v219 row_shr:2 row_mask:0xf bank_mask:0xf
	v_cmp_lt_i32_e32 vcc, 0, v188
	v_cmp_eq_u32_e64 s[98:99], 0, v188
	v_cmp_eq_u32_e64 s[100:101], 1, v188
	s_waitcnt lgkmcnt(2)
	s_nop 1
	v_cndmask_b32_e64 v217, v217, v206, s[100:101]
	v_cndmask_b32_e64 v217, v217, v210, s[98:99]
	v_cndmask_b32_e64 v216, v216, v206, s[98:99]
	ds_bpermute_b32 v210, v204, v219
	ds_bpermute_b32 v206, v203, v219
	s_nop 1
	v_mov_b32_dpp v220, v218 row_shr:1 row_mask:0xf bank_mask:0xf
	v_mov_b32_dpp v221, v218 row_shr:2 row_mask:0xf bank_mask:0xf
	v_cmp_lt_i32_e32 vcc, 0, v188
	v_cmp_eq_u32_e64 s[98:99], 0, v188
	v_cmp_eq_u32_e64 s[100:101], 1, v188
	s_waitcnt lgkmcnt(2)
	s_nop 1
	v_cndmask_b32_e64 v221, v221, v207, s[100:101]
	v_cndmask_b32_e64 v221, v221, v211, s[98:99]
	v_cndmask_b32_e64 v220, v220, v207, s[98:99]
	ds_bpermute_b32 v211, v204, v218
	ds_bpermute_b32 v207, v203, v218
	s_nop 1
	v_mov_b32_dpp v218, v213 row_shr:1 row_mask:0xf bank_mask:0xf
	v_mov_b32_dpp v219, v213 row_shr:2 row_mask:0xf bank_mask:0xf
	v_cmp_lt_i32_e32 vcc, 0, v188
	v_cmp_eq_u32_e64 s[98:99], 0, v188
	v_cmp_eq_u32_e64 s[100:101], 1, v188
	s_waitcnt lgkmcnt(2)
	s_nop 1
	v_cndmask_b32_e64 v219, v219, v208, s[100:101]
	v_cndmask_b32_e64 v219, v219, v212, s[98:99]
	v_cndmask_b32_e64 v218, v218, v208, s[98:99]
	s_waitcnt lgkmcnt(0)
	v_lshlrev_b32_e32 v208, 16, v221
	s_waitcnt vmcnt(0)
	v_fma_f32 v208, v56, v208, v52
	v_lshlrev_b32_e32 v212, 16, v220
	v_fmac_f32_e32 v208, v48, v212
	v_fmac_f32_e32 v208, v148, v44
	v_and_b32_e32 v148, 0xffff0000, v221
	v_fma_f32 v148, v57, v148, v53
	v_and_b32_e32 v212, 0xffff0000, v220
	v_fmac_f32_e32 v148, v49, v212
	v_fmac_f32_e32 v148, v149, v45
	v_mul_f32_e32 v149, 0x3d372713, v208
	v_mul_f32_e32 v149, v208, v149
	v_mul_f32_e32 v212, 0x3d372713, v148
	v_fma_f32 v149, v208, v149, v208
	v_mul_f32_e32 v212, v148, v212
	v_mul_f32_e32 v149, 0xc0135761, v149
	v_fma_f32 v212, v148, v212, v148
	v_exp_f32_e32 v149, v149
	v_mul_f32_e32 v212, 0xc0135761, v212
	v_exp_f32_e32 v212, v212
	v_cmp_lt_i32_e32 vcc, 0, v188
	v_add_f32_e32 v149, 1.0, v149
	v_rcp_f32_e32 v149, v149
	v_add_f32_e32 v212, 1.0, v212
	v_rcp_f32_e32 v212, v212
	v_mul_f32_e32 v149, v208, v149
	v_mul_f32_e32 v208, v144, v149
	v_mul_f32_e32 v144, v148, v212
	v_lshlrev_b32_e32 v148, 16, v217
	v_fma_f32 v148, v78, v148, v62
	v_lshlrev_b32_e32 v149, 16, v216
	v_fmac_f32_e32 v148, v70, v149
	v_fmac_f32_e32 v148, v158, v74
	v_mul_f32_e32 v158, 0x3d372713, v148
	v_mul_f32_e32 v158, v148, v158
	v_fma_f32 v158, v148, v158, v148
	v_mul_f32_e32 v158, 0xc0135761, v158
	v_exp_f32_e32 v158, v158
	v_and_b32_e32 v149, 0xffff0000, v217
	v_fma_f32 v149, v79, v149, v63
	v_and_b32_e32 v212, 0xffff0000, v216
	v_add_f32_e32 v158, 1.0, v158
	v_rcp_f32_e32 v158, v158
	v_fmac_f32_e32 v149, v71, v212
	v_fmac_f32_e32 v149, v159, v75
	v_mul_f32_e32 v159, 0x3d372713, v149
	v_mul_f32_e32 v145, v145, v144
	v_mul_f32_e32 v144, v148, v158
	v_lshlrev_b32_e32 v148, 16, v215
	v_mul_f32_e32 v159, v149, v159
	v_mul_f32_e32 v158, v154, v144
	v_fma_f32 v148, v76, v148, v60
	v_lshlrev_b32_e32 v154, 16, v214
	v_fma_f32 v159, v149, v159, v149
	v_fmac_f32_e32 v148, v68, v154
	v_and_b32_e32 v154, 0xffff0000, v215
	v_mul_f32_e32 v159, 0xc0135761, v159
	v_fmac_f32_e32 v148, v156, v72
	v_fma_f32 v154, v77, v154, v61
	v_and_b32_e32 v156, 0xffff0000, v214
	v_exp_f32_e32 v159, v159
	v_fmac_f32_e32 v154, v69, v156
	v_fmac_f32_e32 v154, v157, v73
	v_mul_f32_e32 v156, 0x3d372713, v148
	v_mul_f32_e32 v156, v148, v156
	v_mul_f32_e32 v157, 0x3d372713, v154
	v_fma_f32 v156, v148, v156, v148
	v_mul_f32_e32 v157, v154, v157
	v_add_f32_e32 v144, 1.0, v159
	v_mul_f32_e32 v156, 0xc0135761, v156
	v_fma_f32 v157, v154, v157, v154
	v_rcp_f32_e32 v144, v144
	v_exp_f32_e32 v156, v156
	v_mul_f32_e32 v157, 0xc0135761, v157
	v_exp_f32_e32 v157, v157
	v_mul_f32_e32 v144, v149, v144
	v_add_f32_e32 v149, 1.0, v156
	v_rcp_f32_e32 v149, v149
	v_add_f32_e32 v156, 1.0, v157
	v_rcp_f32_e32 v156, v156
	v_mul_f32_e32 v157, v155, v144
	v_mul_f32_e32 v144, v148, v149
	v_mul_f32_e32 v152, v152, v144
	v_mul_f32_e32 v144, v154, v156
	v_mul_f32_e32 v156, v153, v144
	v_and_b32_e32 v144, 0xffff0000, v219
	v_and_b32_e32 v149, 0xffff0000, v218
	v_mov_b32_e32 v154, v151
	v_mov_b32_e32 v155, v51
	v_mov_b32_e32 v148, v47
	v_fma_f32 v159, v59, v144, v55
	v_pk_mul_f32 v[148:149], v[154:155], v[148:149]
	v_mov_b32_e32 v144, v47
	v_add_f32_e32 v47, v159, v149
	v_add_f32_e32 v155, v148, v47
	v_mul_f32_e32 v47, 0x3d372713, v155
	v_mul_f32_e32 v47, v155, v47
	v_fma_f32 v47, v155, v47, v155
	v_mul_f32_e32 v47, 0xc0135761, v47
	v_exp_f32_e32 v159, v47
	v_lshlrev_b32_e32 v47, 16, v219
	v_fma_f32 v154, v58, v47, v54
	v_lshlrev_b32_e32 v47, 16, v218
	v_mov_b32_e32 v151, v50
	v_pk_mul_f32 v[148:149], v[150:151], v[46:47]
	v_mov_b64_e32 v[150:151], s[14:15]
	v_add_f32_e32 v47, v154, v149
	v_add_f32_e32 v47, v148, v47
	v_mul_f32_e32 v148, 0x3d372713, v47
	v_mul_f32_e32 v148, v47, v148
	v_fma_f32 v148, v47, v148, v47
	v_mul_f32_e32 v148, 0xc0135761, v148
	v_exp_f32_e32 v148, v148
	v_add_f32_e32 v149, 1.0, v159
	v_rcp_f32_e32 v149, v149
	v_or_b32_e32 v159, 16, v202
	v_add_f32_e32 v148, 1.0, v148
	v_rcp_f32_e32 v148, v148
	v_mul_f32_e32 v149, v155, v149
	v_mad_i64_i32 v[150:151], s[62:63], v159, s91, v[150:151]
	v_mul_f32_e32 v47, v47, v148
	v_mul_f32_e32 v149, v147, v149
	v_mul_f32_e32 v47, v146, v47
	v_cvt_pk_bf16_f32 v146, v152, v156
	v_lshl_add_u64 v[150:151], v[180:181], 1, v[150:151]
	ds_bpermute_b32 v153, v204, v213
	ds_bpermute_b32 v154, v203, v213
	v_cvt_pk_bf16_f32 v147, v158, v157
	v_cvt_pk_bf16_f32 v148, v208, v145
	v_cvt_pk_bf16_f32 v149, v47, v149
	global_store_dwordx4 v[150:151], v[146:149], off
	s_nop 1
	v_cvt_pk_bf16_f32 v146, v140, v141
	s_nop 1
	v_mov_b32_dpp v47, v146 row_shr:1 row_mask:0xf bank_mask:0xf
	v_mov_b32_dpp v145, v146 row_shr:2 row_mask:0xf bank_mask:0xf
	v_cvt_pk_bf16_f32 v147, v142, v143
	v_cvt_pk_bf16_f32 v148, v132, v133
	v_cvt_pk_bf16_f32 v152, v134, v135
	v_cmp_eq_u32_e64 s[98:99], 0, v188
	v_cmp_eq_u32_e64 s[100:101], 1, v188
	s_waitcnt lgkmcnt(2)
; __device__ __forceinline__ unsigned cvt_pk_bf16(float lo, float hi) { unsigned r; asm volatile("v_cvt_pk_bf16_f32 %0, %1, %2" : "=v"(r) : "v"(lo), "v"(hi)); return r; }
; __device__ __forceinline__ float gelu_tanh_f(float x) { const float y = -2.3022081983651455f * (x + 0.044715f * x * x * x); return x * __builtin_amdgcn_rcpf(1.f + __builtin_amdgcn_exp2f(y)); }
;     __device__ __forceinline__ void operator()(const f32x4 (&acc)[2][2][4][2], const Unit& u, int wr, int wc, int fr, int fq) const {
;     ...
;                 pk[0] = cvt_pk_bf16(acc[ai][0][m][0][0], acc[ai][0][m][0][1]); pk[1] = cvt_pk_bf16(acc[ai][0][m][0][2], acc[ai][0][m][0][3]);
;                 pk[2] = cvt_pk_bf16(acc[ai][0][m][1][0], acc[ai][0][m][1][1]); pk[3] = cvt_pk_bf16(acc[ai][0][m][1][2], acc[ai][0][m][1][3]);
;                 float hv[8];
; #pragma unroll
;                 for (int q = 0; q < 4; ++q) {
;                     unsigned g1 = (unsigned)__shfl_up((int)pk[q], 1, 16), g2 = (unsigned)__shfl_up((int)pk[q], 2, 16);
;                     if (fr == 0) { g1 = l15[q]; g2 = l14[q]; } else if (fr == 1) { g2 = l15[q]; }
;                     const unsigned n14 = (unsigned)__shfl((int)pk[q], 14, 16), n15 = (unsigned)__shfl((int)pk[q], 15, 16);
;                     l14[q] = n14; l15[q] = n15;
;                     const int n = q >> 1, j = (q & 1) * 2, e = 2 * q;
;                     const float x0 = bb[e] + w0[e] * __uint_as_float(g2 << 16) + w1[e] * __uint_as_float(g1 << 16) + w2[e] * acc[ai][0][m][n][j];
;                     const float x1 = bb[e + 1] + w0[e + 1] * __uint_as_float(g2 & 0xffff0000u) + w1[e + 1] * __uint_as_float(g1 & 0xffff0000u) + w2[e + 1] * acc[ai][0][m][n][j + 1];
;                     hv[e] = gelu_tanh_f(x0) * acc[ai][1][m][n][j]; hv[e + 1] = gelu_tanh_f(x1) * acc[ai][1][m][n][j + 1];
;                 }
;                 const bool first2 = (slab == 0 && m == 0 && fr < 2);
;                 if (!first2) { u32x4 w; w.x = cvt_pk_bf16(hv[0], hv[1]); w.y = cvt_pk_bf16(hv[2], hv[3]); w.z = cvt_pk_bf16(hv[4], hv[5]); w.w = cvt_pk_bf16(hv[6], hv[7]);
;                     *(u32x4*)(H + (size_t)row * ldh + f0) = w; }
	s_nop 1
	v_cndmask_b32_e64 v145, v145, v205, s[100:101]
	v_cndmask_b32_e64 v145, v145, v209, s[98:99]
	v_cndmask_b32_e64 v47, v47, v205, s[98:99]
	ds_bpermute_b32 v149, v204, v146
	ds_bpermute_b32 v146, v203, v146
	s_nop 1
	v_mov_b32_dpp v155, v147 row_shr:1 row_mask:0xf bank_mask:0xf
	v_mov_b32_dpp v156, v147 row_shr:2 row_mask:0xf bank_mask:0xf
	v_cmp_lt_i32_e32 vcc, 0, v188
	v_cmp_eq_u32_e64 s[98:99], 0, v188
	v_cmp_eq_u32_e64 s[100:101], 1, v188
	s_waitcnt lgkmcnt(2)
	s_nop 1
	v_cndmask_b32_e64 v156, v156, v206, s[100:101]
	v_cndmask_b32_e64 v156, v156, v210, s[98:99]
	v_cndmask_b32_e64 v155, v155, v206, s[98:99]
	ds_bpermute_b32 v150, v204, v147
	ds_bpermute_b32 v147, v203, v147
	s_nop 1
	v_mov_b32_dpp v159, v148 row_shr:1 row_mask:0xf bank_mask:0xf
	v_mov_b32_dpp v205, v148 row_shr:2 row_mask:0xf bank_mask:0xf
	v_cmp_lt_i32_e32 vcc, 0, v188
	v_cmp_eq_u32_e64 s[98:99], 0, v188
	v_cmp_eq_u32_e64 s[100:101], 1, v188
	s_waitcnt lgkmcnt(2)
	s_nop 1
	v_cndmask_b32_e64 v205, v205, v207, s[100:101]
	v_cndmask_b32_e64 v205, v205, v211, s[98:99]
	v_cndmask_b32_e64 v159, v159, v207, s[98:99]
	ds_bpermute_b32 v151, v204, v148
	ds_bpermute_b32 v148, v203, v148
	s_nop 1
	v_mov_b32_dpp v157, v152 row_shr:1 row_mask:0xf bank_mask:0xf
	v_mov_b32_dpp v158, v152 row_shr:2 row_mask:0xf bank_mask:0xf
	v_cmp_lt_i32_e32 vcc, 0, v188
	v_cmp_eq_u32_e64 s[98:99], 0, v188
	v_cmp_eq_u32_e64 s[100:101], 1, v188
	s_waitcnt lgkmcnt(2)
	s_nop 1
	v_cndmask_b32_e64 v158, v158, v154, s[100:101]
	v_cndmask_b32_e64 v158, v158, v153, s[98:99]
	v_cndmask_b32_e64 v157, v157, v154, s[98:99]
	s_waitcnt lgkmcnt(4)
	v_lshlrev_b32_e32 v153, 16, v205
	v_fma_f32 v153, v56, v153, v52
	v_lshlrev_b32_e32 v154, 16, v159
	v_fmac_f32_e32 v153, v48, v154
	v_fmac_f32_e32 v153, v132, v44
	v_and_b32_e32 v132, 0xffff0000, v205
	v_fma_f32 v132, v57, v132, v53
	v_and_b32_e32 v154, 0xffff0000, v159
	v_fmac_f32_e32 v132, v49, v154
	v_fmac_f32_e32 v132, v133, v45
	v_mul_f32_e32 v133, 0x3d372713, v153
	v_mul_f32_e32 v133, v153, v133
	v_fma_f32 v133, v153, v133, v153
	v_mul_f32_e32 v133, 0xc0135761, v133
	v_exp_f32_e32 v133, v133
	v_mul_f32_e32 v154, 0x3d372713, v132
	v_mul_f32_e32 v154, v132, v154
	v_fma_f32 v154, v132, v154, v132
	v_add_f32_e32 v133, 1.0, v133
	v_rcp_f32_e32 v133, v133
	v_mul_f32_e32 v154, 0xc0135761, v154
	v_exp_f32_e32 v154, v154
	v_cmp_lt_i32_e32 vcc, 0, v188
	v_mul_f32_e32 v133, v153, v133
	v_mul_f32_e32 v128, v128, v133
	v_lshlrev_b32_e32 v133, 16, v156
	v_fma_f32 v133, v78, v133, v62
	v_lshlrev_b32_e32 v153, 16, v155
	v_fmac_f32_e32 v133, v70, v153
	v_fmac_f32_e32 v133, v142, v74
	v_mul_f32_e32 v153, 0x3d372713, v133
	v_add_f32_e32 v154, 1.0, v154
	v_mul_f32_e32 v153, v133, v153
	v_rcp_f32_e32 v154, v154
	v_fma_f32 v153, v133, v153, v133
	v_mul_f32_e32 v153, 0xc0135761, v153
	v_exp_f32_e32 v153, v153
	v_and_b32_e32 v142, 0xffff0000, v156
	v_mul_f32_e32 v132, v132, v154
	v_fma_f32 v142, v79, v142, v63
	v_and_b32_e32 v154, 0xffff0000, v155
	v_fmac_f32_e32 v142, v71, v154
	v_fmac_f32_e32 v142, v143, v75
	v_add_f32_e32 v143, 1.0, v153
	v_rcp_f32_e32 v143, v143
	v_mul_f32_e32 v154, v129, v132
	v_lshlrev_b32_e32 v132, 16, v145
	v_fma_f32 v132, v76, v132, v60
	v_mul_f32_e32 v129, v133, v143
	v_lshlrev_b32_e32 v133, 16, v47
	v_fmac_f32_e32 v132, v68, v133
	v_and_b32_e32 v133, 0xffff0000, v145
	v_fma_f32 v133, v77, v133, v61
	v_and_b32_e32 v47, 0xffff0000, v47
	v_fmac_f32_e32 v132, v140, v72
	v_fmac_f32_e32 v133, v69, v47
	v_fmac_f32_e32 v133, v141, v73
	v_mul_f32_e32 v47, 0x3d372713, v132
	v_mul_f32_e32 v47, v132, v47
	v_mul_f32_e32 v140, 0x3d372713, v133
	v_fma_f32 v47, v132, v47, v132
	v_mul_f32_e32 v140, v133, v140
	v_mul_f32_e32 v47, 0xc0135761, v47
	v_fma_f32 v140, v133, v140, v133
	v_exp_f32_e32 v47, v47
	v_mul_f32_e32 v140, 0xc0135761, v140
	v_exp_f32_e32 v140, v140
	v_mul_f32_e32 v153, 0x3d372713, v142
	v_add_f32_e32 v47, 1.0, v47
	v_rcp_f32_e32 v47, v47
	v_add_f32_e32 v140, 1.0, v140
	v_rcp_f32_e32 v140, v140
	v_mul_f32_e32 v153, v142, v153
	v_fma_f32 v153, v142, v153, v142
	v_mul_f32_e32 v47, v132, v47
	v_mul_f32_e32 v153, 0xc0135761, v153
	v_mul_f32_e32 v136, v136, v47
	v_mul_f32_e32 v47, v133, v140
	v_exp_f32_e32 v153, v153
	v_mul_f32_e32 v137, v137, v47
	s_waitcnt lgkmcnt(0)
	v_and_b32_e32 v47, 0xffff0000, v158
	v_and_b32_e32 v145, 0xffff0000, v157
	v_mov_b32_e32 v132, v135
	v_mov_b32_e32 v133, v51
	v_fma_f32 v47, v59, v47, v55
	v_pk_mul_f32 v[132:133], v[132:133], v[144:145]
	v_mul_f32_e32 v138, v138, v129
	v_add_f32_e32 v47, v47, v133
	v_add_f32_e32 v140, v132, v47
	v_add_f32_e32 v129, 1.0, v153
	v_mul_f32_e32 v47, 0x3d372713, v140
	v_rcp_f32_e32 v129, v129
	v_mul_f32_e32 v47, v140, v47
	v_fma_f32 v47, v140, v47, v140
	v_mul_f32_e32 v47, 0xc0135761, v47
	v_exp_f32_e32 v141, v47
	v_lshlrev_b32_e32 v47, 16, v158
	v_mul_f32_e32 v129, v142, v129
	v_fma_f32 v142, v58, v47, v54
	v_lshlrev_b32_e32 v47, 16, v157
	v_mov_b32_e32 v135, v50
	v_pk_mul_f32 v[132:133], v[134:135], v[46:47]
	v_add_f32_e32 v134, 1.0, v141
	v_add_f32_e32 v47, v142, v133
	v_add_f32_e32 v47, v132, v47
	v_mul_f32_e32 v132, 0x3d372713, v47
	v_mul_f32_e32 v132, v47, v132
	v_fma_f32 v132, v47, v132, v47
	v_mul_f32_e32 v132, 0xc0135761, v132
	v_exp_f32_e32 v133, v132
	v_rcp_f32_e32 v134, v134
	v_mul_f32_e32 v139, v139, v129
	v_or_b32_e32 v141, 32, v202
	v_add_f32_e32 v133, 1.0, v133
	v_rcp_f32_e32 v133, v133
	v_mul_f32_e32 v134, v140, v134
	v_mul_f32_e32 v131, v131, v134
	v_cvt_pk_bf16_f32 v134, v136, v137
	v_mul_f32_e32 v47, v47, v133
	v_mul_f32_e32 v47, v130, v47
	v_cvt_pk_bf16_f32 v135, v138, v139
	v_cvt_pk_bf16_f32 v136, v128, v154
	v_cvt_pk_bf16_f32 v137, v47, v131
	v_mov_b64_e32 v[130:131], s[14:15]
	v_mad_i64_i32 v[130:131], s[62:63], v141, s91, v[130:131]
	v_lshl_add_u64 v[130:131], v[180:181], 1, v[130:131]
	global_store_dwordx4 v[130:131], v[134:137], off
	v_cvt_pk_bf16_f32 v128, v124, v125
	ds_bpermute_b32 v129, v204, v152
	ds_bpermute_b32 v132, v203, v152
	s_nop 1
	v_mov_b32_dpp v47, v128 row_shr:1 row_mask:0xf bank_mask:0xf
	v_mov_b32_dpp v128, v128 row_shr:2 row_mask:0xf bank_mask:0xf
	v_cvt_pk_bf16_f32 v131, v126, v127
	v_cvt_pk_bf16_f32 v133, v120, v121
	v_cvt_pk_bf16_f32 v134, v122, v123
	v_cmp_eq_u32_e64 s[98:99], 0, v188
	v_cmp_eq_u32_e64 s[100:101], 1, v188
	s_waitcnt lgkmcnt(2)
; __device__ __forceinline__ unsigned cvt_pk_bf16(float lo, float hi) { unsigned r; asm volatile("v_cvt_pk_bf16_f32 %0, %1, %2" : "=v"(r) : "v"(lo), "v"(hi)); return r; }
;     __device__ __forceinline__ void operator()(const f32x4 (&acc)[2][2][4][2], const Unit& u, int wr, int wc, int fr, int fq) const {
;     ...
;                 pk[0] = cvt_pk_bf16(acc[ai][0][m][0][0], acc[ai][0][m][0][1]); pk[1] = cvt_pk_bf16(acc[ai][0][m][0][2], acc[ai][0][m][0][3]);
;                 pk[2] = cvt_pk_bf16(acc[ai][0][m][1][0], acc[ai][0][m][1][1]); pk[3] = cvt_pk_bf16(acc[ai][0][m][1][2], acc[ai][0][m][1][3]);
;                 float hv[8];
; #pragma unroll
;                 for (int q = 0; q < 4; ++q) {
;                     unsigned g1 = (unsigned)__shfl_up((int)pk[q], 1, 16), g2 = (unsigned)__shfl_up((int)pk[q], 2, 16);
;                     if (fr == 0) { g1 = l15[q]; g2 = l14[q]; } else if (fr == 1) { g2 = l15[q]; }
;                     const unsigned n14 = (unsigned)__shfl((int)pk[q], 14, 16), n15 = (unsigned)__shfl((int)pk[q], 15, 16);
;                     l14[q] = n14; l15[q] = n15;
;                     const int n = q >> 1, j = (q & 1) * 2, e = 2 * q;
;                     const float x0 = bb[e] + w0[e] * __uint_as_float(g2 << 16) + w1[e] * __uint_as_float(g1 << 16) + w2[e] * acc[ai][0][m][n][j];
;                     const float x1 = bb[e + 1] + w0[e + 1] * __uint_as_float(g2 & 0xffff0000u) + w1[e + 1] * __uint_as_float(g1 & 0xffff0000u) + w2[e + 1] * acc[ai][0][m][n][j + 1];
;                     hv[e] = gelu_tanh_f(x0) * acc[ai][1][m][n][j]; hv[e + 1] = gelu_tanh_f(x1) * acc[ai][1][m][n][j + 1];
;                 }
;                 const bool first2 = (slab == 0 && m == 0 && fr < 2);
;                 if (!first2) { u32x4 w; w.x = cvt_pk_bf16(hv[0], hv[1]); w.y = cvt_pk_bf16(hv[2], hv[3]); w.z = cvt_pk_bf16(hv[4], hv[5]); w.w = cvt_pk_bf16(hv[6], hv[7]);
;                     *(u32x4*)(H + (size_t)row * ldh + f0) = w; }
;                 else { float* p = hp + (size_t)fr * ff; *(f32x4*)p = acc[0][0][0][0]; *(f32x4*)(p + 4) = acc[0][0][0][1];
;                     float* pu = hp + (size_t)(4 + fr) * ff; *(f32x4*)pu = acc[0][1][0][0]; *(f32x4*)(pu + 4) = acc[0][1][0][1]; }
;                 if (slab == 3 && m == 3 && fr >= 14) { float* p = hp + (size_t)(2 + fr - 14) * ff; *(f32x4*)p = acc[1][0][3][0]; *(f32x4*)(p + 4) = acc[1][0][3][1]; }
	s_nop 1
	v_cndmask_b32_e64 v128, v128, v146, s[100:101]
	v_cndmask_b32_e64 v128, v128, v149, s[98:99]
	v_cndmask_b32_e64 v47, v47, v146, s[98:99]
	s_nop 1
	v_mov_b32_dpp v130, v131 row_shr:1 row_mask:0xf bank_mask:0xf
	v_mov_b32_dpp v131, v131 row_shr:2 row_mask:0xf bank_mask:0xf
	v_cmp_lt_i32_e32 vcc, 0, v188
	v_cmp_eq_u32_e64 s[98:99], 0, v188
	v_cmp_eq_u32_e64 s[100:101], 1, v188
	s_waitcnt lgkmcnt(2)
	s_nop 1
	v_cndmask_b32_e64 v131, v131, v147, s[100:101]
	v_cndmask_b32_e64 v131, v131, v150, s[98:99]
	v_cndmask_b32_e64 v130, v130, v147, s[98:99]
	s_nop 1
	v_mov_b32_dpp v135, v133 row_shr:1 row_mask:0xf bank_mask:0xf
	v_mov_b32_dpp v136, v133 row_shr:2 row_mask:0xf bank_mask:0xf
	v_cmp_lt_i32_e32 vcc, 0, v188
	v_cmp_eq_u32_e64 s[98:99], 0, v188
	v_cmp_eq_u32_e64 s[100:101], 1, v188
	s_waitcnt lgkmcnt(2)
	s_nop 1
	v_cndmask_b32_e64 v136, v136, v148, s[100:101]
	v_cndmask_b32_e64 v136, v136, v151, s[98:99]
	v_cndmask_b32_e64 v135, v135, v148, s[98:99]
	s_nop 1
	v_mov_b32_dpp v133, v134 row_shr:1 row_mask:0xf bank_mask:0xf
	v_mov_b32_dpp v134, v134 row_shr:2 row_mask:0xf bank_mask:0xf
	v_cmp_lt_i32_e32 vcc, 0, v188
	v_cmp_eq_u32_e64 s[98:99], 0, v188
	v_cmp_eq_u32_e64 s[100:101], 1, v188
	s_waitcnt lgkmcnt(2)
	s_nop 1
	v_cndmask_b32_e64 v134, v134, v132, s[100:101]
	v_cndmask_b32_e64 v134, v134, v129, s[98:99]
	v_cndmask_b32_e64 v133, v133, v132, s[98:99]
	s_waitcnt lgkmcnt(2)
	v_lshlrev_b32_e32 v129, 16, v136
	v_fma_f32 v129, v56, v129, v52
	v_lshlrev_b32_e32 v132, 16, v135
	v_fmac_f32_e32 v129, v48, v132
	v_fmac_f32_e32 v129, v120, v44
	v_and_b32_e32 v120, 0xffff0000, v136
	v_fma_f32 v120, v57, v120, v53
	v_and_b32_e32 v132, 0xffff0000, v135
	v_fmac_f32_e32 v120, v49, v132
	v_fmac_f32_e32 v120, v121, v45
	v_mul_f32_e32 v121, 0x3d372713, v129
	v_mul_f32_e32 v121, v129, v121
	v_mul_f32_e32 v132, 0x3d372713, v120
	v_fma_f32 v121, v129, v121, v129
	v_mul_f32_e32 v132, v120, v132
	v_mul_f32_e32 v121, 0xc0135761, v121
	v_fma_f32 v132, v120, v132, v120
	v_exp_f32_e32 v121, v121
	v_mul_f32_e32 v132, 0xc0135761, v132
	v_exp_f32_e32 v132, v132
	s_waitcnt lgkmcnt(1)
	v_and_b32_e32 v145, 0xffff0000, v133
	v_add_f32_e32 v121, 1.0, v121
	v_rcp_f32_e32 v121, v121
	v_add_f32_e32 v132, 1.0, v132
	v_rcp_f32_e32 v132, v132
	v_mul_f32_e32 v121, v129, v121
	v_mul_f32_e32 v121, v112, v121
	v_mul_f32_e32 v112, v120, v132
	v_lshlrev_b32_e32 v120, 16, v131
	v_fma_f32 v120, v78, v120, v62
	v_lshlrev_b32_e32 v129, 16, v130
	v_fmac_f32_e32 v120, v70, v129
	v_fmac_f32_e32 v120, v126, v74
	v_mul_f32_e32 v129, 0x3d372713, v120
	v_mul_f32_e32 v129, v120, v129
	v_fma_f32 v129, v120, v129, v120
	v_mul_f32_e32 v129, 0xc0135761, v129
	v_exp_f32_e32 v129, v129
	v_and_b32_e32 v126, 0xffff0000, v131
	v_fma_f32 v126, v79, v126, v63
	v_and_b32_e32 v130, 0xffff0000, v130
	v_fmac_f32_e32 v126, v71, v130
	v_fmac_f32_e32 v126, v127, v75
	v_add_f32_e32 v127, 1.0, v129
	v_rcp_f32_e32 v127, v127
	v_mul_f32_e32 v130, v113, v112
	v_lshlrev_b32_e32 v113, 16, v128
	v_fma_f32 v113, v76, v113, v60
	v_mul_f32_e32 v112, v120, v127
	v_lshlrev_b32_e32 v120, 16, v47
	v_fmac_f32_e32 v113, v68, v120
	v_and_b32_e32 v120, 0xffff0000, v128
	v_fmac_f32_e32 v113, v124, v72
	v_fma_f32 v120, v77, v120, v61
	v_and_b32_e32 v47, 0xffff0000, v47
	v_mul_f32_e32 v129, 0x3d372713, v126
	v_fmac_f32_e32 v120, v69, v47
	v_mul_f32_e32 v47, 0x3d372713, v113
	v_mul_f32_e32 v129, v126, v129
	v_mul_f32_e32 v47, v113, v47
	v_fma_f32 v129, v126, v129, v126
	v_fma_f32 v47, v113, v47, v113
	v_mul_f32_e32 v129, 0xc0135761, v129
	v_fmac_f32_e32 v120, v125, v73
	v_mul_f32_e32 v47, 0xc0135761, v47
	v_exp_f32_e32 v129, v129
	v_exp_f32_e32 v47, v47
	v_mul_f32_e32 v124, 0x3d372713, v120
	v_mul_f32_e32 v124, v120, v124
	v_fma_f32 v124, v120, v124, v120
	v_mul_f32_e32 v124, 0xc0135761, v124
	v_mul_f32_e32 v118, v118, v112
	v_add_f32_e32 v112, 1.0, v129
	v_exp_f32_e32 v124, v124
	v_add_f32_e32 v47, 1.0, v47
	v_rcp_f32_e32 v112, v112
	v_rcp_f32_e32 v47, v47
	v_add_f32_e32 v124, 1.0, v124
	v_rcp_f32_e32 v124, v124
	v_mul_f32_e32 v112, v126, v112
	v_mul_f32_e32 v47, v113, v47
	v_mul_f32_e32 v119, v119, v112
	v_mul_f32_e32 v116, v116, v47
	s_waitcnt lgkmcnt(0)
	v_and_b32_e32 v47, 0xffff0000, v134
	v_mov_b32_e32 v112, v123
	v_mov_b32_e32 v113, v51
	v_fma_f32 v47, v59, v47, v55
	v_pk_mul_f32 v[112:113], v[112:113], v[144:145]
	v_mul_f32_e32 v120, v120, v124
	v_add_f32_e32 v47, v47, v113
	v_add_f32_e32 v124, v112, v47
	v_mul_f32_e32 v47, 0x3d372713, v124
	v_mul_f32_e32 v47, v124, v47
	v_fma_f32 v47, v124, v47, v124
	v_mul_f32_e32 v47, 0xc0135761, v47
	v_exp_f32_e32 v125, v47
	v_lshlrev_b32_e32 v47, 16, v134
	v_fma_f32 v126, v58, v47, v54
	v_lshlrev_b32_e32 v47, 16, v133
	v_mov_b32_e32 v123, v50
	v_pk_mul_f32 v[112:113], v[122:123], v[46:47]
	s_nop 0
	v_add_f32_e32 v47, v126, v113
	v_add_f32_e32 v47, v112, v47
	v_mul_f32_e32 v112, 0x3d372713, v47
	v_mul_f32_e32 v112, v47, v112
	v_fma_f32 v112, v47, v112, v47
	v_mul_f32_e32 v112, 0xc0135761, v112
	v_exp_f32_e32 v112, v112
	v_mul_f32_e32 v113, v117, v120
	v_add_f32_e32 v117, 1.0, v125
	v_rcp_f32_e32 v117, v117
	v_add_f32_e32 v112, 1.0, v112
	v_rcp_f32_e32 v112, v112
	v_or_b32_e32 v120, 48, v202
	v_mul_f32_e32 v117, v124, v117
	v_mul_f32_e32 v115, v115, v117
	v_mul_f32_e32 v47, v47, v112
	v_cvt_pk_bf16_f32 v112, v116, v113
	v_mov_b64_e32 v[116:117], s[14:15]
	v_mad_i64_i32 v[116:117], s[62:63], v120, s91, v[116:117]
	v_cvt_pk_bf16_f32 v113, v118, v119
	v_lshl_add_u64 v[116:117], v[180:181], 1, v[116:117]
	v_mul_f32_e32 v47, v114, v47
	v_cvt_pk_bf16_f32 v114, v121, v130
	v_cvt_pk_bf16_f32 v115, v47, v115
	global_store_dwordx4 v[116:117], v[112:115], off
	s_nop 1
	v_lshl_add_u64 v[112:113], v[186:187], 0, v[170:171]
	s_and_saveexec_b64 s[62:63], s[42:43]
	s_cbranch_execz .LBB0_2509
	global_store_dwordx4 v[112:113], v[12:15], off
	global_store_dwordx4 v[112:113], v[4:7], off offset:16

; __device__ __forceinline__ unsigned cvt_pk_bf16(float lo, float hi) { unsigned r; asm volatile("v_cvt_pk_bf16_f32 %0, %1, %2" : "=v"(r) : "v"(lo), "v"(hi)); return r; }
; __device__ __forceinline__ float gelu_tanh_f(float x) { const float y = -2.3022081983651455f * (x + 0.044715f * x * x * x); return x * __builtin_amdgcn_rcpf(1.f + __builtin_amdgcn_exp2f(y)); }
;     __device__ __forceinline__ void operator()(const f32x4 (&acc)[2][2][4][2], const Unit& u, int wr, int wc, int fr, int fq) const {
;     ...
;                 pk[0] = cvt_pk_bf16(acc[ai][0][m][0][0], acc[ai][0][m][0][1]); pk[1] = cvt_pk_bf16(acc[ai][0][m][0][2], acc[ai][0][m][0][3]);
;                 pk[2] = cvt_pk_bf16(acc[ai][0][m][1][0], acc[ai][0][m][1][1]); pk[3] = cvt_pk_bf16(acc[ai][0][m][1][2], acc[ai][0][m][1][3]);
;                 float hv[8];
; #pragma unroll
;                 for (int q = 0; q < 4; ++q) {
;                     unsigned g1 = (unsigned)__shfl_up((int)pk[q], 1, 16), g2 = (unsigned)__shfl_up((int)pk[q], 2, 16);
;                     if (fr == 0) { g1 = l15[q]; g2 = l14[q]; } else if (fr == 1) { g2 = l15[q]; }
;                     const unsigned n14 = (unsigned)__shfl((int)pk[q], 14, 16), n15 = (unsigned)__shfl((int)pk[q], 15, 16);
;                     l14[q] = n14; l15[q] = n15;
;                     const int n = q >> 1, j = (q & 1) * 2, e = 2 * q;
;                     const float x0 = bb[e] + w0[e] * __uint_as_float(g2 << 16) + w1[e] * __uint_as_float(g1 << 16) + w2[e] * acc[ai][0][m][n][j];
;                     const float x1 = bb[e + 1] + w0[e + 1] * __uint_as_float(g2 & 0xffff0000u) + w1[e + 1] * __uint_as_float(g1 & 0xffff0000u) + w2[e + 1] * acc[ai][0][m][n][j + 1];
;                     hv[e] = gelu_tanh_f(x0) * acc[ai][1][m][n][j]; hv[e + 1] = gelu_tanh_f(x1) * acc[ai][1][m][n][j + 1];
;                 }
;                 const bool first2 = (slab == 0 && m == 0 && fr < 2);
;                 if (!first2) { u32x4 w; w.x = cvt_pk_bf16(hv[0], hv[1]); w.y = cvt_pk_bf16(hv[2], hv[3]); w.z = cvt_pk_bf16(hv[4], hv[5]); w.w = cvt_pk_bf16(hv[6], hv[7]);
;                     *(u32x4*)(H + (size_t)row * ldh + f0) = w; }
.LBB0_2511:
	v_cvt_pk_bf16_f32 v123, v108, v109
	s_nop 1
	v_mov_b32_dpp v47, v123 row_shr:1 row_mask:0xf bank_mask:0xf
	v_mov_b32_dpp v122, v123 row_shr:2 row_mask:0xf bank_mask:0xf
	v_cmp_lt_i32_e32 vcc, 0, v188
	v_cvt_pk_bf16_f32 v127, v110, v111
	v_cvt_pk_bf16_f32 v126, v96, v97
	v_cvt_pk_bf16_f32 v124, v98, v99
	v_cmp_eq_u32_e64 s[98:99], 0, v188
	v_cmp_eq_u32_e64 s[100:101], 1, v188
	s_waitcnt lgkmcnt(2)
	s_nop 1
	v_cndmask_b32_e64 v122, v122, v118, s[100:101]
	v_cndmask_b32_e64 v122, v122, v114, s[98:99]
	v_cndmask_b32_e64 v47, v47, v118, s[98:99]
	ds_bpermute_b32 v118, v204, v123
	ds_bpermute_b32 v114, v203, v123
	s_nop 1
	v_mov_b32_dpp v123, v127 row_shr:1 row_mask:0xf bank_mask:0xf
	v_mov_b32_dpp v125, v127 row_shr:2 row_mask:0xf bank_mask:0xf
	v_cmp_lt_i32_e32 vcc, 0, v188
	v_cmp_eq_u32_e64 s[98:99], 0, v188
	v_cmp_eq_u32_e64 s[100:101], 1, v188
	s_waitcnt lgkmcnt(2)
	s_nop 1
	v_cndmask_b32_e64 v125, v125, v119, s[100:101]
	v_cndmask_b32_e64 v125, v125, v115, s[98:99]
	v_cndmask_b32_e64 v123, v123, v119, s[98:99]
	ds_bpermute_b32 v119, v204, v127
	ds_bpermute_b32 v115, v203, v127
	s_nop 1
	v_mov_b32_dpp v128, v126 row_shr:1 row_mask:0xf bank_mask:0xf
	v_mov_b32_dpp v129, v126 row_shr:2 row_mask:0xf bank_mask:0xf
	v_cmp_lt_i32_e32 vcc, 0, v188
	v_cmp_eq_u32_e64 s[98:99], 0, v188
	v_cmp_eq_u32_e64 s[100:101], 1, v188
	s_waitcnt lgkmcnt(2)
	s_nop 1
	v_cndmask_b32_e64 v129, v129, v120, s[100:101]
	v_cndmask_b32_e64 v129, v129, v116, s[98:99]
	v_cndmask_b32_e64 v128, v128, v120, s[98:99]
	ds_bpermute_b32 v120, v204, v126
	ds_bpermute_b32 v116, v203, v126
	s_nop 1
	v_mov_b32_dpp v126, v124 row_shr:1 row_mask:0xf bank_mask:0xf
	v_mov_b32_dpp v127, v124 row_shr:2 row_mask:0xf bank_mask:0xf
	v_cmp_lt_i32_e32 vcc, 0, v188
	v_cmp_eq_u32_e64 s[98:99], 0, v188
	v_cmp_eq_u32_e64 s[100:101], 1, v188
	s_waitcnt lgkmcnt(2)
	s_nop 1
	v_cndmask_b32_e64 v127, v127, v121, s[100:101]
	v_cndmask_b32_e64 v127, v127, v117, s[98:99]
	v_cndmask_b32_e64 v126, v126, v121, s[98:99]
	ds_bpermute_b32 v121, v204, v124
	ds_bpermute_b32 v117, v203, v124
	s_and_saveexec_b64 s[62:63], s[46:47]
	s_xor_b64 s[62:63], exec, s[62:63]
	s_cbranch_execz .LBB0_2537
	s_waitcnt lgkmcnt(6)
	v_lshlrev_b32_e32 v124, 16, v129
	v_fma_f32 v124, v56, v124, v52
	v_lshlrev_b32_e32 v130, 16, v128
	v_fmac_f32_e32 v124, v48, v130
	v_fmac_f32_e32 v124, v96, v44
	v_and_b32_e32 v96, 0xffff0000, v129
	v_fma_f32 v96, v57, v96, v53
	v_and_b32_e32 v128, 0xffff0000, v128
	v_fmac_f32_e32 v96, v49, v128
	v_fmac_f32_e32 v96, v97, v45
	v_mul_f32_e32 v97, 0x3d372713, v124
	v_mul_f32_e32 v97, v124, v97
	v_mul_f32_e32 v128, 0x3d372713, v96
	v_fma_f32 v97, v124, v97, v124
	v_mul_f32_e32 v128, v96, v128
	v_mul_f32_e32 v97, 0xc0135761, v97
	v_fma_f32 v128, v96, v128, v96
	v_exp_f32_e32 v97, v97
	v_mul_f32_e32 v128, 0xc0135761, v128
	v_exp_f32_e32 v128, v128
	s_waitcnt lgkmcnt(3)
	v_and_b32_e32 v145, 0xffff0000, v126
	v_add_f32_e32 v97, 1.0, v97
	v_rcp_f32_e32 v97, v97
	v_add_f32_e32 v128, 1.0, v128
	v_rcp_f32_e32 v128, v128
	v_mul_f32_e32 v97, v124, v97
	v_mul_f32_e32 v97, v80, v97
	v_mul_f32_e32 v80, v96, v128
	v_lshlrev_b32_e32 v96, 16, v125
	v_fma_f32 v96, v78, v96, v62
	v_lshlrev_b32_e32 v124, 16, v123
	v_fmac_f32_e32 v96, v70, v124
	v_fmac_f32_e32 v96, v110, v74
	v_mul_f32_e32 v124, 0x3d372713, v96
	v_mul_f32_e32 v124, v96, v124
	v_fma_f32 v124, v96, v124, v96
	v_mul_f32_e32 v124, 0xc0135761, v124
	v_exp_f32_e32 v124, v124
	v_and_b32_e32 v110, 0xffff0000, v125
	v_fma_f32 v110, v79, v110, v63
	v_and_b32_e32 v123, 0xffff0000, v123
	v_fmac_f32_e32 v110, v71, v123
	v_fmac_f32_e32 v110, v111, v75
	v_add_f32_e32 v111, 1.0, v124
	v_rcp_f32_e32 v111, v111
	v_mul_f32_e32 v124, v81, v80
	v_lshlrev_b32_e32 v81, 16, v122
	v_fma_f32 v81, v76, v81, v60
	v_mul_f32_e32 v80, v96, v111
	v_lshlrev_b32_e32 v96, 16, v47
	v_fmac_f32_e32 v81, v68, v96
	v_and_b32_e32 v96, 0xffff0000, v122
	v_fmac_f32_e32 v81, v108, v72
	v_fma_f32 v96, v77, v96, v61
	v_and_b32_e32 v47, 0xffff0000, v47
	v_mul_f32_e32 v123, 0x3d372713, v110
	v_fmac_f32_e32 v96, v69, v47
	v_mul_f32_e32 v47, 0x3d372713, v81
	v_mul_f32_e32 v123, v110, v123
	v_mul_f32_e32 v47, v81, v47
	v_fma_f32 v123, v110, v123, v110
	v_fma_f32 v47, v81, v47, v81
	v_mul_f32_e32 v123, 0xc0135761, v123
	v_fmac_f32_e32 v96, v109, v73
	v_mul_f32_e32 v47, 0xc0135761, v47
	v_exp_f32_e32 v123, v123
	v_exp_f32_e32 v47, v47
	v_mul_f32_e32 v108, 0x3d372713, v96
	v_mul_f32_e32 v108, v96, v108
	v_fma_f32 v108, v96, v108, v96
	v_mul_f32_e32 v108, 0xc0135761, v108
	v_mul_f32_e32 v86, v86, v80
	v_add_f32_e32 v80, 1.0, v123
	v_exp_f32_e32 v108, v108
	v_add_f32_e32 v47, 1.0, v47
	v_rcp_f32_e32 v80, v80
	v_rcp_f32_e32 v47, v47
	v_add_f32_e32 v108, 1.0, v108
	v_rcp_f32_e32 v108, v108
	v_mul_f32_e32 v80, v110, v80
	v_mul_f32_e32 v47, v81, v47
	v_mul_f32_e32 v87, v87, v80
	v_mul_f32_e32 v84, v84, v47
	s_waitcnt lgkmcnt(2)
	v_and_b32_e32 v47, 0xffff0000, v127
	v_mov_b32_e32 v80, v99
	v_mov_b32_e32 v81, v51
	v_fma_f32 v47, v59, v47, v55
	v_pk_mul_f32 v[80:81], v[80:81], v[144:145]
	v_mul_f32_e32 v96, v96, v108
	v_add_f32_e32 v47, v47, v81
	v_add_f32_e32 v108, v80, v47
	v_mul_f32_e32 v47, 0x3d372713, v108
	v_mul_f32_e32 v47, v108, v47
	v_fma_f32 v47, v108, v47, v108
	v_mul_f32_e32 v47, 0xc0135761, v47
	v_exp_f32_e32 v109, v47
	v_lshlrev_b32_e32 v47, 16, v127
	v_fma_f32 v110, v58, v47, v54
	v_lshlrev_b32_e32 v47, 16, v126
	v_mov_b32_e32 v99, v50
	v_pk_mul_f32 v[80:81], v[98:99], v[46:47]
	s_nop 0
	v_add_f32_e32 v47, v110, v81
	v_add_f32_e32 v47, v80, v47
	v_mul_f32_e32 v80, 0x3d372713, v47
	v_mul_f32_e32 v80, v47, v80
	v_fma_f32 v80, v47, v80, v47
	v_mul_f32_e32 v80, 0xc0135761, v80
	v_exp_f32_e32 v80, v80
	v_mul_f32_e32 v81, v85, v96
	v_add_f32_e32 v85, 1.0, v109
	v_rcp_f32_e32 v85, v85
	v_add_f32_e32 v80, 1.0, v80
	v_rcp_f32_e32 v80, v80
	v_add_u32_e32 v96, 0x80, v202
	v_mul_f32_e32 v85, v108, v85
	v_mul_f32_e32 v83, v83, v85
	v_mul_f32_e32 v47, v47, v80
	v_cvt_pk_bf16_f32 v80, v84, v81
	v_mov_b64_e32 v[84:85], s[14:15]
	v_mad_i64_i32 v[84:85], s[64:65], v96, s91, v[84:85]
	v_lshl_add_u64 v[84:85], v[180:181], 1, v[84:85]
	v_mul_f32_e32 v47, v82, v47
	v_cvt_pk_bf16_f32 v81, v86, v87
	v_cvt_pk_bf16_f32 v82, v97, v124
	v_cvt_pk_bf16_f32 v83, v47, v83
	global_store_dwordx4 v[84:85], v[80:83], off

; __device__ __forceinline__ unsigned cvt_pk_bf16(float lo, float hi) { unsigned r; asm volatile("v_cvt_pk_bf16_f32 %0, %1, %2" : "=v"(r) : "v"(lo), "v"(hi)); return r; }
; __device__ __forceinline__ float gelu_tanh_f(float x) { const float y = -2.3022081983651455f * (x + 0.044715f * x * x * x); return x * __builtin_amdgcn_rcpf(1.f + __builtin_amdgcn_exp2f(y)); }
;     __device__ __forceinline__ void operator()(const f32x4 (&acc)[2][2][4][2], const Unit& u, int wr, int wc, int fr, int fq) const {
;     ...
;                 pk[0] = cvt_pk_bf16(acc[ai][0][m][0][0], acc[ai][0][m][0][1]); pk[1] = cvt_pk_bf16(acc[ai][0][m][0][2], acc[ai][0][m][0][3]);
;                 pk[2] = cvt_pk_bf16(acc[ai][0][m][1][0], acc[ai][0][m][1][1]); pk[3] = cvt_pk_bf16(acc[ai][0][m][1][2], acc[ai][0][m][1][3]);
;                 float hv[8];
; #pragma unroll
;                 for (int q = 0; q < 4; ++q) {
;                     unsigned g1 = (unsigned)__shfl_up((int)pk[q], 1, 16), g2 = (unsigned)__shfl_up((int)pk[q], 2, 16);
;                     if (fr == 0) { g1 = l15[q]; g2 = l14[q]; } else if (fr == 1) { g2 = l15[q]; }
;                     const unsigned n14 = (unsigned)__shfl((int)pk[q], 14, 16), n15 = (unsigned)__shfl((int)pk[q], 15, 16);
;                     l14[q] = n14; l15[q] = n15;
;                     const int n = q >> 1, j = (q & 1) * 2, e = 2 * q;
;                     const float x0 = bb[e] + w0[e] * __uint_as_float(g2 << 16) + w1[e] * __uint_as_float(g1 << 16) + w2[e] * acc[ai][0][m][n][j];
;                     const float x1 = bb[e + 1] + w0[e + 1] * __uint_as_float(g2 & 0xffff0000u) + w1[e + 1] * __uint_as_float(g1 & 0xffff0000u) + w2[e + 1] * acc[ai][0][m][n][j + 1];
;                     hv[e] = gelu_tanh_f(x0) * acc[ai][1][m][n][j]; hv[e + 1] = gelu_tanh_f(x1) * acc[ai][1][m][n][j + 1];
;                 }
;                 const bool first2 = (slab == 0 && m == 0 && fr < 2);
;                 if (!first2) { u32x4 w; w.x = cvt_pk_bf16(hv[0], hv[1]); w.y = cvt_pk_bf16(hv[2], hv[3]); w.z = cvt_pk_bf16(hv[4], hv[5]); w.w = cvt_pk_bf16(hv[6], hv[7]);
;                     *(u32x4*)(H + (size_t)row * ldh + f0) = w; }
.LBB0_2539:
	s_or_b64 exec, exec, s[62:63]
	v_cvt_pk_bf16_f32 v80, v64, v65
	s_waitcnt lgkmcnt(14)
	s_nop 1
	v_mov_b32_dpp v47, v80 row_shr:1 row_mask:0xf bank_mask:0xf
	v_mov_b32_dpp v87, v80 row_shr:2 row_mask:0xf bank_mask:0xf
	v_cmp_lt_i32_e32 vcc, 0, v188
	v_cvt_pk_bf16_f32 v81, v66, v67
	v_cvt_pk_bf16_f32 v82, v36, v37
	v_cvt_pk_bf16_f32 v86, v38, v39
	v_cmp_eq_u32_e64 s[98:99], 0, v188
	v_cmp_eq_u32_e64 s[100:101], 1, v188
	s_waitcnt lgkmcnt(2)
	s_nop 1
	v_cndmask_b32_e64 v87, v87, v114, s[100:101]
	v_cndmask_b32_e64 v87, v87, v118, s[98:99]
	v_cndmask_b32_e64 v47, v47, v114, s[98:99]
	ds_bpermute_b32 v83, v204, v80
	ds_bpermute_b32 v80, v203, v80
	s_nop 1
	v_mov_b32_dpp v88, v81 row_shr:1 row_mask:0xf bank_mask:0xf
	v_mov_b32_dpp v89, v81 row_shr:2 row_mask:0xf bank_mask:0xf
	v_cmp_lt_i32_e32 vcc, 0, v188
	v_cmp_eq_u32_e64 s[98:99], 0, v188
	v_cmp_eq_u32_e64 s[100:101], 1, v188
	s_waitcnt lgkmcnt(2)
	s_nop 1
	v_cndmask_b32_e64 v89, v89, v115, s[100:101]
	v_cndmask_b32_e64 v89, v89, v119, s[98:99]
	v_cndmask_b32_e64 v88, v88, v115, s[98:99]
	ds_bpermute_b32 v84, v204, v81
	ds_bpermute_b32 v81, v203, v81
	s_nop 1
	v_mov_b32_dpp v92, v82 row_shr:1 row_mask:0xf bank_mask:0xf
	v_mov_b32_dpp v93, v82 row_shr:2 row_mask:0xf bank_mask:0xf
	v_cmp_lt_i32_e32 vcc, 0, v188
	v_cmp_eq_u32_e64 s[98:99], 0, v188
	v_cmp_eq_u32_e64 s[100:101], 1, v188
	s_waitcnt lgkmcnt(2)
	s_nop 1
	v_cndmask_b32_e64 v93, v93, v116, s[100:101]
	v_cndmask_b32_e64 v93, v93, v120, s[98:99]
	v_cndmask_b32_e64 v92, v92, v116, s[98:99]
	ds_bpermute_b32 v85, v204, v82
	ds_bpermute_b32 v82, v203, v82
	s_nop 1
	v_mov_b32_dpp v90, v86 row_shr:1 row_mask:0xf bank_mask:0xf
	v_mov_b32_dpp v91, v86 row_shr:2 row_mask:0xf bank_mask:0xf
	v_cmp_lt_i32_e32 vcc, 0, v188
	v_cmp_eq_u32_e64 s[98:99], 0, v188
	v_cmp_eq_u32_e64 s[100:101], 1, v188
	s_waitcnt lgkmcnt(2)
	s_nop 1
	v_cndmask_b32_e64 v91, v91, v117, s[100:101]
	v_cndmask_b32_e64 v91, v91, v121, s[98:99]
	v_cndmask_b32_e64 v90, v90, v117, s[98:99]
	s_waitcnt lgkmcnt(4)
	v_lshlrev_b32_e32 v94, 16, v93
	v_fma_f32 v94, v56, v94, v52
	v_lshlrev_b32_e32 v95, 16, v92
	v_fmac_f32_e32 v94, v48, v95
	v_fmac_f32_e32 v94, v36, v44
	v_and_b32_e32 v36, 0xffff0000, v93
	v_fma_f32 v36, v57, v36, v53
	v_and_b32_e32 v92, 0xffff0000, v92
	v_fmac_f32_e32 v36, v49, v92
	v_fmac_f32_e32 v36, v37, v45
	v_mul_f32_e32 v37, 0x3d372713, v94
	v_mul_f32_e32 v37, v94, v37
	v_mul_f32_e32 v92, 0x3d372713, v36
	v_fma_f32 v37, v94, v37, v94
	v_mul_f32_e32 v92, v36, v92
	v_mul_f32_e32 v37, 0xc0135761, v37
	v_fma_f32 v92, v36, v92, v36
	v_exp_f32_e32 v37, v37
	v_mul_f32_e32 v92, 0xc0135761, v92
	v_exp_f32_e32 v92, v92
	s_waitcnt lgkmcnt(1)
	v_and_b32_e32 v145, 0xffff0000, v90
	v_add_f32_e32 v37, 1.0, v37
	v_rcp_f32_e32 v37, v37
	v_add_f32_e32 v92, 1.0, v92
	v_rcp_f32_e32 v92, v92
	v_cmp_lt_i32_e32 vcc, 0, v188
	v_mul_f32_e32 v37, v94, v37
	v_mul_f32_e32 v37, v32, v37
	v_mul_f32_e32 v32, v36, v92
	v_lshlrev_b32_e32 v36, 16, v89
	v_fma_f32 v36, v78, v36, v62
	v_lshlrev_b32_e32 v92, 16, v88
	v_fmac_f32_e32 v36, v70, v92
	v_fmac_f32_e32 v36, v66, v74
	v_and_b32_e32 v66, 0xffff0000, v89
	v_mul_f32_e32 v89, 0x3d372713, v36
	v_mul_f32_e32 v89, v36, v89
	v_fma_f32 v89, v36, v89, v36
	v_mul_f32_e32 v89, 0xc0135761, v89
	v_exp_f32_e32 v89, v89
	v_fma_f32 v66, v79, v66, v63
	v_and_b32_e32 v88, 0xffff0000, v88
	v_fmac_f32_e32 v66, v71, v88
	v_fmac_f32_e32 v66, v67, v75
	v_add_f32_e32 v67, 1.0, v89
	v_rcp_f32_e32 v67, v67
	v_mul_f32_e32 v89, v33, v32
	v_lshlrev_b32_e32 v33, 16, v87
	v_fma_f32 v33, v76, v33, v60
	v_mul_f32_e32 v32, v36, v67
	v_mul_f32_e32 v36, v42, v32
	v_lshlrev_b32_e32 v42, 16, v47
	v_fmac_f32_e32 v33, v68, v42
	v_and_b32_e32 v42, 0xffff0000, v87
	v_fma_f32 v42, v77, v42, v61
	v_and_b32_e32 v47, 0xffff0000, v47
	v_mul_f32_e32 v88, 0x3d372713, v66
	v_fmac_f32_e32 v33, v64, v72
	v_fmac_f32_e32 v42, v69, v47
	v_mul_f32_e32 v88, v66, v88
	v_fmac_f32_e32 v42, v65, v73
	v_mul_f32_e32 v47, 0x3d372713, v33
	v_fma_f32 v88, v66, v88, v66
	v_mul_f32_e32 v47, v33, v47
	v_mul_f32_e32 v64, 0x3d372713, v42
	v_mul_f32_e32 v88, 0xc0135761, v88
	v_fma_f32 v47, v33, v47, v33
	v_mul_f32_e32 v64, v42, v64
	v_exp_f32_e32 v88, v88
	v_mul_f32_e32 v47, 0xc0135761, v47
	v_fma_f32 v64, v42, v64, v42
	v_exp_f32_e32 v47, v47
	v_mul_f32_e32 v64, 0xc0135761, v64
	v_exp_f32_e32 v64, v64
	v_add_f32_e32 v32, 1.0, v88
	v_rcp_f32_e32 v32, v32
	v_add_f32_e32 v47, 1.0, v47
	v_rcp_f32_e32 v47, v47
	v_add_f32_e32 v64, 1.0, v64
	v_rcp_f32_e32 v64, v64
	v_mul_f32_e32 v32, v66, v32
	v_mul_f32_e32 v43, v43, v32
	v_mul_f32_e32 v32, v33, v47
	v_mul_f32_e32 v40, v40, v32
	v_mul_f32_e32 v32, v42, v64
	v_mul_f32_e32 v64, v41, v32
	s_waitcnt lgkmcnt(0)
	v_and_b32_e32 v32, 0xffff0000, v91
	v_fma_f32 v42, v59, v32, v55
	v_mov_b32_e32 v32, v39
	v_mov_b32_e32 v33, v51
	v_pk_mul_f32 v[32:33], v[32:33], v[144:145]
	v_lshlrev_b32_e32 v47, 16, v90
	v_add_f32_e32 v33, v42, v33
	v_add_f32_e32 v65, v32, v33
	v_mul_f32_e32 v32, 0x3d372713, v65
	v_mul_f32_e32 v32, v65, v32
	v_fma_f32 v32, v65, v32, v65
	v_mul_f32_e32 v32, 0xc0135761, v32
	v_exp_f32_e32 v66, v32
	v_lshlrev_b32_e32 v32, 16, v91
	v_mov_b32_e32 v39, v50
	v_fma_f32 v42, v58, v32, v54
	v_pk_mul_f32 v[32:33], v[38:39], v[46:47]
	v_add_f32_e32 v38, 1.0, v66
	v_add_f32_e32 v33, v42, v33
	v_add_f32_e32 v32, v32, v33
	v_mul_f32_e32 v33, 0x3d372713, v32
	v_mul_f32_e32 v33, v32, v33
	v_fma_f32 v33, v32, v33, v32
	v_mul_f32_e32 v33, 0xc0135761, v33
	v_exp_f32_e32 v33, v33
	v_rcp_f32_e32 v38, v38
	v_add_u32_e32 v39, 0x90, v202
	ds_bpermute_b32 v41, v204, v86
	v_add_f32_e32 v33, 1.0, v33
	v_rcp_f32_e32 v33, v33
	v_mul_f32_e32 v38, v65, v38
	v_mul_f32_e32 v35, v35, v38
	ds_bpermute_b32 v42, v203, v86
	v_mul_f32_e32 v32, v32, v33
	v_mul_f32_e32 v38, v34, v32
	v_cvt_pk_bf16_f32 v32, v40, v64
	v_cvt_pk_bf16_f32 v33, v36, v43
	v_cvt_pk_bf16_f32 v34, v37, v89
	v_mov_b64_e32 v[36:37], s[14:15]
	v_mad_i64_i32 v[36:37], s[62:63], v39, s91, v[36:37]
	v_lshl_add_u64 v[36:37], v[180:181], 1, v[36:37]
	v_cvt_pk_bf16_f32 v35, v38, v35
	global_store_dwordx4 v[36:37], v[32:35], off
	s_nop 1
	v_cvt_pk_bf16_f32 v32, v28, v29
	s_nop 1
	v_mov_b32_dpp v39, v32 row_shr:1 row_mask:0xf bank_mask:0xf
	v_mov_b32_dpp v40, v32 row_shr:2 row_mask:0xf bank_mask:0xf
	v_cvt_pk_bf16_f32 v33, v30, v31
	v_cvt_pk_bf16_f32 v34, v20, v21
	v_cvt_pk_bf16_f32 v38, v22, v23
	v_cmp_eq_u32_e64 s[98:99], 0, v188
	v_cmp_eq_u32_e64 s[100:101], 1, v188
	s_waitcnt lgkmcnt(2)
; __device__ __forceinline__ unsigned cvt_pk_bf16(float lo, float hi) { unsigned r; asm volatile("v_cvt_pk_bf16_f32 %0, %1, %2" : "=v"(r) : "v"(lo), "v"(hi)); return r; }
; __device__ __forceinline__ float gelu_tanh_f(float x) { const float y = -2.3022081983651455f * (x + 0.044715f * x * x * x); return x * __builtin_amdgcn_rcpf(1.f + __builtin_amdgcn_exp2f(y)); }
;     __device__ __forceinline__ void operator()(const f32x4 (&acc)[2][2][4][2], const Unit& u, int wr, int wc, int fr, int fq) const {
;     ...
;                 pk[0] = cvt_pk_bf16(acc[ai][0][m][0][0], acc[ai][0][m][0][1]); pk[1] = cvt_pk_bf16(acc[ai][0][m][0][2], acc[ai][0][m][0][3]);
;                 pk[2] = cvt_pk_bf16(acc[ai][0][m][1][0], acc[ai][0][m][1][1]); pk[3] = cvt_pk_bf16(acc[ai][0][m][1][2], acc[ai][0][m][1][3]);
;                 float hv[8];
; #pragma unroll
;                 for (int q = 0; q < 4; ++q) {
;                     unsigned g1 = (unsigned)__shfl_up((int)pk[q], 1, 16), g2 = (unsigned)__shfl_up((int)pk[q], 2, 16);
;                     if (fr == 0) { g1 = l15[q]; g2 = l14[q]; } else if (fr == 1) { g2 = l15[q]; }
;                     const unsigned n14 = (unsigned)__shfl((int)pk[q], 14, 16), n15 = (unsigned)__shfl((int)pk[q], 15, 16);
;                     l14[q] = n14; l15[q] = n15;
;                     const int n = q >> 1, j = (q & 1) * 2, e = 2 * q;
;                     const float x0 = bb[e] + w0[e] * __uint_as_float(g2 << 16) + w1[e] * __uint_as_float(g1 << 16) + w2[e] * acc[ai][0][m][n][j];
;                     const float x1 = bb[e + 1] + w0[e + 1] * __uint_as_float(g2 & 0xffff0000u) + w1[e + 1] * __uint_as_float(g1 & 0xffff0000u) + w2[e + 1] * acc[ai][0][m][n][j + 1];
;                     hv[e] = gelu_tanh_f(x0) * acc[ai][1][m][n][j]; hv[e + 1] = gelu_tanh_f(x1) * acc[ai][1][m][n][j + 1];
;                 }
;                 const bool first2 = (slab == 0 && m == 0 && fr < 2);
;                 if (!first2) { u32x4 w; w.x = cvt_pk_bf16(hv[0], hv[1]); w.y = cvt_pk_bf16(hv[2], hv[3]); w.z = cvt_pk_bf16(hv[4], hv[5]); w.w = cvt_pk_bf16(hv[6], hv[7]);
;                     *(u32x4*)(H + (size_t)row * ldh + f0) = w; }
	s_nop 1
	v_cndmask_b32_e64 v40, v40, v80, s[100:101]
	v_cndmask_b32_e64 v40, v40, v83, s[98:99]
	v_cndmask_b32_e64 v39, v39, v80, s[98:99]
	ds_bpermute_b32 v35, v204, v32
	ds_bpermute_b32 v32, v203, v32
	s_nop 1
	v_mov_b32_dpp v43, v33 row_shr:1 row_mask:0xf bank_mask:0xf
	v_mov_b32_dpp v47, v33 row_shr:2 row_mask:0xf bank_mask:0xf
	v_cmp_lt_i32_e32 vcc, 0, v188
	v_cmp_eq_u32_e64 s[98:99], 0, v188
	v_cmp_eq_u32_e64 s[100:101], 1, v188
	s_waitcnt lgkmcnt(2)
	s_nop 1
	v_cndmask_b32_e64 v47, v47, v81, s[100:101]
	v_cndmask_b32_e64 v47, v47, v84, s[98:99]
	v_cndmask_b32_e64 v43, v43, v81, s[98:99]
	ds_bpermute_b32 v36, v204, v33
	ds_bpermute_b32 v33, v203, v33
	s_nop 1
	v_mov_b32_dpp v66, v34 row_shr:1 row_mask:0xf bank_mask:0xf
	v_mov_b32_dpp v67, v34 row_shr:2 row_mask:0xf bank_mask:0xf
	v_cmp_lt_i32_e32 vcc, 0, v188
	v_cmp_eq_u32_e64 s[98:99], 0, v188
	v_cmp_eq_u32_e64 s[100:101], 1, v188
	s_waitcnt lgkmcnt(2)
	s_nop 1
	v_cndmask_b32_e64 v67, v67, v82, s[100:101]
	v_cndmask_b32_e64 v67, v67, v85, s[98:99]
	v_cndmask_b32_e64 v66, v66, v82, s[98:99]
	ds_bpermute_b32 v37, v204, v34
	ds_bpermute_b32 v34, v203, v34
	s_nop 1
	v_mov_b32_dpp v64, v38 row_shr:1 row_mask:0xf bank_mask:0xf
	v_mov_b32_dpp v65, v38 row_shr:2 row_mask:0xf bank_mask:0xf
	v_cmp_lt_i32_e32 vcc, 0, v188
	v_cmp_eq_u32_e64 s[98:99], 0, v188
	v_cmp_eq_u32_e64 s[100:101], 1, v188
	s_waitcnt lgkmcnt(2)
	s_nop 1
	v_cndmask_b32_e64 v65, v65, v42, s[100:101]
	v_cndmask_b32_e64 v65, v65, v41, s[98:99]
	v_cndmask_b32_e64 v64, v64, v42, s[98:99]
	s_waitcnt lgkmcnt(4)
	v_lshlrev_b32_e32 v41, 16, v67
	v_fma_f32 v41, v56, v41, v52
	v_lshlrev_b32_e32 v42, 16, v66
	v_fmac_f32_e32 v41, v48, v42
	v_fmac_f32_e32 v41, v20, v44
	v_and_b32_e32 v20, 0xffff0000, v67
	v_fma_f32 v20, v57, v20, v53
	v_and_b32_e32 v42, 0xffff0000, v66
	v_fmac_f32_e32 v20, v49, v42
	v_fmac_f32_e32 v20, v21, v45
	v_mul_f32_e32 v21, 0x3d372713, v41
	v_mul_f32_e32 v21, v41, v21
	v_mul_f32_e32 v42, 0x3d372713, v20
	v_fma_f32 v21, v41, v21, v41
	v_mul_f32_e32 v42, v20, v42
	v_mul_f32_e32 v21, 0xc0135761, v21
	v_fma_f32 v42, v20, v42, v20
	v_exp_f32_e32 v21, v21
	v_mul_f32_e32 v42, 0xc0135761, v42
	v_exp_f32_e32 v42, v42
	s_waitcnt lgkmcnt(1)
	v_and_b32_e32 v145, 0xffff0000, v64
	v_add_f32_e32 v21, 1.0, v21
	v_rcp_f32_e32 v21, v21
	v_add_f32_e32 v42, 1.0, v42
	v_rcp_f32_e32 v42, v42
	v_cmp_lt_i32_e32 vcc, 0, v188
	v_mul_f32_e32 v21, v41, v21
	v_mul_f32_e32 v41, v16, v21
	v_mul_f32_e32 v16, v20, v42
	v_lshlrev_b32_e32 v20, 16, v47
	v_fma_f32 v20, v78, v20, v62
	v_lshlrev_b32_e32 v21, 16, v43
	v_fmac_f32_e32 v20, v70, v21
	v_fmac_f32_e32 v20, v30, v74
	v_mul_f32_e32 v30, 0x3d372713, v20
	v_mul_f32_e32 v30, v20, v30
	v_fma_f32 v30, v20, v30, v20
	v_mul_f32_e32 v30, 0xc0135761, v30
	v_exp_f32_e32 v30, v30
	v_and_b32_e32 v21, 0xffff0000, v47
	v_fma_f32 v21, v79, v21, v63
	v_and_b32_e32 v42, 0xffff0000, v43
	v_add_f32_e32 v30, 1.0, v30
	v_rcp_f32_e32 v30, v30
	v_fmac_f32_e32 v21, v71, v42
	v_fmac_f32_e32 v21, v31, v75
	v_mul_f32_e32 v31, 0x3d372713, v21
	v_mul_f32_e32 v42, v17, v16
	v_lshlrev_b32_e32 v17, 16, v40
	v_mul_f32_e32 v31, v21, v31
	v_mul_f32_e32 v16, v20, v30
	v_fma_f32 v17, v76, v17, v60
	v_lshlrev_b32_e32 v20, 16, v39
	v_fma_f32 v31, v21, v31, v21
	v_fmac_f32_e32 v17, v68, v20
	v_and_b32_e32 v20, 0xffff0000, v40
	v_mul_f32_e32 v31, 0xc0135761, v31
	v_fmac_f32_e32 v17, v28, v72
	v_fma_f32 v20, v77, v20, v61
	v_and_b32_e32 v28, 0xffff0000, v39
	v_exp_f32_e32 v31, v31
	v_fmac_f32_e32 v20, v69, v28
	v_fmac_f32_e32 v20, v29, v73
	v_mul_f32_e32 v28, 0x3d372713, v17
	v_mul_f32_e32 v28, v17, v28
	v_mul_f32_e32 v29, 0x3d372713, v20
	v_fma_f32 v28, v17, v28, v17
	v_mul_f32_e32 v29, v20, v29
	v_mul_f32_e32 v26, v26, v16
	v_add_f32_e32 v16, 1.0, v31
	v_mul_f32_e32 v28, 0xc0135761, v28
	v_fma_f32 v29, v20, v29, v20
	v_rcp_f32_e32 v16, v16
	v_exp_f32_e32 v28, v28
	v_mul_f32_e32 v29, 0xc0135761, v29
	v_exp_f32_e32 v29, v29
	v_mul_f32_e32 v16, v21, v16
	v_add_f32_e32 v21, 1.0, v28
	v_rcp_f32_e32 v21, v21
	v_add_f32_e32 v28, 1.0, v29
	v_rcp_f32_e32 v28, v28
	v_mul_f32_e32 v27, v27, v16
	v_mul_f32_e32 v16, v17, v21
	v_mul_f32_e32 v24, v24, v16
	v_mul_f32_e32 v16, v20, v28
	v_mul_f32_e32 v25, v25, v16
	s_waitcnt lgkmcnt(0)
	v_and_b32_e32 v16, 0xffff0000, v65
	v_fma_f32 v21, v59, v16, v55
	v_mov_b32_e32 v16, v23
	v_mov_b32_e32 v17, v51
	v_pk_mul_f32 v[16:17], v[16:17], v[144:145]
	v_lshlrev_b32_e32 v47, 16, v64
	v_add_f32_e32 v17, v21, v17
	v_add_f32_e32 v28, v16, v17
	v_mul_f32_e32 v16, 0x3d372713, v28
	v_mul_f32_e32 v16, v28, v16
	v_fma_f32 v16, v28, v16, v28
	v_mul_f32_e32 v16, 0xc0135761, v16
	v_exp_f32_e32 v29, v16
	v_lshlrev_b32_e32 v16, 16, v65
	v_mov_b32_e32 v23, v50
	v_fma_f32 v21, v58, v16, v54
	v_pk_mul_f32 v[16:17], v[22:23], v[46:47]
	v_add_f32_e32 v22, 1.0, v29
	v_add_f32_e32 v17, v21, v17
	v_add_f32_e32 v16, v16, v17
	v_mul_f32_e32 v17, 0x3d372713, v16
	v_mul_f32_e32 v17, v16, v17
	v_fma_f32 v17, v16, v17, v16
	v_mul_f32_e32 v17, 0xc0135761, v17
	v_exp_f32_e32 v17, v17
	v_rcp_f32_e32 v22, v22
	v_add_u32_e32 v29, 0xa0, v202
	ds_bpermute_b32 v20, v204, v38
	v_add_f32_e32 v17, 1.0, v17
	v_rcp_f32_e32 v17, v17
	v_mul_f32_e32 v22, v28, v22
	v_mul_f32_e32 v19, v19, v22
	ds_bpermute_b32 v21, v203, v38
	v_mul_f32_e32 v16, v16, v17
	v_mul_f32_e32 v22, v18, v16
	v_cvt_pk_bf16_f32 v16, v24, v25
	v_cvt_pk_bf16_f32 v17, v26, v27
	v_cvt_pk_bf16_f32 v18, v41, v42
	v_cvt_pk_bf16_f32 v19, v22, v19
	v_mov_b64_e32 v[22:23], s[14:15]
	v_mad_i64_i32 v[22:23], s[62:63], v29, s91, v[22:23]
	v_lshl_add_u64 v[22:23], v[180:181], 1, v[22:23]
	global_store_dwordx4 v[22:23], v[16:19], off
	s_nop 1
	v_cvt_pk_bf16_f32 v17, v12, v13
	s_nop 1
	v_mov_b32_dpp v16, v17 row_shr:1 row_mask:0xf bank_mask:0xf
	v_mov_b32_dpp v17, v17 row_shr:2 row_mask:0xf bank_mask:0xf
	v_cvt_pk_bf16_f32 v19, v14, v15
	v_cvt_pk_bf16_f32 v22, v4, v5
	v_cvt_pk_bf16_f32 v23, v6, v7
	v_cmp_eq_u32_e64 s[98:99], 0, v188
	v_cmp_eq_u32_e64 s[100:101], 1, v188
	s_waitcnt lgkmcnt(2)
; __device__ __forceinline__ unsigned cvt_pk_bf16(float lo, float hi) { unsigned r; asm volatile("v_cvt_pk_bf16_f32 %0, %1, %2" : "=v"(r) : "v"(lo), "v"(hi)); return r; }
;     __device__ __forceinline__ void operator()(const f32x4 (&acc)[2][2][4][2], const Unit& u, int wr, int wc, int fr, int fq) const {
;     ...
;                 pk[0] = cvt_pk_bf16(acc[ai][0][m][0][0], acc[ai][0][m][0][1]); pk[1] = cvt_pk_bf16(acc[ai][0][m][0][2], acc[ai][0][m][0][3]);
;                 pk[2] = cvt_pk_bf16(acc[ai][0][m][1][0], acc[ai][0][m][1][1]); pk[3] = cvt_pk_bf16(acc[ai][0][m][1][2], acc[ai][0][m][1][3]);
;                 float hv[8];
; #pragma unroll
;                 for (int q = 0; q < 4; ++q) {
;                     unsigned g1 = (unsigned)__shfl_up((int)pk[q], 1, 16), g2 = (unsigned)__shfl_up((int)pk[q], 2, 16);
;                     if (fr == 0) { g1 = l15[q]; g2 = l14[q]; } else if (fr == 1) { g2 = l15[q]; }
;                     const unsigned n14 = (unsigned)__shfl((int)pk[q], 14, 16), n15 = (unsigned)__shfl((int)pk[q], 15, 16);
;                     l14[q] = n14; l15[q] = n15;
;                     const int n = q >> 1, j = (q & 1) * 2, e = 2 * q;
;                     const float x0 = bb[e] + w0[e] * __uint_as_float(g2 << 16) + w1[e] * __uint_as_float(g1 << 16) + w2[e] * acc[ai][0][m][n][j];
;                     const float x1 = bb[e + 1] + w0[e + 1] * __uint_as_float(g2 & 0xffff0000u) + w1[e + 1] * __uint_as_float(g1 & 0xffff0000u) + w2[e + 1] * acc[ai][0][m][n][j + 1];
;                     hv[e] = gelu_tanh_f(x0) * acc[ai][1][m][n][j]; hv[e + 1] = gelu_tanh_f(x1) * acc[ai][1][m][n][j + 1];
;                 }
;                 const bool first2 = (slab == 0 && m == 0 && fr < 2);
;                 if (!first2) { u32x4 w; w.x = cvt_pk_bf16(hv[0], hv[1]); w.y = cvt_pk_bf16(hv[2], hv[3]); w.z = cvt_pk_bf16(hv[4], hv[5]); w.w = cvt_pk_bf16(hv[6], hv[7]);
;                     *(u32x4*)(H + (size_t)row * ldh + f0) = w; }
;                 else { float* p = hp + (size_t)fr * ff; *(f32x4*)p = acc[0][0][0][0]; *(f32x4*)(p + 4) = acc[0][0][0][1];
;                     float* pu = hp + (size_t)(4 + fr) * ff; *(f32x4*)pu = acc[0][1][0][0]; *(f32x4*)(pu + 4) = acc[0][1][0][1]; }
;                 if (slab == 3 && m == 3 && fr >= 14) { float* p = hp + (size_t)(2 + fr - 14) * ff; *(f32x4*)p = acc[1][0][3][0]; *(f32x4*)(p + 4) = acc[1][0][3][1]; }
	s_nop 1
	v_cndmask_b32_e64 v17, v17, v32, s[100:101]
	v_cndmask_b32_e64 v17, v17, v35, s[98:99]
	v_cndmask_b32_e64 v16, v16, v32, s[98:99]
	s_nop 1
	v_mov_b32_dpp v18, v19 row_shr:1 row_mask:0xf bank_mask:0xf
	v_mov_b32_dpp v19, v19 row_shr:2 row_mask:0xf bank_mask:0xf
	v_cmp_lt_i32_e32 vcc, 0, v188
	v_cmp_eq_u32_e64 s[98:99], 0, v188
	v_cmp_eq_u32_e64 s[100:101], 1, v188
	s_waitcnt lgkmcnt(2)
	s_nop 1
	v_cndmask_b32_e64 v19, v19, v33, s[100:101]
	v_cndmask_b32_e64 v19, v19, v36, s[98:99]
	v_cndmask_b32_e64 v18, v18, v33, s[98:99]
	s_nop 1
	v_mov_b32_dpp v24, v22 row_shr:1 row_mask:0xf bank_mask:0xf
	v_mov_b32_dpp v25, v22 row_shr:2 row_mask:0xf bank_mask:0xf
	v_cmp_lt_i32_e32 vcc, 0, v188
	v_cmp_eq_u32_e64 s[98:99], 0, v188
	v_cmp_eq_u32_e64 s[100:101], 1, v188
	s_waitcnt lgkmcnt(2)
	s_nop 1
	v_cndmask_b32_e64 v25, v25, v34, s[100:101]
	v_cndmask_b32_e64 v25, v25, v37, s[98:99]
	v_cndmask_b32_e64 v24, v24, v34, s[98:99]
	s_nop 1
	v_mov_b32_dpp v22, v23 row_shr:1 row_mask:0xf bank_mask:0xf
	v_mov_b32_dpp v23, v23 row_shr:2 row_mask:0xf bank_mask:0xf
	v_cmp_lt_i32_e32 vcc, 0, v188
	v_cmp_eq_u32_e64 s[98:99], 0, v188
	v_cmp_eq_u32_e64 s[100:101], 1, v188
	s_waitcnt lgkmcnt(2)
	s_nop 1
	v_cndmask_b32_e64 v23, v23, v21, s[100:101]
	v_cndmask_b32_e64 v23, v23, v20, s[98:99]
	v_cndmask_b32_e64 v22, v22, v21, s[98:99]
	s_waitcnt lgkmcnt(2)
	v_lshlrev_b32_e32 v20, 16, v25
	v_fma_f32 v20, v56, v20, v52
	v_lshlrev_b32_e32 v21, 16, v24
	v_fmac_f32_e32 v20, v48, v21
	v_and_b32_e32 v21, 0xffff0000, v25
	v_fma_f32 v21, v57, v21, v53
	v_and_b32_e32 v24, 0xffff0000, v24
	v_fmac_f32_e32 v20, v4, v44
	v_fmac_f32_e32 v21, v49, v24
	v_fmac_f32_e32 v21, v5, v45
	v_mul_f32_e32 v24, 0x3d372713, v20
	v_mul_f32_e32 v24, v20, v24
	v_mul_f32_e32 v25, 0x3d372713, v21
	v_fma_f32 v24, v20, v24, v20
	v_mul_f32_e32 v25, v21, v25
	v_mul_f32_e32 v24, 0xc0135761, v24
	v_fma_f32 v25, v21, v25, v21
	v_exp_f32_e32 v24, v24
	v_mul_f32_e32 v25, 0xc0135761, v25
	v_exp_f32_e32 v25, v25
	s_waitcnt lgkmcnt(1)
	v_and_b32_e32 v145, 0xffff0000, v22
	v_add_f32_e32 v24, 1.0, v24
	v_rcp_f32_e32 v24, v24
	v_add_f32_e32 v25, 1.0, v25
	v_rcp_f32_e32 v25, v25
	v_lshlrev_b32_e32 v47, 16, v22
	v_mul_f32_e32 v20, v20, v24
	v_mul_f32_e32 v20, v0, v20
	v_mul_f32_e32 v0, v21, v25
	v_lshlrev_b32_e32 v21, 16, v19
	v_fma_f32 v21, v78, v21, v62
	v_lshlrev_b32_e32 v24, 16, v18
	v_fmac_f32_e32 v21, v70, v24
	v_fmac_f32_e32 v21, v14, v74
	v_mul_f32_e32 v24, 0x3d372713, v21
	v_mul_f32_e32 v24, v21, v24
	v_fma_f32 v24, v21, v24, v21
	v_mul_f32_e32 v24, 0xc0135761, v24
	v_exp_f32_e32 v24, v24
	v_and_b32_e32 v19, 0xffff0000, v19
	v_fma_f32 v19, v79, v19, v63
	v_and_b32_e32 v18, 0xffff0000, v18
	v_fmac_f32_e32 v19, v71, v18
	v_add_f32_e32 v18, 1.0, v24
	v_rcp_f32_e32 v18, v18
	v_mul_f32_e32 v25, v1, v0
	v_lshlrev_b32_e32 v1, 16, v17
	v_fma_f32 v1, v76, v1, v60
	v_mul_f32_e32 v0, v21, v18
	v_lshlrev_b32_e32 v18, 16, v16
	v_fmac_f32_e32 v19, v15, v75
	v_fmac_f32_e32 v1, v68, v18
	v_and_b32_e32 v17, 0xffff0000, v17
	v_mul_f32_e32 v24, 0x3d372713, v19
	v_fmac_f32_e32 v1, v12, v72
	v_fmac_f32_e32 v61, v77, v17
	v_and_b32_e32 v16, 0xffff0000, v16
	v_mul_f32_e32 v24, v19, v24
	v_fmac_f32_e32 v61, v69, v16
	v_mul_f32_e32 v16, 0x3d372713, v1
	v_fma_f32 v24, v19, v24, v19
	v_fmac_f32_e32 v61, v13, v73
	v_mul_f32_e32 v16, v1, v16
	v_mul_f32_e32 v24, 0xc0135761, v24
	v_fma_f32 v16, v1, v16, v1
	v_mul_f32_e32 v17, 0x3d372713, v61
	v_exp_f32_e32 v24, v24
	v_mul_f32_e32 v16, 0xc0135761, v16
	v_mul_f32_e32 v17, v61, v17
	v_exp_f32_e32 v16, v16
	v_fma_f32 v17, v61, v17, v61
	v_mul_f32_e32 v17, 0xc0135761, v17
	v_exp_f32_e32 v17, v17
	v_mul_f32_e32 v10, v10, v0
	v_add_f32_e32 v0, 1.0, v24
	v_rcp_f32_e32 v0, v0
	v_add_f32_e32 v16, 1.0, v16
	v_rcp_f32_e32 v16, v16
	v_add_f32_e32 v17, 1.0, v17
	v_rcp_f32_e32 v17, v17
	v_mul_f32_e32 v0, v19, v0
	v_mul_f32_e32 v11, v11, v0
	v_mul_f32_e32 v0, v1, v16
	v_mul_f32_e32 v8, v8, v0
	s_waitcnt lgkmcnt(0)
	v_and_b32_e32 v0, 0xffff0000, v23
	v_mul_f32_e32 v16, v61, v17
	v_fma_f32 v17, v59, v0, v55
	v_mov_b32_e32 v0, v7
	v_mov_b32_e32 v1, v51
	v_pk_mul_f32 v[0:1], v[0:1], v[144:145]
	v_mul_f32_e32 v9, v9, v16
	v_add_f32_e32 v1, v17, v1
	v_add_f32_e32 v17, v0, v1
	v_mul_f32_e32 v0, 0x3d372713, v17
	v_mul_f32_e32 v0, v17, v0
	v_fma_f32 v0, v17, v0, v17
	v_mul_f32_e32 v0, 0xc0135761, v0
	v_exp_f32_e32 v18, v0
	v_lshlrev_b32_e32 v0, 16, v23
	v_fmac_f32_e32 v54, v58, v0
	v_mov_b32_e32 v0, v6
	v_mov_b32_e32 v1, v50
	v_pk_mul_f32 v[0:1], v[0:1], v[46:47]
	v_add_f32_e32 v16, 1.0, v18
	v_add_f32_e32 v1, v54, v1
	v_add_f32_e32 v0, v0, v1
	v_mul_f32_e32 v1, 0x3d372713, v0
	v_mul_f32_e32 v1, v0, v1
	v_fma_f32 v1, v0, v1, v0
	v_mul_f32_e32 v1, 0xc0135761, v1
	v_exp_f32_e32 v1, v1
	v_rcp_f32_e32 v16, v16
	v_add_u32_e32 v18, 0xb0, v202
	v_add_f32_e32 v1, 1.0, v1
	v_rcp_f32_e32 v1, v1
	v_mul_f32_e32 v16, v17, v16
	v_mul_f32_e32 v3, v3, v16
	v_mul_f32_e32 v0, v0, v1
	v_mul_f32_e32 v16, v2, v0
	v_cvt_pk_bf16_f32 v0, v8, v9
	v_mov_b64_e32 v[8:9], s[14:15]
	v_mad_i64_i32 v[8:9], s[62:63], v18, s91, v[8:9]
	v_lshl_add_u64 v[8:9], v[180:181], 1, v[8:9]
	v_cvt_pk_bf16_f32 v1, v10, v11
	v_cvt_pk_bf16_f32 v2, v20, v25
	v_cvt_pk_bf16_f32 v3, v16, v3
	global_store_dwordx4 v[8:9], v[0:3], off
	s_and_saveexec_b64 s[62:63], s[48:49]
	s_cbranch_execz .LBB0_2613
	global_store_dwordx4 v[112:113], v[12:15], off
	global_store_dwordx4 v[112:113], v[4:7], off offset:16
